# peeled first K-loop iteration of every GEMM unit (first MFMA per accumulator uses C=0), removing the 128-mov accumulator zero-init per unit
# speedup vs baseline: 1.0080x; 1.0035x over previous
; #define PG8_STAGE(bufoff, gbase, voff) do { _Pragma("unroll") for (int _i = 0; _i < 2; ++_i) \
;         __builtin_amdgcn_global_load_lds((const unsigned*)((const char*)(gbase) + (voff)[_i]), (PG8_LAS unsigned*)(lds + (bufoff) + ldsw + _i * 8192), 16, 0, 0); } while (0)
; #define PG8_LDA(dst, b, h) do { _Pragma("unroll") for (int m = 0; m < 4; ++m) _Pragma("unroll") for (int k = 0; k < 2; ++k) dst[m][k] = *(const PG8_LAS bf16x8*)(lds + PG8_SA(b, h) + aoff + m * 2048 + k * 1024); } while (0)
; #define PG8_LDB(dst, b, h) do { _Pragma("unroll") for (int n = 0; n < 2; ++n) _Pragma("unroll") for (int k = 0; k < 2; ++k) dst[n][k] = *(const PG8_LAS bf16x8*)(lds + PG8_SB(b, h) + boff + n * 2048 + k * 1024); } while (0)
; #define PG8_WAIT_V(n) asm volatile("s_waitcnt vmcnt(" #n ")" ::: "memory")
; #define PG8_WAIT_L(n) asm volatile("s_waitcnt lgkmcnt(" #n ")" ::: "memory")
; #define PG8_BAR __builtin_amdgcn_s_barrier()
; #define PG8_SCHED __builtin_amdgcn_sched_barrier(0)
; template <class Epi, class Sched, bool ALIGN_EPI = false, bool SP2 = false>
; __device__ __forceinline__ void gemm_phase(PG8_LAS unsigned char* lds, const Gemm g, const Sched& S, const Epi& E) {
;     ...
;         const bool has_next = S.next(ui + 1, nxt);
;         const char* nA = has_next ? (const char*)g.A + (size_t)nxt.pm * tstep : cA; const char* nB = has_next ? (const char*)g.Bt + (size_t)nxt.pn * tstep : cB;
;         for (int t = 0; t < nt; t += 2) {
;             const bool last = (t == nt - 2);
;             const char* a1 = cA + (size_t)(t + 1) * kstep;
;             const char* a2 = last ? nA : cA + (size_t)(t + 2) * kstep; const char* b2 = last ? nB : cB + (size_t)(t + 2) * kstep;
;             const char* a3 = a2 + kstep; const char* b3 = b2 + kstep;
;             if (last && has_next) S.a_ready(nxt, ui + 1);
;             if constexpr (SP2) {
;             PG8_LDB(B0, 0, 0); PG8_LDB(B1, 0, 1); PG8_SCHED; PG8_LDA(At, 0, 0); PG8_STAGE(PG8_SA(1, 1), a1 + hstep, voffA);
;             PG8_WAIT_V(8); PG8_WAIT_L(0); PG8_BAR; PG8_MMA(0, 0, At, B0); PG8_MMA(0, 1, At, B1); PG8_BAR; PG8_SCHED;
;             PG8_LDA(At, 0, 1); PG8_STAGE(PG8_SB(0, 0), b2, voffB); PG8_STAGE(PG8_SB(0, 1), b2 + hstep, voffB); PG8_STAGE(PG8_SA(0, 0), a2, voffA);
;             PG8_WAIT_V(8); PG8_WAIT_L(0); PG8_BAR; PG8_MMA(1, 0, At, B0); PG8_MMA(1, 1, At, B1); PG8_BAR; PG8_SCHED;
.LBB0_336:
	s_ashr_i32 s17, s16, 31
	s_lshl_b64 s[18:19], s[16:17], 19
	s_add_u32 s18, s36, s18
	s_addc_u32 s19, s37, s19
	s_and_b64 s[20:21], s[0:1], exec
	s_cselect_b32 s17, s19, s25
	s_cselect_b32 s50, s18, s24
	s_ashr_i32 s15, s14, 31
	s_lshl_b64 s[20:21], s[14:15], 19
	s_add_u32 s20, s34, s20
	s_addc_u32 s21, s35, s21
	s_and_b64 s[28:29], s[0:1], exec
	s_cselect_b32 s15, s21, s27
	s_cselect_b32 s51, s20, s26
	s_add_u32 s24, s24, 0x40080
	s_addc_u32 s25, s25, 0
	s_add_u32 s52, s26, 0x100
	s_addc_u32 s53, s27, 0
	s_mov_b32 s54, -2
	ds_read_b128 v[152:155], v148
	ds_read_b128 v[156:159], v148 offset:1024
	ds_read_b128 v[160:163], v148 offset:2048
	ds_read_b128 v[164:167], v148 offset:3072
	ds_read_b128 v[168:171], v149
	ds_read_b128 v[172:175], v149 offset:1024
	ds_read_b128 v[176:179], v149 offset:2048
	ds_read_b128 v[180:183], v149 offset:3072
	s_add_u32 s26, s24, 0xfffc0080
	s_addc_u32 s27, s25, -1
	s_cmp_eq_u32 s54, 12
	s_cselect_b32 s29, s17, s27
	s_cselect_b32 s28, s50, s26
	s_cselect_b32 s27, s15, s53
	s_cselect_b32 s26, s51, s52
	v_lshl_add_u64 v[216:217], s[24:25], 0, v[136:137]
	s_add_i32 m0, s23, 0xc000
	ds_read_b128 v[184:187], v150
	ds_read_b128 v[188:191], v150 offset:1024
	ds_read_b128 v[192:195], v150 offset:2048
	ds_read_b128 v[196:199], v150 offset:3072
	ds_read_b128 v[200:203], v150 offset:4096
	ds_read_b128 v[204:207], v150 offset:5120
	ds_read_b128 v[208:211], v150 offset:6144
	ds_read_b128 v[212:215], v150 offset:7168
	global_load_lds_dwordx4 v[216:217], off
	v_lshl_add_u64 v[216:217], s[24:25], 0, v[138:139]
	s_add_i32 m0, s23, 0xe000
	s_nop 0
	global_load_lds_dwordx4 v[216:217], off
	s_waitcnt vmcnt(8)
	s_waitcnt lgkmcnt(0)
	s_barrier
	s_setprio 1
	s_waitcnt lgkmcnt(0)
	v_mfma_f32_16x16x32_bf16 v[124:127], v[152:155], v[184:187], 0
	v_mfma_f32_16x16x32_bf16 v[120:123], v[160:163], v[184:187], 0
	v_mfma_f32_16x16x32_bf16 v[108:111], v[152:155], v[192:195], 0
	v_mfma_f32_16x16x32_bf16 v[104:107], v[160:163], v[192:195], 0
	v_mfma_f32_16x16x32_bf16 v[92:95], v[152:155], v[200:203], 0
	v_mfma_f32_16x16x32_bf16 v[88:91], v[160:163], v[200:203], 0
	v_mfma_f32_16x16x32_bf16 v[76:79], v[152:155], v[208:211], 0
	v_mfma_f32_16x16x32_bf16 v[72:75], v[160:163], v[208:211], 0
	v_mfma_f32_16x16x32_bf16 v[124:127], v[156:159], v[188:191], v[124:127]
	v_mfma_f32_16x16x32_bf16 v[120:123], v[164:167], v[188:191], v[120:123]
	v_mfma_f32_16x16x32_bf16 v[108:111], v[156:159], v[196:199], v[108:111]
	v_mfma_f32_16x16x32_bf16 v[104:107], v[164:167], v[196:199], v[104:107]
	v_mfma_f32_16x16x32_bf16 v[92:95], v[156:159], v[204:207], v[92:95]
	v_mfma_f32_16x16x32_bf16 v[88:91], v[164:167], v[204:207], v[88:91]
	v_mfma_f32_16x16x32_bf16 v[76:79], v[156:159], v[212:215], v[76:79]
	v_mfma_f32_16x16x32_bf16 v[72:75], v[164:167], v[212:215], v[72:75]
	s_setprio 0
	s_setprio 1
	v_mfma_f32_16x16x32_bf16 v[116:119], v[168:171], v[184:187], 0
	v_mfma_f32_16x16x32_bf16 v[112:115], v[176:179], v[184:187], 0
	v_mfma_f32_16x16x32_bf16 v[100:103], v[168:171], v[192:195], 0
	v_mfma_f32_16x16x32_bf16 v[96:99], v[176:179], v[192:195], 0
	v_mfma_f32_16x16x32_bf16 v[84:87], v[168:171], v[200:203], 0
	v_mfma_f32_16x16x32_bf16 v[80:83], v[176:179], v[200:203], 0
	v_mfma_f32_16x16x32_bf16 v[68:71], v[168:171], v[208:211], 0
	v_mfma_f32_16x16x32_bf16 v[64:67], v[176:179], v[208:211], 0
	v_mfma_f32_16x16x32_bf16 v[116:119], v[172:175], v[188:191], v[116:119]
	v_mfma_f32_16x16x32_bf16 v[112:115], v[180:183], v[188:191], v[112:115]
	v_mfma_f32_16x16x32_bf16 v[100:103], v[172:175], v[196:199], v[100:103]
	v_mfma_f32_16x16x32_bf16 v[96:99], v[180:183], v[196:199], v[96:99]
	v_mfma_f32_16x16x32_bf16 v[84:87], v[172:175], v[204:207], v[84:87]
	v_mfma_f32_16x16x32_bf16 v[80:83], v[180:183], v[204:207], v[80:83]
	v_mfma_f32_16x16x32_bf16 v[68:71], v[172:175], v[212:215], v[68:71]
	v_mfma_f32_16x16x32_bf16 v[64:67], v[180:183], v[212:215], v[64:67]
	s_setprio 0
	s_barrier
	s_add_i32 s55, s44, s33
	v_lshl_add_u64 v[216:217], s[26:27], 0, v[132:133]
	s_mov_b32 m0, s55
	ds_read_b128 v[184:187], v150 offset:16384
	ds_read_b128 v[188:191], v150 offset:17408
	ds_read_b128 v[192:195], v150 offset:18432
	ds_read_b128 v[196:199], v150 offset:19456
	ds_read_b128 v[200:203], v150 offset:20480
	ds_read_b128 v[204:207], v150 offset:21504
	ds_read_b128 v[208:211], v150 offset:22528
	ds_read_b128 v[212:215], v150 offset:23552
	global_load_lds_dwordx4 v[216:217], off
	s_add_i32 m0, s55, 0x2000
	s_add_u32 s56, s26, 0x40000
	v_lshl_add_u64 v[218:219], s[26:27], 0, v[128:129]
	s_addc_u32 s57, s27, 0
	s_add_i32 s55, s45, s33
	global_load_lds_dwordx4 v[218:219], off
	v_lshl_add_u64 v[220:221], s[56:57], 0, v[132:133]
	s_mov_b32 m0, s55
	v_lshl_add_u64 v[222:223], s[28:29], 0, v[130:131]
	global_load_lds_dwordx4 v[220:221], off
	v_lshl_add_u64 v[220:221], s[56:57], 0, v[128:129]
	s_add_i32 m0, s55, 0x2000
	s_nop 0
	global_load_lds_dwordx4 v[220:221], off
	v_lshl_add_u64 v[220:221], s[28:29], 0, v[134:135]
	s_mov_b32 m0, s23
	s_nop 0
	global_load_lds_dwordx4 v[220:221], off
	s_mov_b32 m0, s39
	s_nop 0
	global_load_lds_dwordx4 v[222:223], off
	s_waitcnt vmcnt(8)
	s_waitcnt lgkmcnt(0)
	s_barrier
; #define PG8_STAGE(bufoff, gbase, voff) do { _Pragma("unroll") for (int _i = 0; _i < 2; ++_i) \
;         __builtin_amdgcn_global_load_lds((const unsigned*)((const char*)(gbase) + (voff)[_i]), (PG8_LAS unsigned*)(lds + (bufoff) + ldsw + _i * 8192), 16, 0, 0); } while (0)
; #define PG8_LDA(dst, b, h) do { _Pragma("unroll") for (int m = 0; m < 4; ++m) _Pragma("unroll") for (int k = 0; k < 2; ++k) dst[m][k] = *(const PG8_LAS bf16x8*)(lds + PG8_SA(b, h) + aoff + m * 2048 + k * 1024); } while (0)
; #define PG8_LDB(dst, b, h) do { _Pragma("unroll") for (int n = 0; n < 2; ++n) _Pragma("unroll") for (int k = 0; k < 2; ++k) dst[n][k] = *(const PG8_LAS bf16x8*)(lds + PG8_SB(b, h) + boff + n * 2048 + k * 1024); } while (0)
; #define PG8_MMA(ai, bj, At, Bt) do { __builtin_amdgcn_s_setprio(1); _Pragma("unroll") for (int m = 0; m < 4; ++m) _Pragma("unroll") for (int n = 0; n < 2; ++n) _Pragma("unroll") for (int k = 0; k < 2; ++k) \
;         acc[ai][bj][m][n] = __builtin_amdgcn_mfma_f32_16x16x32_bf16(Bt[n][k], At[m][k], acc[ai][bj][m][n], 0, 0, 0); __builtin_amdgcn_s_setprio(0); } while (0)
; #define PG8_WAIT_V(n) asm volatile("s_waitcnt vmcnt(" #n ")" ::: "memory")
; #define PG8_WAIT_L(n) asm volatile("s_waitcnt lgkmcnt(" #n ")" ::: "memory")
; #define PG8_BAR __builtin_amdgcn_s_barrier()
; #define PG8_SCHED __builtin_amdgcn_sched_barrier(0)
; template <class Epi, class Sched, bool ALIGN_EPI = false, bool SP2 = false>
; __device__ __forceinline__ void gemm_phase(PG8_LAS unsigned char* lds, const Gemm g, const Sched& S, const Epi& E) {
;     ...
;             PG8_WAIT_V(8); PG8_WAIT_L(0); PG8_BAR; PG8_MMA(1, 0, At, B0); PG8_MMA(1, 1, At, B1); PG8_BAR; PG8_SCHED;
;             PG8_LDB(B0, 1, 0); PG8_LDB(B1, 1, 1); PG8_SCHED; PG8_LDA(At, 1, 0); PG8_STAGE(PG8_SA(0, 1), a2 + hstep, voffA);
;             PG8_WAIT_V(8); PG8_WAIT_L(0); PG8_BAR; PG8_MMA(0, 0, At, B0); PG8_MMA(0, 1, At, B1); PG8_BAR; PG8_SCHED;
	s_setprio 1
	s_waitcnt lgkmcnt(0)
	v_mfma_f32_16x16x32_bf16 v[60:63], v[152:155], v[184:187], 0
	v_mfma_f32_16x16x32_bf16 v[56:59], v[160:163], v[184:187], 0
	v_mfma_f32_16x16x32_bf16 v[44:47], v[152:155], v[192:195], 0
	v_mfma_f32_16x16x32_bf16 v[40:43], v[160:163], v[192:195], 0
	v_mfma_f32_16x16x32_bf16 v[28:31], v[152:155], v[200:203], 0
	v_mfma_f32_16x16x32_bf16 v[24:27], v[160:163], v[200:203], 0
	v_mfma_f32_16x16x32_bf16 v[12:15], v[152:155], v[208:211], 0
	v_mfma_f32_16x16x32_bf16 v[8:11], v[160:163], v[208:211], 0
	v_mfma_f32_16x16x32_bf16 v[60:63], v[156:159], v[188:191], v[60:63]
	v_mfma_f32_16x16x32_bf16 v[56:59], v[164:167], v[188:191], v[56:59]
	v_mfma_f32_16x16x32_bf16 v[44:47], v[156:159], v[196:199], v[44:47]
	v_mfma_f32_16x16x32_bf16 v[40:43], v[164:167], v[196:199], v[40:43]
	v_mfma_f32_16x16x32_bf16 v[28:31], v[156:159], v[204:207], v[28:31]
	v_mfma_f32_16x16x32_bf16 v[24:27], v[164:167], v[204:207], v[24:27]
	v_mfma_f32_16x16x32_bf16 v[12:15], v[156:159], v[212:215], v[12:15]
	v_mfma_f32_16x16x32_bf16 v[8:11], v[164:167], v[212:215], v[8:11]
	s_setprio 0
	s_setprio 1
	v_mfma_f32_16x16x32_bf16 v[52:55], v[168:171], v[184:187], 0
	v_mfma_f32_16x16x32_bf16 v[48:51], v[176:179], v[184:187], 0
	v_mfma_f32_16x16x32_bf16 v[36:39], v[168:171], v[192:195], 0
	v_mfma_f32_16x16x32_bf16 v[32:35], v[176:179], v[192:195], 0
	v_mfma_f32_16x16x32_bf16 v[20:23], v[168:171], v[200:203], 0
	v_mfma_f32_16x16x32_bf16 v[16:19], v[176:179], v[200:203], 0
	v_mfma_f32_16x16x32_bf16 v[4:7], v[168:171], v[208:211], 0
	v_mfma_f32_16x16x32_bf16 v[0:3], v[176:179], v[208:211], 0
	v_mfma_f32_16x16x32_bf16 v[52:55], v[172:175], v[188:191], v[52:55]
	v_mfma_f32_16x16x32_bf16 v[48:51], v[180:183], v[188:191], v[48:51]
	v_mfma_f32_16x16x32_bf16 v[36:39], v[172:175], v[196:199], v[36:39]
	v_mfma_f32_16x16x32_bf16 v[32:35], v[180:183], v[196:199], v[32:35]
	v_mfma_f32_16x16x32_bf16 v[20:23], v[172:175], v[204:207], v[20:23]
	v_mfma_f32_16x16x32_bf16 v[16:19], v[180:183], v[204:207], v[16:19]
	v_mfma_f32_16x16x32_bf16 v[4:7], v[172:175], v[212:215], v[4:7]
	v_mfma_f32_16x16x32_bf16 v[0:3], v[180:183], v[212:215], v[0:3]
	s_setprio 0
	s_barrier
	s_add_i32 s55, 0, 0x18000
	v_add_u32_e32 v151, s55, v145
	s_add_i32 s56, 0, 0x1c000
	ds_read_b128 v[152:155], v151
	ds_read_b128 v[156:159], v151 offset:1024
	ds_read_b128 v[160:163], v151 offset:2048
	ds_read_b128 v[164:167], v151 offset:3072
	v_add_u32_e32 v151, s56, v145
	ds_read_b128 v[168:171], v151
	ds_read_b128 v[172:175], v151 offset:1024
	ds_read_b128 v[176:179], v151 offset:2048
	ds_read_b128 v[180:183], v151 offset:3072
	s_add_u32 s28, s28, 0x40000
	s_addc_u32 s29, s29, 0
	s_mov_b32 m0, s40
	v_lshl_add_u64 v[224:225], s[28:29], 0, v[134:135]
	ds_read_b128 v[184:187], v150 offset:32768
	ds_read_b128 v[188:191], v150 offset:33792
	ds_read_b128 v[192:195], v150 offset:34816
	ds_read_b128 v[196:199], v150 offset:35840
	ds_read_b128 v[200:203], v150 offset:36864
	ds_read_b128 v[204:207], v150 offset:37888
	ds_read_b128 v[208:211], v150 offset:38912
	ds_read_b128 v[212:215], v150 offset:39936
	global_load_lds_dwordx4 v[224:225], off
	v_lshl_add_u64 v[224:225], s[28:29], 0, v[130:131]
	s_mov_b32 m0, s41
	s_nop 0
	global_load_lds_dwordx4 v[224:225], off
	s_waitcnt vmcnt(8)
	s_waitcnt lgkmcnt(0)
	s_barrier
	s_setprio 1
	s_waitcnt lgkmcnt(0)
	v_mfma_f32_16x16x32_bf16 v[124:127], v[152:155], v[184:187], v[124:127]
	v_mfma_f32_16x16x32_bf16 v[120:123], v[160:163], v[184:187], v[120:123]
	v_mfma_f32_16x16x32_bf16 v[108:111], v[152:155], v[192:195], v[108:111]
	v_mfma_f32_16x16x32_bf16 v[104:107], v[160:163], v[192:195], v[104:107]
	v_mfma_f32_16x16x32_bf16 v[92:95], v[152:155], v[200:203], v[92:95]
	v_mfma_f32_16x16x32_bf16 v[88:91], v[160:163], v[200:203], v[88:91]
	v_mfma_f32_16x16x32_bf16 v[76:79], v[152:155], v[208:211], v[76:79]
	v_mfma_f32_16x16x32_bf16 v[72:75], v[160:163], v[208:211], v[72:75]
	v_mfma_f32_16x16x32_bf16 v[124:127], v[156:159], v[188:191], v[124:127]
	v_mfma_f32_16x16x32_bf16 v[120:123], v[164:167], v[188:191], v[120:123]
	v_mfma_f32_16x16x32_bf16 v[108:111], v[156:159], v[196:199], v[108:111]
	v_mfma_f32_16x16x32_bf16 v[104:107], v[164:167], v[196:199], v[104:107]
	v_mfma_f32_16x16x32_bf16 v[92:95], v[156:159], v[204:207], v[92:95]
	v_mfma_f32_16x16x32_bf16 v[88:91], v[164:167], v[204:207], v[88:91]
	v_mfma_f32_16x16x32_bf16 v[76:79], v[156:159], v[212:215], v[76:79]
	v_mfma_f32_16x16x32_bf16 v[72:75], v[164:167], v[212:215], v[72:75]
	s_setprio 0
	s_setprio 1
	v_mfma_f32_16x16x32_bf16 v[116:119], v[168:171], v[184:187], v[116:119]
	v_mfma_f32_16x16x32_bf16 v[112:115], v[176:179], v[184:187], v[112:115]
	v_mfma_f32_16x16x32_bf16 v[100:103], v[168:171], v[192:195], v[100:103]
	v_mfma_f32_16x16x32_bf16 v[96:99], v[176:179], v[192:195], v[96:99]
	v_mfma_f32_16x16x32_bf16 v[84:87], v[168:171], v[200:203], v[84:87]
	v_mfma_f32_16x16x32_bf16 v[80:83], v[176:179], v[200:203], v[80:83]
	v_mfma_f32_16x16x32_bf16 v[68:71], v[168:171], v[208:211], v[68:71]
	v_mfma_f32_16x16x32_bf16 v[64:67], v[176:179], v[208:211], v[64:67]
	v_mfma_f32_16x16x32_bf16 v[116:119], v[172:175], v[188:191], v[116:119]
	v_mfma_f32_16x16x32_bf16 v[112:115], v[180:183], v[188:191], v[112:115]
	v_mfma_f32_16x16x32_bf16 v[100:103], v[172:175], v[196:199], v[100:103]
	v_mfma_f32_16x16x32_bf16 v[96:99], v[180:183], v[196:199], v[96:99]
	v_mfma_f32_16x16x32_bf16 v[84:87], v[172:175], v[204:207], v[84:87]
	v_mfma_f32_16x16x32_bf16 v[80:83], v[180:183], v[204:207], v[80:83]
	v_mfma_f32_16x16x32_bf16 v[68:71], v[172:175], v[212:215], v[68:71]
	v_mfma_f32_16x16x32_bf16 v[64:67], v[180:183], v[212:215], v[64:67]
	s_setprio 0
	s_barrier
; #define PG8_STAGE(bufoff, gbase, voff) do { _Pragma("unroll") for (int _i = 0; _i < 2; ++_i) \
;         __builtin_amdgcn_global_load_lds((const unsigned*)((const char*)(gbase) + (voff)[_i]), (PG8_LAS unsigned*)(lds + (bufoff) + ldsw + _i * 8192), 16, 0, 0); } while (0)
; #define PG8_LDA(dst, b, h) do { _Pragma("unroll") for (int m = 0; m < 4; ++m) _Pragma("unroll") for (int k = 0; k < 2; ++k) dst[m][k] = *(const PG8_LAS bf16x8*)(lds + PG8_SA(b, h) + aoff + m * 2048 + k * 1024); } while (0)
; #define PG8_MMA(ai, bj, At, Bt) do { __builtin_amdgcn_s_setprio(1); _Pragma("unroll") for (int m = 0; m < 4; ++m) _Pragma("unroll") for (int n = 0; n < 2; ++n) _Pragma("unroll") for (int k = 0; k < 2; ++k) \
;         acc[ai][bj][m][n] = __builtin_amdgcn_mfma_f32_16x16x32_bf16(Bt[n][k], At[m][k], acc[ai][bj][m][n], 0, 0, 0); __builtin_amdgcn_s_setprio(0); } while (0)
; #define PG8_WAIT_V(n) asm volatile("s_waitcnt vmcnt(" #n ")" ::: "memory")
; #define PG8_WAIT_L(n) asm volatile("s_waitcnt lgkmcnt(" #n ")" ::: "memory")
; #define PG8_BAR __builtin_amdgcn_s_barrier()
; #define PG8_SCHED __builtin_amdgcn_sched_barrier(0)
; template <class Epi, class Sched, bool ALIGN_EPI = false, bool SP2 = false>
; __device__ __forceinline__ void gemm_phase(PG8_LAS unsigned char* lds, const Gemm g, const Sched& S, const Epi& E) {
;     ...
;         for (int t = 0; t < nt; t += 2) {
;     ...
;             PG8_LDA(At, 1, 1); PG8_STAGE(PG8_SB(1, 0), b3, voffB); PG8_STAGE(PG8_SB(1, 1), b3 + hstep, voffB); PG8_STAGE(PG8_SA(1, 0), a3, voffA);
;             PG8_WAIT_V(8); PG8_WAIT_L(0); PG8_BAR; PG8_MMA(1, 0, At, B0); PG8_MMA(1, 1, At, B1); PG8_BAR; PG8_SCHED;
	s_add_i32 s28, s55, s33
	v_lshl_add_u64 v[216:217], v[216:217], 0, s[8:9]
	s_mov_b32 m0, s28
	ds_read_b128 v[184:187], v150 offset:49152
	ds_read_b128 v[188:191], v150 offset:50176
	ds_read_b128 v[192:195], v150 offset:51200
	ds_read_b128 v[196:199], v150 offset:52224
	ds_read_b128 v[200:203], v150 offset:53248
	ds_read_b128 v[204:207], v150 offset:54272
	ds_read_b128 v[208:211], v150 offset:55296
	ds_read_b128 v[212:215], v150 offset:56320
	global_load_lds_dwordx4 v[216:217], off
	s_add_i32 m0, s28, 0x2000
	s_add_u32 s26, s26, 0x40080
	v_lshl_add_u64 v[216:217], v[218:219], 0, s[8:9]
	s_addc_u32 s27, s27, 0
	s_add_i32 s28, s56, s33
	global_load_lds_dwordx4 v[216:217], off
	v_lshl_add_u64 v[216:217], s[26:27], 0, v[132:133]
	s_mov_b32 m0, s28
	s_nop 0
	global_load_lds_dwordx4 v[216:217], off
	v_lshl_add_u64 v[216:217], s[26:27], 0, v[128:129]
	s_add_i32 m0, s28, 0x2000
	s_nop 0
	global_load_lds_dwordx4 v[216:217], off
	v_lshl_add_u64 v[216:217], v[220:221], 0, s[8:9]
	s_mov_b32 m0, s42
	s_nop 0
	global_load_lds_dwordx4 v[216:217], off
	v_lshl_add_u64 v[216:217], v[222:223], 0, s[8:9]
	s_mov_b32 m0, s43
	s_nop 0
	global_load_lds_dwordx4 v[216:217], off
	s_waitcnt vmcnt(8)
	s_waitcnt lgkmcnt(0)
	s_barrier
	s_setprio 1
	s_waitcnt lgkmcnt(0)
	v_mfma_f32_16x16x32_bf16 v[60:63], v[152:155], v[184:187], v[60:63]
	v_mfma_f32_16x16x32_bf16 v[56:59], v[160:163], v[184:187], v[56:59]
	v_mfma_f32_16x16x32_bf16 v[44:47], v[152:155], v[192:195], v[44:47]
	v_mfma_f32_16x16x32_bf16 v[40:43], v[160:163], v[192:195], v[40:43]
	v_mfma_f32_16x16x32_bf16 v[28:31], v[152:155], v[200:203], v[28:31]
	v_mfma_f32_16x16x32_bf16 v[24:27], v[160:163], v[200:203], v[24:27]
	v_mfma_f32_16x16x32_bf16 v[12:15], v[152:155], v[208:211], v[12:15]
	v_mfma_f32_16x16x32_bf16 v[8:11], v[160:163], v[208:211], v[8:11]
	v_mfma_f32_16x16x32_bf16 v[60:63], v[156:159], v[188:191], v[60:63]
	v_mfma_f32_16x16x32_bf16 v[56:59], v[164:167], v[188:191], v[56:59]
	v_mfma_f32_16x16x32_bf16 v[44:47], v[156:159], v[196:199], v[44:47]
	v_mfma_f32_16x16x32_bf16 v[40:43], v[164:167], v[196:199], v[40:43]
	v_mfma_f32_16x16x32_bf16 v[28:31], v[156:159], v[204:207], v[28:31]
	v_mfma_f32_16x16x32_bf16 v[24:27], v[164:167], v[204:207], v[24:27]
	v_mfma_f32_16x16x32_bf16 v[12:15], v[156:159], v[212:215], v[12:15]
	v_mfma_f32_16x16x32_bf16 v[8:11], v[164:167], v[212:215], v[8:11]
	s_setprio 0
	s_setprio 1
	v_mfma_f32_16x16x32_bf16 v[52:55], v[168:171], v[184:187], v[52:55]
	v_mfma_f32_16x16x32_bf16 v[48:51], v[176:179], v[184:187], v[48:51]
	v_mfma_f32_16x16x32_bf16 v[36:39], v[168:171], v[192:195], v[36:39]
	v_mfma_f32_16x16x32_bf16 v[32:35], v[176:179], v[192:195], v[32:35]
	v_mfma_f32_16x16x32_bf16 v[20:23], v[168:171], v[200:203], v[20:23]
	v_mfma_f32_16x16x32_bf16 v[16:19], v[176:179], v[200:203], v[16:19]
	v_mfma_f32_16x16x32_bf16 v[4:7], v[168:171], v[208:211], v[4:7]
	v_mfma_f32_16x16x32_bf16 v[0:3], v[176:179], v[208:211], v[0:3]
	v_mfma_f32_16x16x32_bf16 v[52:55], v[172:175], v[188:191], v[52:55]
	v_mfma_f32_16x16x32_bf16 v[48:51], v[180:183], v[188:191], v[48:51]
	v_mfma_f32_16x16x32_bf16 v[36:39], v[172:175], v[196:199], v[36:39]
	v_mfma_f32_16x16x32_bf16 v[32:35], v[180:183], v[196:199], v[32:35]
	v_mfma_f32_16x16x32_bf16 v[20:23], v[172:175], v[204:207], v[20:23]
	v_mfma_f32_16x16x32_bf16 v[16:19], v[180:183], v[204:207], v[16:19]
	v_mfma_f32_16x16x32_bf16 v[4:7], v[172:175], v[212:215], v[4:7]
	v_mfma_f32_16x16x32_bf16 v[0:3], v[180:183], v[212:215], v[0:3]
	s_setprio 0
	s_barrier
	s_add_i32 s54, s54, 2
	s_add_u32 s24, s24, 0x100
	s_addc_u32 s25, s25, 0
	s_add_u32 s52, s52, 0x100
	s_addc_u32 s53, s53, 0
	s_cmp_gt_u32 s54, 13

; #define PG8_STAGE(bufoff, gbase, voff) do { _Pragma("unroll") for (int _i = 0; _i < 2; ++_i) \
;         __builtin_amdgcn_global_load_lds((const unsigned*)((const char*)(gbase) + (voff)[_i]), (PG8_LAS unsigned*)(lds + (bufoff) + ldsw + _i * 8192), 16, 0, 0); } while (0)
; #define PG8_LDA(dst, b, h) do { _Pragma("unroll") for (int m = 0; m < 4; ++m) _Pragma("unroll") for (int k = 0; k < 2; ++k) dst[m][k] = *(const PG8_LAS bf16x8*)(lds + PG8_SA(b, h) + aoff + m * 2048 + k * 1024); } while (0)
; #define PG8_LDB(dst, b, h) do { _Pragma("unroll") for (int n = 0; n < 2; ++n) _Pragma("unroll") for (int k = 0; k < 2; ++k) dst[n][k] = *(const PG8_LAS bf16x8*)(lds + PG8_SB(b, h) + boff + n * 2048 + k * 1024); } while (0)
; #define PG8_WAIT_V(n) asm volatile("s_waitcnt vmcnt(" #n ")" ::: "memory")
; #define PG8_WAIT_L(n) asm volatile("s_waitcnt lgkmcnt(" #n ")" ::: "memory")
; #define PG8_BAR __builtin_amdgcn_s_barrier()
; #define PG8_SCHED __builtin_amdgcn_sched_barrier(0)
; template <class Epi, class Sched, bool ALIGN_EPI = false, bool SP2 = false>
; __device__ __forceinline__ void gemm_phase(PG8_LAS unsigned char* lds, const Gemm g, const Sched& S, const Epi& E) {
;     ...
;         const bool has_next = S.next(ui + 1, nxt);
;         const char* nA = has_next ? (const char*)g.A + (size_t)nxt.pm * tstep : cA; const char* nB = has_next ? (const char*)g.Bt + (size_t)nxt.pn * tstep : cB;
;         for (int t = 0; t < nt; t += 2) {
;             const bool last = (t == nt - 2);
;             const char* a1 = cA + (size_t)(t + 1) * kstep;
;             const char* a2 = last ? nA : cA + (size_t)(t + 2) * kstep; const char* b2 = last ? nB : cB + (size_t)(t + 2) * kstep;
;             const char* a3 = a2 + kstep; const char* b3 = b2 + kstep;
;             if (last && has_next) S.a_ready(nxt, ui + 1);
;             if constexpr (SP2) {
;             PG8_LDB(B0, 0, 0); PG8_LDB(B1, 0, 1); PG8_SCHED; PG8_LDA(At, 0, 0); PG8_STAGE(PG8_SA(1, 1), a1 + hstep, voffA);
;             PG8_WAIT_V(8); PG8_WAIT_L(0); PG8_BAR; PG8_MMA(0, 0, At, B0); PG8_MMA(0, 1, At, B1); PG8_BAR; PG8_SCHED;
;             PG8_LDA(At, 0, 1); PG8_STAGE(PG8_SB(0, 0), b2, voffB); PG8_STAGE(PG8_SB(0, 1), b2 + hstep, voffB); PG8_STAGE(PG8_SA(0, 0), a2, voffA);
;             PG8_WAIT_V(8); PG8_WAIT_L(0); PG8_BAR; PG8_MMA(1, 0, At, B0); PG8_MMA(1, 1, At, B1); PG8_BAR; PG8_SCHED;
.LBB0_417:
	s_add_u32 s24, s24, 0xb0080
	s_addc_u32 s25, s25, 0
	s_add_u32 s51, s26, 0x100
	s_addc_u32 s52, s27, 0
	s_mov_b32 s53, -2
	s_waitcnt lgkmcnt(0)
	ds_read_b128 v[120:123], v245
	ds_read_b128 v[128:131], v245 offset:1024
	ds_read_b128 v[136:139], v245 offset:2048
	ds_read_b128 v[140:143], v245 offset:3072
	ds_read_b128 v[144:147], v246
	ds_read_b128 v[148:151], v246 offset:1024
	ds_read_b128 v[152:155], v246 offset:2048
	ds_read_b128 v[156:159], v246 offset:3072
	s_add_u32 s26, s24, 0xfff50080
	s_addc_u32 s27, s25, -1
	s_cmp_eq_u32 s53, 40
	s_cselect_b32 s29, s7, s27
	s_cselect_b32 s28, s6, s26
	s_cselect_b32 s27, s23, s52
	s_cselect_b32 s26, s22, s51
	v_lshl_add_u64 v[204:205], s[24:25], 0, v[200:201]
	s_add_i32 m0, s35, 0xc000
	ds_read_b128 v[160:163], v247
	ds_read_b128 v[164:167], v247 offset:1024
	ds_read_b128 v[168:171], v247 offset:2048
	ds_read_b128 v[172:175], v247 offset:3072
	ds_read_b128 v[176:179], v247 offset:4096
	ds_read_b128 v[180:183], v247 offset:5120
	ds_read_b128 v[184:187], v247 offset:6144
	ds_read_b128 v[188:191], v247 offset:7168
	global_load_lds_dwordx4 v[204:205], off
	v_lshl_add_u64 v[204:205], s[24:25], 0, v[202:203]
	s_add_i32 m0, s35, 0xe000
	s_nop 0
	global_load_lds_dwordx4 v[204:205], off
	s_waitcnt vmcnt(8)
	s_waitcnt lgkmcnt(0)
	s_barrier
	s_setprio 1
	s_waitcnt lgkmcnt(0)
	v_mfma_f32_16x16x32_bf16 v[132:135], v[120:123], v[160:163], 0
	v_mfma_f32_16x16x32_bf16 v[124:127], v[136:139], v[160:163], 0
	v_mfma_f32_16x16x32_bf16 v[108:111], v[120:123], v[168:171], 0
	v_mfma_f32_16x16x32_bf16 v[104:107], v[136:139], v[168:171], 0
	v_mfma_f32_16x16x32_bf16 v[92:95], v[120:123], v[176:179], 0
	v_mfma_f32_16x16x32_bf16 v[88:91], v[136:139], v[176:179], 0
	v_mfma_f32_16x16x32_bf16 v[76:79], v[120:123], v[184:187], 0
	v_mfma_f32_16x16x32_bf16 v[72:75], v[136:139], v[184:187], 0
	v_mfma_f32_16x16x32_bf16 v[132:135], v[128:131], v[164:167], v[132:135]
	v_mfma_f32_16x16x32_bf16 v[124:127], v[140:143], v[164:167], v[124:127]
	v_mfma_f32_16x16x32_bf16 v[108:111], v[128:131], v[172:175], v[108:111]
	v_mfma_f32_16x16x32_bf16 v[104:107], v[140:143], v[172:175], v[104:107]
	v_mfma_f32_16x16x32_bf16 v[92:95], v[128:131], v[180:183], v[92:95]
	v_mfma_f32_16x16x32_bf16 v[88:91], v[140:143], v[180:183], v[88:91]
	v_mfma_f32_16x16x32_bf16 v[76:79], v[128:131], v[188:191], v[76:79]
	v_mfma_f32_16x16x32_bf16 v[72:75], v[140:143], v[188:191], v[72:75]
	s_setprio 0
	s_setprio 1
	v_mfma_f32_16x16x32_bf16 v[116:119], v[144:147], v[160:163], 0
	v_mfma_f32_16x16x32_bf16 v[112:115], v[152:155], v[160:163], 0
	v_mfma_f32_16x16x32_bf16 v[100:103], v[144:147], v[168:171], 0
	v_mfma_f32_16x16x32_bf16 v[96:99], v[152:155], v[168:171], 0
	v_mfma_f32_16x16x32_bf16 v[84:87], v[144:147], v[176:179], 0
	v_mfma_f32_16x16x32_bf16 v[80:83], v[152:155], v[176:179], 0
	v_mfma_f32_16x16x32_bf16 v[68:71], v[144:147], v[184:187], 0
	v_mfma_f32_16x16x32_bf16 v[64:67], v[152:155], v[184:187], 0
	v_mfma_f32_16x16x32_bf16 v[116:119], v[148:151], v[164:167], v[116:119]
	v_mfma_f32_16x16x32_bf16 v[112:115], v[156:159], v[164:167], v[112:115]
	v_mfma_f32_16x16x32_bf16 v[100:103], v[148:151], v[172:175], v[100:103]
	v_mfma_f32_16x16x32_bf16 v[96:99], v[156:159], v[172:175], v[96:99]
	v_mfma_f32_16x16x32_bf16 v[84:87], v[148:151], v[180:183], v[84:87]
	v_mfma_f32_16x16x32_bf16 v[80:83], v[156:159], v[180:183], v[80:83]
	v_mfma_f32_16x16x32_bf16 v[68:71], v[148:151], v[188:191], v[68:71]
	v_mfma_f32_16x16x32_bf16 v[64:67], v[156:159], v[188:191], v[64:67]
	s_setprio 0
	s_barrier
	s_add_i32 s54, s45, s34
	v_lshl_add_u64 v[204:205], s[26:27], 0, v[194:195]
	s_mov_b32 m0, s54
	ds_read_b128 v[160:163], v247 offset:16384
	ds_read_b128 v[164:167], v247 offset:17408
	ds_read_b128 v[168:171], v247 offset:18432
	ds_read_b128 v[172:175], v247 offset:19456
	ds_read_b128 v[176:179], v247 offset:20480
	ds_read_b128 v[180:183], v247 offset:21504
	ds_read_b128 v[184:187], v247 offset:22528
	ds_read_b128 v[188:191], v247 offset:23552
	global_load_lds_dwordx4 v[204:205], off
	s_add_i32 m0, s54, 0x2000
	s_add_u32 s54, s26, 0xb0000
	v_lshl_add_u64 v[206:207], s[26:27], 0, v[198:199]
	s_addc_u32 s55, s27, 0
	s_add_i32 s56, s46, s34
	global_load_lds_dwordx4 v[206:207], off
	v_lshl_add_u64 v[208:209], s[54:55], 0, v[194:195]
	s_mov_b32 m0, s56
	v_lshl_add_u64 v[210:211], s[28:29], 0, v[196:197]
	global_load_lds_dwordx4 v[208:209], off
	v_lshl_add_u64 v[208:209], s[54:55], 0, v[198:199]
	s_add_i32 m0, s56, 0x2000
	s_nop 0
	global_load_lds_dwordx4 v[208:209], off
	v_lshl_add_u64 v[208:209], s[28:29], 0, v[192:193]
	s_mov_b32 m0, s35
	s_nop 0
	global_load_lds_dwordx4 v[208:209], off
	s_mov_b32 m0, s36
	s_nop 0
	global_load_lds_dwordx4 v[210:211], off
	s_waitcnt vmcnt(8)
	s_waitcnt lgkmcnt(0)
	s_barrier
; #define PG8_STAGE(bufoff, gbase, voff) do { _Pragma("unroll") for (int _i = 0; _i < 2; ++_i) \
;         __builtin_amdgcn_global_load_lds((const unsigned*)((const char*)(gbase) + (voff)[_i]), (PG8_LAS unsigned*)(lds + (bufoff) + ldsw + _i * 8192), 16, 0, 0); } while (0)
; #define PG8_LDA(dst, b, h) do { _Pragma("unroll") for (int m = 0; m < 4; ++m) _Pragma("unroll") for (int k = 0; k < 2; ++k) dst[m][k] = *(const PG8_LAS bf16x8*)(lds + PG8_SA(b, h) + aoff + m * 2048 + k * 1024); } while (0)
; #define PG8_LDB(dst, b, h) do { _Pragma("unroll") for (int n = 0; n < 2; ++n) _Pragma("unroll") for (int k = 0; k < 2; ++k) dst[n][k] = *(const PG8_LAS bf16x8*)(lds + PG8_SB(b, h) + boff + n * 2048 + k * 1024); } while (0)
; #define PG8_MMA(ai, bj, At, Bt) do { __builtin_amdgcn_s_setprio(1); _Pragma("unroll") for (int m = 0; m < 4; ++m) _Pragma("unroll") for (int n = 0; n < 2; ++n) _Pragma("unroll") for (int k = 0; k < 2; ++k) \
;         acc[ai][bj][m][n] = __builtin_amdgcn_mfma_f32_16x16x32_bf16(Bt[n][k], At[m][k], acc[ai][bj][m][n], 0, 0, 0); __builtin_amdgcn_s_setprio(0); } while (0)
; #define PG8_WAIT_V(n) asm volatile("s_waitcnt vmcnt(" #n ")" ::: "memory")
; #define PG8_WAIT_L(n) asm volatile("s_waitcnt lgkmcnt(" #n ")" ::: "memory")
; #define PG8_BAR __builtin_amdgcn_s_barrier()
; #define PG8_SCHED __builtin_amdgcn_sched_barrier(0)
; template <class Epi, class Sched, bool ALIGN_EPI = false, bool SP2 = false>
; __device__ __forceinline__ void gemm_phase(PG8_LAS unsigned char* lds, const Gemm g, const Sched& S, const Epi& E) {
;     ...
;             PG8_WAIT_V(8); PG8_WAIT_L(0); PG8_BAR; PG8_MMA(1, 0, At, B0); PG8_MMA(1, 1, At, B1); PG8_BAR; PG8_SCHED;
;             PG8_LDB(B0, 1, 0); PG8_LDB(B1, 1, 1); PG8_SCHED; PG8_LDA(At, 1, 0); PG8_STAGE(PG8_SA(0, 1), a2 + hstep, voffA);
;             PG8_WAIT_V(8); PG8_WAIT_L(0); PG8_BAR; PG8_MMA(0, 0, At, B0); PG8_MMA(0, 1, At, B1); PG8_BAR; PG8_SCHED;
	s_setprio 1
	s_waitcnt lgkmcnt(0)
	v_mfma_f32_16x16x32_bf16 v[60:63], v[120:123], v[160:163], 0
	v_mfma_f32_16x16x32_bf16 v[56:59], v[136:139], v[160:163], 0
	v_mfma_f32_16x16x32_bf16 v[44:47], v[120:123], v[168:171], 0
	v_mfma_f32_16x16x32_bf16 v[40:43], v[136:139], v[168:171], 0
	v_mfma_f32_16x16x32_bf16 v[28:31], v[120:123], v[176:179], 0
	v_mfma_f32_16x16x32_bf16 v[24:27], v[136:139], v[176:179], 0
	v_mfma_f32_16x16x32_bf16 v[12:15], v[120:123], v[184:187], 0
	v_mfma_f32_16x16x32_bf16 v[8:11], v[136:139], v[184:187], 0
	v_mfma_f32_16x16x32_bf16 v[60:63], v[128:131], v[164:167], v[60:63]
	v_mfma_f32_16x16x32_bf16 v[56:59], v[140:143], v[164:167], v[56:59]
	v_mfma_f32_16x16x32_bf16 v[44:47], v[128:131], v[172:175], v[44:47]
	v_mfma_f32_16x16x32_bf16 v[40:43], v[140:143], v[172:175], v[40:43]
	v_mfma_f32_16x16x32_bf16 v[28:31], v[128:131], v[180:183], v[28:31]
	v_mfma_f32_16x16x32_bf16 v[24:27], v[140:143], v[180:183], v[24:27]
	v_mfma_f32_16x16x32_bf16 v[12:15], v[128:131], v[188:191], v[12:15]
	v_mfma_f32_16x16x32_bf16 v[8:11], v[140:143], v[188:191], v[8:11]
	s_setprio 0
	s_setprio 1
	v_mfma_f32_16x16x32_bf16 v[52:55], v[144:147], v[160:163], 0
	v_mfma_f32_16x16x32_bf16 v[48:51], v[152:155], v[160:163], 0
	v_mfma_f32_16x16x32_bf16 v[36:39], v[144:147], v[168:171], 0
	v_mfma_f32_16x16x32_bf16 v[32:35], v[152:155], v[168:171], 0
	v_mfma_f32_16x16x32_bf16 v[20:23], v[144:147], v[176:179], 0
	v_mfma_f32_16x16x32_bf16 v[16:19], v[152:155], v[176:179], 0
	v_mfma_f32_16x16x32_bf16 v[4:7], v[144:147], v[184:187], 0
	v_mfma_f32_16x16x32_bf16 v[0:3], v[152:155], v[184:187], 0
	v_mfma_f32_16x16x32_bf16 v[52:55], v[148:151], v[164:167], v[52:55]
	v_mfma_f32_16x16x32_bf16 v[48:51], v[156:159], v[164:167], v[48:51]
	v_mfma_f32_16x16x32_bf16 v[36:39], v[148:151], v[172:175], v[36:39]
	v_mfma_f32_16x16x32_bf16 v[32:35], v[156:159], v[172:175], v[32:35]
	v_mfma_f32_16x16x32_bf16 v[20:23], v[148:151], v[180:183], v[20:23]
	v_mfma_f32_16x16x32_bf16 v[16:19], v[156:159], v[180:183], v[16:19]
	v_mfma_f32_16x16x32_bf16 v[4:7], v[148:151], v[188:191], v[4:7]
	v_mfma_f32_16x16x32_bf16 v[0:3], v[156:159], v[188:191], v[0:3]
	s_setprio 0
	s_barrier
	s_add_i32 s54, 0, 0x18000
	s_add_i32 s55, 0, 0x1c000
	v_add_u32_e32 v140, s54, v243
	v_add_u32_e32 v156, s55, v243
	ds_read_b128 v[120:123], v140
	ds_read_b128 v[128:131], v140 offset:1024
	ds_read_b128 v[136:139], v140 offset:2048
	ds_read_b128 v[140:143], v140 offset:3072
	ds_read_b128 v[144:147], v156
	ds_read_b128 v[148:151], v156 offset:1024
	ds_read_b128 v[152:155], v156 offset:2048
	ds_read_b128 v[156:159], v156 offset:3072
	s_add_u32 s28, s28, 0xb0000
	s_addc_u32 s29, s29, 0
	s_mov_b32 m0, s37
	v_lshl_add_u64 v[212:213], s[28:29], 0, v[192:193]
	ds_read_b128 v[160:163], v247 offset:32768
	ds_read_b128 v[164:167], v247 offset:33792
	ds_read_b128 v[168:171], v247 offset:34816
	ds_read_b128 v[172:175], v247 offset:35840
	ds_read_b128 v[176:179], v247 offset:36864
	ds_read_b128 v[180:183], v247 offset:37888
	ds_read_b128 v[184:187], v247 offset:38912
	ds_read_b128 v[188:191], v247 offset:39936
	global_load_lds_dwordx4 v[212:213], off
	v_lshl_add_u64 v[212:213], s[28:29], 0, v[196:197]
	s_mov_b32 m0, s38
	s_nop 0
	global_load_lds_dwordx4 v[212:213], off
	s_waitcnt vmcnt(8)
	s_waitcnt lgkmcnt(0)
	s_barrier
	s_setprio 1
	s_waitcnt lgkmcnt(0)
	v_mfma_f32_16x16x32_bf16 v[132:135], v[120:123], v[160:163], v[132:135]
	v_mfma_f32_16x16x32_bf16 v[124:127], v[136:139], v[160:163], v[124:127]
	v_mfma_f32_16x16x32_bf16 v[108:111], v[120:123], v[168:171], v[108:111]
	v_mfma_f32_16x16x32_bf16 v[104:107], v[136:139], v[168:171], v[104:107]
	v_mfma_f32_16x16x32_bf16 v[92:95], v[120:123], v[176:179], v[92:95]
	v_mfma_f32_16x16x32_bf16 v[88:91], v[136:139], v[176:179], v[88:91]
	v_mfma_f32_16x16x32_bf16 v[76:79], v[120:123], v[184:187], v[76:79]
	v_mfma_f32_16x16x32_bf16 v[72:75], v[136:139], v[184:187], v[72:75]
	v_mfma_f32_16x16x32_bf16 v[132:135], v[128:131], v[164:167], v[132:135]
	v_mfma_f32_16x16x32_bf16 v[124:127], v[140:143], v[164:167], v[124:127]
	v_mfma_f32_16x16x32_bf16 v[108:111], v[128:131], v[172:175], v[108:111]
	v_mfma_f32_16x16x32_bf16 v[104:107], v[140:143], v[172:175], v[104:107]
	v_mfma_f32_16x16x32_bf16 v[92:95], v[128:131], v[180:183], v[92:95]
	v_mfma_f32_16x16x32_bf16 v[88:91], v[140:143], v[180:183], v[88:91]
	v_mfma_f32_16x16x32_bf16 v[76:79], v[128:131], v[188:191], v[76:79]
	v_mfma_f32_16x16x32_bf16 v[72:75], v[140:143], v[188:191], v[72:75]
	s_setprio 0
	s_setprio 1
	v_mfma_f32_16x16x32_bf16 v[116:119], v[144:147], v[160:163], v[116:119]
	v_mfma_f32_16x16x32_bf16 v[112:115], v[152:155], v[160:163], v[112:115]
	v_mfma_f32_16x16x32_bf16 v[100:103], v[144:147], v[168:171], v[100:103]
	v_mfma_f32_16x16x32_bf16 v[96:99], v[152:155], v[168:171], v[96:99]
	v_mfma_f32_16x16x32_bf16 v[84:87], v[144:147], v[176:179], v[84:87]
	v_mfma_f32_16x16x32_bf16 v[80:83], v[152:155], v[176:179], v[80:83]
	v_mfma_f32_16x16x32_bf16 v[68:71], v[144:147], v[184:187], v[68:71]
	v_mfma_f32_16x16x32_bf16 v[64:67], v[152:155], v[184:187], v[64:67]
	v_mfma_f32_16x16x32_bf16 v[116:119], v[148:151], v[164:167], v[116:119]
	v_mfma_f32_16x16x32_bf16 v[112:115], v[156:159], v[164:167], v[112:115]
	v_mfma_f32_16x16x32_bf16 v[100:103], v[148:151], v[172:175], v[100:103]
	v_mfma_f32_16x16x32_bf16 v[96:99], v[156:159], v[172:175], v[96:99]
	v_mfma_f32_16x16x32_bf16 v[84:87], v[148:151], v[180:183], v[84:87]
	v_mfma_f32_16x16x32_bf16 v[80:83], v[156:159], v[180:183], v[80:83]
	v_mfma_f32_16x16x32_bf16 v[68:71], v[148:151], v[188:191], v[68:71]
	v_mfma_f32_16x16x32_bf16 v[64:67], v[156:159], v[188:191], v[64:67]
	s_setprio 0
	s_barrier
; #define PG8_STAGE(bufoff, gbase, voff) do { _Pragma("unroll") for (int _i = 0; _i < 2; ++_i) \
;         __builtin_amdgcn_global_load_lds((const unsigned*)((const char*)(gbase) + (voff)[_i]), (PG8_LAS unsigned*)(lds + (bufoff) + ldsw + _i * 8192), 16, 0, 0); } while (0)
; #define PG8_LDA(dst, b, h) do { _Pragma("unroll") for (int m = 0; m < 4; ++m) _Pragma("unroll") for (int k = 0; k < 2; ++k) dst[m][k] = *(const PG8_LAS bf16x8*)(lds + PG8_SA(b, h) + aoff + m * 2048 + k * 1024); } while (0)
; #define PG8_MMA(ai, bj, At, Bt) do { __builtin_amdgcn_s_setprio(1); _Pragma("unroll") for (int m = 0; m < 4; ++m) _Pragma("unroll") for (int n = 0; n < 2; ++n) _Pragma("unroll") for (int k = 0; k < 2; ++k) \
;         acc[ai][bj][m][n] = __builtin_amdgcn_mfma_f32_16x16x32_bf16(Bt[n][k], At[m][k], acc[ai][bj][m][n], 0, 0, 0); __builtin_amdgcn_s_setprio(0); } while (0)
; #define PG8_WAIT_V(n) asm volatile("s_waitcnt vmcnt(" #n ")" ::: "memory")
; #define PG8_WAIT_L(n) asm volatile("s_waitcnt lgkmcnt(" #n ")" ::: "memory")
; #define PG8_BAR __builtin_amdgcn_s_barrier()
; #define PG8_SCHED __builtin_amdgcn_sched_barrier(0)
; template <class Epi, class Sched, bool ALIGN_EPI = false, bool SP2 = false>
; __device__ __forceinline__ void gemm_phase(PG8_LAS unsigned char* lds, const Gemm g, const Sched& S, const Epi& E) {
;     ...
;         for (int t = 0; t < nt; t += 2) {
;     ...
;             PG8_LDA(At, 1, 1); PG8_STAGE(PG8_SB(1, 0), b3, voffB); PG8_STAGE(PG8_SB(1, 1), b3 + hstep, voffB); PG8_STAGE(PG8_SA(1, 0), a3, voffA);
;             PG8_WAIT_V(8); PG8_WAIT_L(0); PG8_BAR; PG8_MMA(1, 0, At, B0); PG8_MMA(1, 1, At, B1); PG8_BAR; PG8_SCHED;
	s_add_i32 s28, s54, s34
	v_lshl_add_u64 v[204:205], v[204:205], 0, s[18:19]
	s_mov_b32 m0, s28
	ds_read_b128 v[160:163], v247 offset:49152
	ds_read_b128 v[164:167], v247 offset:50176
	ds_read_b128 v[168:171], v247 offset:51200
	ds_read_b128 v[172:175], v247 offset:52224
	ds_read_b128 v[176:179], v247 offset:53248
	ds_read_b128 v[180:183], v247 offset:54272
	ds_read_b128 v[184:187], v247 offset:55296
	ds_read_b128 v[188:191], v247 offset:56320
	global_load_lds_dwordx4 v[204:205], off
	s_add_i32 m0, s28, 0x2000
	s_add_u32 s26, s26, 0xb0080
	v_lshl_add_u64 v[204:205], v[206:207], 0, s[18:19]
	s_addc_u32 s27, s27, 0
	s_add_i32 s28, s55, s34
	global_load_lds_dwordx4 v[204:205], off
	v_lshl_add_u64 v[204:205], s[26:27], 0, v[194:195]
	s_mov_b32 m0, s28
	s_nop 0
	global_load_lds_dwordx4 v[204:205], off
	v_lshl_add_u64 v[204:205], s[26:27], 0, v[198:199]
	s_add_i32 m0, s28, 0x2000
	s_nop 0
	global_load_lds_dwordx4 v[204:205], off
	v_lshl_add_u64 v[204:205], v[208:209], 0, s[18:19]
	s_mov_b32 m0, s40
	s_nop 0
	global_load_lds_dwordx4 v[204:205], off
	v_lshl_add_u64 v[204:205], v[210:211], 0, s[18:19]
	s_mov_b32 m0, s41
	s_nop 0
	global_load_lds_dwordx4 v[204:205], off
	s_waitcnt vmcnt(8)
	s_waitcnt lgkmcnt(0)
	s_barrier
	s_setprio 1
	s_waitcnt lgkmcnt(0)
	v_mfma_f32_16x16x32_bf16 v[60:63], v[120:123], v[160:163], v[60:63]
	v_mfma_f32_16x16x32_bf16 v[56:59], v[136:139], v[160:163], v[56:59]
	v_mfma_f32_16x16x32_bf16 v[44:47], v[120:123], v[168:171], v[44:47]
	v_mfma_f32_16x16x32_bf16 v[40:43], v[136:139], v[168:171], v[40:43]
	v_mfma_f32_16x16x32_bf16 v[28:31], v[120:123], v[176:179], v[28:31]
	v_mfma_f32_16x16x32_bf16 v[24:27], v[136:139], v[176:179], v[24:27]
	v_mfma_f32_16x16x32_bf16 v[12:15], v[120:123], v[184:187], v[12:15]
	v_mfma_f32_16x16x32_bf16 v[8:11], v[136:139], v[184:187], v[8:11]
	v_mfma_f32_16x16x32_bf16 v[60:63], v[128:131], v[164:167], v[60:63]
	v_mfma_f32_16x16x32_bf16 v[56:59], v[140:143], v[164:167], v[56:59]
	v_mfma_f32_16x16x32_bf16 v[44:47], v[128:131], v[172:175], v[44:47]
	v_mfma_f32_16x16x32_bf16 v[40:43], v[140:143], v[172:175], v[40:43]
	v_mfma_f32_16x16x32_bf16 v[28:31], v[128:131], v[180:183], v[28:31]
	v_mfma_f32_16x16x32_bf16 v[24:27], v[140:143], v[180:183], v[24:27]
	v_mfma_f32_16x16x32_bf16 v[12:15], v[128:131], v[188:191], v[12:15]
	v_mfma_f32_16x16x32_bf16 v[8:11], v[140:143], v[188:191], v[8:11]
	s_setprio 0
	s_setprio 1
	v_mfma_f32_16x16x32_bf16 v[52:55], v[144:147], v[160:163], v[52:55]
	v_mfma_f32_16x16x32_bf16 v[48:51], v[152:155], v[160:163], v[48:51]
	v_mfma_f32_16x16x32_bf16 v[36:39], v[144:147], v[168:171], v[36:39]
	v_mfma_f32_16x16x32_bf16 v[32:35], v[152:155], v[168:171], v[32:35]
	v_mfma_f32_16x16x32_bf16 v[20:23], v[144:147], v[176:179], v[20:23]
	v_mfma_f32_16x16x32_bf16 v[16:19], v[152:155], v[176:179], v[16:19]
	v_mfma_f32_16x16x32_bf16 v[4:7], v[144:147], v[184:187], v[4:7]
	v_mfma_f32_16x16x32_bf16 v[0:3], v[152:155], v[184:187], v[0:3]
	v_mfma_f32_16x16x32_bf16 v[52:55], v[148:151], v[164:167], v[52:55]
	v_mfma_f32_16x16x32_bf16 v[48:51], v[156:159], v[164:167], v[48:51]
	v_mfma_f32_16x16x32_bf16 v[36:39], v[148:151], v[172:175], v[36:39]
	v_mfma_f32_16x16x32_bf16 v[32:35], v[156:159], v[172:175], v[32:35]
	v_mfma_f32_16x16x32_bf16 v[20:23], v[148:151], v[180:183], v[20:23]
	v_mfma_f32_16x16x32_bf16 v[16:19], v[156:159], v[180:183], v[16:19]
	v_mfma_f32_16x16x32_bf16 v[4:7], v[148:151], v[188:191], v[4:7]
	v_mfma_f32_16x16x32_bf16 v[0:3], v[156:159], v[188:191], v[0:3]
	s_setprio 0
	s_barrier
	s_add_i32 s53, s53, 2
	s_add_u32 s24, s24, 0x100
	s_addc_u32 s25, s25, 0
	s_add_u32 s51, s51, 0x100
	s_addc_u32 s52, s52, 0
	s_cmp_gt_u32 s53, 41

; #define PG8_STAGE(bufoff, gbase, voff) do { _Pragma("unroll") for (int _i = 0; _i < 2; ++_i) \
;         __builtin_amdgcn_global_load_lds((const unsigned*)((const char*)(gbase) + (voff)[_i]), (PG8_LAS unsigned*)(lds + (bufoff) + ldsw + _i * 8192), 16, 0, 0); } while (0)
; #define PG8_LDA(dst, b, h) do { _Pragma("unroll") for (int m = 0; m < 4; ++m) _Pragma("unroll") for (int k = 0; k < 2; ++k) dst[m][k] = *(const PG8_LAS bf16x8*)(lds + PG8_SA(b, h) + aoff + m * 2048 + k * 1024); } while (0)
; #define PG8_LDB(dst, b, h) do { _Pragma("unroll") for (int n = 0; n < 2; ++n) _Pragma("unroll") for (int k = 0; k < 2; ++k) dst[n][k] = *(const PG8_LAS bf16x8*)(lds + PG8_SB(b, h) + boff + n * 2048 + k * 1024); } while (0)
; #define PG8_WAIT_V(n) asm volatile("s_waitcnt vmcnt(" #n ")" ::: "memory")
; #define PG8_WAIT_L(n) asm volatile("s_waitcnt lgkmcnt(" #n ")" ::: "memory")
; #define PG8_BAR __builtin_amdgcn_s_barrier()
; #define PG8_SCHED __builtin_amdgcn_sched_barrier(0)
; template <class Epi, class Sched, bool ALIGN_EPI = false, bool SP2 = false>
; __device__ __forceinline__ void gemm_phase(PG8_LAS unsigned char* lds, const Gemm g, const Sched& S, const Epi& E) {
;     ...
;         const bool has_next = S.next(ui + 1, nxt);
;         const char* nA = has_next ? (const char*)g.A + (size_t)nxt.pm * tstep : cA; const char* nB = has_next ? (const char*)g.Bt + (size_t)nxt.pn * tstep : cB;
;         for (int t = 0; t < nt; t += 2) {
;             const bool last = (t == nt - 2);
;             const char* a1 = cA + (size_t)(t + 1) * kstep;
;             const char* a2 = last ? nA : cA + (size_t)(t + 2) * kstep; const char* b2 = last ? nB : cB + (size_t)(t + 2) * kstep;
;             const char* a3 = a2 + kstep; const char* b3 = b2 + kstep;
;             if (last && has_next) S.a_ready(nxt, ui + 1);
;             if constexpr (SP2) {
;             PG8_LDB(B0, 0, 0); PG8_LDB(B1, 0, 1); PG8_SCHED; PG8_LDA(At, 0, 0); PG8_STAGE(PG8_SA(1, 1), a1 + hstep, voffA);
;             PG8_WAIT_V(8); PG8_WAIT_L(0); PG8_BAR; PG8_MMA(0, 0, At, B0); PG8_MMA(0, 1, At, B1); PG8_BAR; PG8_SCHED;
;             PG8_LDA(At, 0, 1); PG8_STAGE(PG8_SB(0, 0), b2, voffB); PG8_STAGE(PG8_SB(0, 1), b2 + hstep, voffB); PG8_STAGE(PG8_SA(0, 0), a2, voffA);
;             PG8_WAIT_V(8); PG8_WAIT_L(0); PG8_BAR; PG8_MMA(1, 0, At, B0); PG8_MMA(1, 1, At, B1); PG8_BAR; PG8_SCHED;
.LBB0_508:
	s_ashr_i32 s31, s30, 31
	s_lshl_b64 s[34:35], s[30:31], 19
	s_add_u32 s34, s48, s34
	s_addc_u32 s35, s49, s35
	s_and_b64 s[36:37], s[4:5], exec
	s_cselect_b32 s9, s35, s39
	s_cselect_b32 s14, s34, s38
	s_ashr_i32 s29, s28, 31
	s_lshl_b64 s[36:37], s[28:29], 19
	s_add_u32 s36, s50, s36
	s_addc_u32 s37, s51, s37
	s_and_b64 s[42:43], s[4:5], exec
	s_cselect_b32 s29, s37, s41
	s_cselect_b32 s31, s36, s40
	s_add_u32 s38, s38, 0x40080
	s_addc_u32 s39, s39, 0
	s_add_u32 s44, s40, 0x100
	s_addc_u32 s45, s41, 0
	s_mov_b32 s70, -2
	ds_read_b128 v[148:151], v162
	ds_read_b128 v[166:169], v162 offset:1024
	ds_read_b128 v[170:173], v162 offset:2048
	ds_read_b128 v[174:177], v162 offset:3072
	ds_read_b128 v[178:181], v163
	ds_read_b128 v[182:185], v163 offset:1024
	ds_read_b128 v[186:189], v163 offset:2048
	ds_read_b128 v[190:193], v163 offset:3072
	s_add_u32 s40, s38, 0xfffc0080
	s_addc_u32 s41, s39, -1
	s_cmp_eq_u32 s70, 12
	s_cselect_b32 s43, s9, s41
	s_cselect_b32 s42, s14, s40
	s_cselect_b32 s41, s29, s45
	s_cselect_b32 s40, s31, s44
	v_lshl_add_u64 v[226:227], s[38:39], 0, v[132:133]
	s_add_i32 m0, s52, 0xc000
	ds_read_b128 v[194:197], v164
	ds_read_b128 v[198:201], v164 offset:1024
	ds_read_b128 v[202:205], v164 offset:2048
	ds_read_b128 v[206:209], v164 offset:3072
	ds_read_b128 v[210:213], v164 offset:4096
	ds_read_b128 v[214:217], v164 offset:5120
	ds_read_b128 v[218:221], v164 offset:6144
	ds_read_b128 v[222:225], v164 offset:7168
	global_load_lds_dwordx4 v[226:227], off
	v_lshl_add_u64 v[226:227], s[38:39], 0, v[134:135]
	s_add_i32 m0, s52, 0xe000
	s_nop 0
	global_load_lds_dwordx4 v[226:227], off
	s_waitcnt vmcnt(8)
	s_waitcnt lgkmcnt(0)
	s_barrier
	s_setprio 1
	s_waitcnt lgkmcnt(0)
	v_mfma_f32_16x16x32_bf16 v[124:127], v[148:151], v[194:197], 0
	v_mfma_f32_16x16x32_bf16 v[120:123], v[170:173], v[194:197], 0
	v_mfma_f32_16x16x32_bf16 v[108:111], v[148:151], v[202:205], 0
	v_mfma_f32_16x16x32_bf16 v[104:107], v[170:173], v[202:205], 0
	v_mfma_f32_16x16x32_bf16 v[92:95], v[148:151], v[210:213], 0
	v_mfma_f32_16x16x32_bf16 v[88:91], v[170:173], v[210:213], 0
	v_mfma_f32_16x16x32_bf16 v[76:79], v[148:151], v[218:221], 0
	v_mfma_f32_16x16x32_bf16 v[72:75], v[170:173], v[218:221], 0
	v_mfma_f32_16x16x32_bf16 v[124:127], v[166:169], v[198:201], v[124:127]
	v_mfma_f32_16x16x32_bf16 v[120:123], v[174:177], v[198:201], v[120:123]
	v_mfma_f32_16x16x32_bf16 v[108:111], v[166:169], v[206:209], v[108:111]
	v_mfma_f32_16x16x32_bf16 v[104:107], v[174:177], v[206:209], v[104:107]
	v_mfma_f32_16x16x32_bf16 v[92:95], v[166:169], v[214:217], v[92:95]
	v_mfma_f32_16x16x32_bf16 v[88:91], v[174:177], v[214:217], v[88:91]
	v_mfma_f32_16x16x32_bf16 v[76:79], v[166:169], v[222:225], v[76:79]
	v_mfma_f32_16x16x32_bf16 v[72:75], v[174:177], v[222:225], v[72:75]
	s_setprio 0
	s_setprio 1
	v_mfma_f32_16x16x32_bf16 v[116:119], v[178:181], v[194:197], 0
	v_mfma_f32_16x16x32_bf16 v[112:115], v[186:189], v[194:197], 0
	v_mfma_f32_16x16x32_bf16 v[100:103], v[178:181], v[202:205], 0
	v_mfma_f32_16x16x32_bf16 v[96:99], v[186:189], v[202:205], 0
	v_mfma_f32_16x16x32_bf16 v[84:87], v[178:181], v[210:213], 0
	v_mfma_f32_16x16x32_bf16 v[80:83], v[186:189], v[210:213], 0
	v_mfma_f32_16x16x32_bf16 v[68:71], v[178:181], v[218:221], 0
	v_mfma_f32_16x16x32_bf16 v[64:67], v[186:189], v[218:221], 0
	v_mfma_f32_16x16x32_bf16 v[116:119], v[182:185], v[198:201], v[116:119]
	v_mfma_f32_16x16x32_bf16 v[112:115], v[190:193], v[198:201], v[112:115]
	v_mfma_f32_16x16x32_bf16 v[100:103], v[182:185], v[206:209], v[100:103]
	v_mfma_f32_16x16x32_bf16 v[96:99], v[190:193], v[206:209], v[96:99]
	v_mfma_f32_16x16x32_bf16 v[84:87], v[182:185], v[214:217], v[84:87]
	v_mfma_f32_16x16x32_bf16 v[80:83], v[190:193], v[214:217], v[80:83]
	v_mfma_f32_16x16x32_bf16 v[68:71], v[182:185], v[222:225], v[68:71]
	v_mfma_f32_16x16x32_bf16 v[64:67], v[190:193], v[222:225], v[64:67]
	s_setprio 0
	s_barrier
	s_add_i32 s71, s61, s33
	v_lshl_add_u64 v[226:227], s[40:41], 0, v[138:139]
	s_mov_b32 m0, s71
	ds_read_b128 v[194:197], v164 offset:16384
	ds_read_b128 v[198:201], v164 offset:17408
	ds_read_b128 v[202:205], v164 offset:18432
	ds_read_b128 v[206:209], v164 offset:19456
	ds_read_b128 v[210:213], v164 offset:20480
	ds_read_b128 v[214:217], v164 offset:21504
	ds_read_b128 v[218:221], v164 offset:22528
	ds_read_b128 v[222:225], v164 offset:23552
	global_load_lds_dwordx4 v[226:227], off
	s_add_i32 m0, s71, 0x2000
	s_add_u32 s72, s40, 0x40000
	v_lshl_add_u64 v[228:229], s[40:41], 0, v[142:143]
	s_addc_u32 s73, s41, 0
	s_add_i32 s71, s62, s33
	global_load_lds_dwordx4 v[228:229], off
	v_lshl_add_u64 v[230:231], s[72:73], 0, v[138:139]
	s_mov_b32 m0, s71
	v_lshl_add_u64 v[232:233], s[42:43], 0, v[140:141]
	global_load_lds_dwordx4 v[230:231], off
	v_lshl_add_u64 v[230:231], s[72:73], 0, v[142:143]
	s_add_i32 m0, s71, 0x2000
	s_nop 0
	global_load_lds_dwordx4 v[230:231], off
	v_lshl_add_u64 v[230:231], s[42:43], 0, v[136:137]
	s_mov_b32 m0, s52
	s_nop 0
	global_load_lds_dwordx4 v[230:231], off
	s_mov_b32 m0, s53
	s_nop 0
	global_load_lds_dwordx4 v[232:233], off
	s_waitcnt vmcnt(8)
	s_waitcnt lgkmcnt(0)
	s_barrier
; #define PG8_STAGE(bufoff, gbase, voff) do { _Pragma("unroll") for (int _i = 0; _i < 2; ++_i) \
;         __builtin_amdgcn_global_load_lds((const unsigned*)((const char*)(gbase) + (voff)[_i]), (PG8_LAS unsigned*)(lds + (bufoff) + ldsw + _i * 8192), 16, 0, 0); } while (0)
; #define PG8_LDA(dst, b, h) do { _Pragma("unroll") for (int m = 0; m < 4; ++m) _Pragma("unroll") for (int k = 0; k < 2; ++k) dst[m][k] = *(const PG8_LAS bf16x8*)(lds + PG8_SA(b, h) + aoff + m * 2048 + k * 1024); } while (0)
; #define PG8_LDB(dst, b, h) do { _Pragma("unroll") for (int n = 0; n < 2; ++n) _Pragma("unroll") for (int k = 0; k < 2; ++k) dst[n][k] = *(const PG8_LAS bf16x8*)(lds + PG8_SB(b, h) + boff + n * 2048 + k * 1024); } while (0)
; #define PG8_MMA(ai, bj, At, Bt) do { __builtin_amdgcn_s_setprio(1); _Pragma("unroll") for (int m = 0; m < 4; ++m) _Pragma("unroll") for (int n = 0; n < 2; ++n) _Pragma("unroll") for (int k = 0; k < 2; ++k) \
;         acc[ai][bj][m][n] = __builtin_amdgcn_mfma_f32_16x16x32_bf16(Bt[n][k], At[m][k], acc[ai][bj][m][n], 0, 0, 0); __builtin_amdgcn_s_setprio(0); } while (0)
; #define PG8_WAIT_V(n) asm volatile("s_waitcnt vmcnt(" #n ")" ::: "memory")
; #define PG8_WAIT_L(n) asm volatile("s_waitcnt lgkmcnt(" #n ")" ::: "memory")
; #define PG8_BAR __builtin_amdgcn_s_barrier()
; #define PG8_SCHED __builtin_amdgcn_sched_barrier(0)
; template <class Epi, class Sched, bool ALIGN_EPI = false, bool SP2 = false>
; __device__ __forceinline__ void gemm_phase(PG8_LAS unsigned char* lds, const Gemm g, const Sched& S, const Epi& E) {
;     ...
;             PG8_WAIT_V(8); PG8_WAIT_L(0); PG8_BAR; PG8_MMA(1, 0, At, B0); PG8_MMA(1, 1, At, B1); PG8_BAR; PG8_SCHED;
;             PG8_LDB(B0, 1, 0); PG8_LDB(B1, 1, 1); PG8_SCHED; PG8_LDA(At, 1, 0); PG8_STAGE(PG8_SA(0, 1), a2 + hstep, voffA);
;             PG8_WAIT_V(8); PG8_WAIT_L(0); PG8_BAR; PG8_MMA(0, 0, At, B0); PG8_MMA(0, 1, At, B1); PG8_BAR; PG8_SCHED;
	s_setprio 1
	s_waitcnt lgkmcnt(0)
	v_mfma_f32_16x16x32_bf16 v[60:63], v[148:151], v[194:197], 0
	v_mfma_f32_16x16x32_bf16 v[56:59], v[170:173], v[194:197], 0
	v_mfma_f32_16x16x32_bf16 v[44:47], v[148:151], v[202:205], 0
	v_mfma_f32_16x16x32_bf16 v[40:43], v[170:173], v[202:205], 0
	v_mfma_f32_16x16x32_bf16 v[28:31], v[148:151], v[210:213], 0
	v_mfma_f32_16x16x32_bf16 v[24:27], v[170:173], v[210:213], 0
	v_mfma_f32_16x16x32_bf16 v[12:15], v[148:151], v[218:221], 0
	v_mfma_f32_16x16x32_bf16 v[8:11], v[170:173], v[218:221], 0
	v_mfma_f32_16x16x32_bf16 v[60:63], v[166:169], v[198:201], v[60:63]
	v_mfma_f32_16x16x32_bf16 v[56:59], v[174:177], v[198:201], v[56:59]
	v_mfma_f32_16x16x32_bf16 v[44:47], v[166:169], v[206:209], v[44:47]
	v_mfma_f32_16x16x32_bf16 v[40:43], v[174:177], v[206:209], v[40:43]
	v_mfma_f32_16x16x32_bf16 v[28:31], v[166:169], v[214:217], v[28:31]
	v_mfma_f32_16x16x32_bf16 v[24:27], v[174:177], v[214:217], v[24:27]
	v_mfma_f32_16x16x32_bf16 v[12:15], v[166:169], v[222:225], v[12:15]
	v_mfma_f32_16x16x32_bf16 v[8:11], v[174:177], v[222:225], v[8:11]
	s_setprio 0
	s_setprio 1
	v_mfma_f32_16x16x32_bf16 v[52:55], v[178:181], v[194:197], 0
	v_mfma_f32_16x16x32_bf16 v[48:51], v[186:189], v[194:197], 0
	v_mfma_f32_16x16x32_bf16 v[36:39], v[178:181], v[202:205], 0
	v_mfma_f32_16x16x32_bf16 v[32:35], v[186:189], v[202:205], 0
	v_mfma_f32_16x16x32_bf16 v[20:23], v[178:181], v[210:213], 0
	v_mfma_f32_16x16x32_bf16 v[16:19], v[186:189], v[210:213], 0
	v_mfma_f32_16x16x32_bf16 v[4:7], v[178:181], v[218:221], 0
	v_mfma_f32_16x16x32_bf16 v[0:3], v[186:189], v[218:221], 0
	v_mfma_f32_16x16x32_bf16 v[52:55], v[182:185], v[198:201], v[52:55]
	v_mfma_f32_16x16x32_bf16 v[48:51], v[190:193], v[198:201], v[48:51]
	v_mfma_f32_16x16x32_bf16 v[36:39], v[182:185], v[206:209], v[36:39]
	v_mfma_f32_16x16x32_bf16 v[32:35], v[190:193], v[206:209], v[32:35]
	v_mfma_f32_16x16x32_bf16 v[20:23], v[182:185], v[214:217], v[20:23]
	v_mfma_f32_16x16x32_bf16 v[16:19], v[190:193], v[214:217], v[16:19]
	v_mfma_f32_16x16x32_bf16 v[4:7], v[182:185], v[222:225], v[4:7]
	v_mfma_f32_16x16x32_bf16 v[0:3], v[190:193], v[222:225], v[0:3]
	s_setprio 0
	s_barrier
	s_add_i32 s71, 0, 0x18000
	v_add_u32_e32 v130, s71, v160
	s_add_i32 s72, 0, 0x1c000
	ds_read_b128 v[148:151], v130
	ds_read_b128 v[166:169], v130 offset:1024
	ds_read_b128 v[170:173], v130 offset:2048
	ds_read_b128 v[174:177], v130 offset:3072
	v_add_u32_e32 v130, s72, v160
	ds_read_b128 v[178:181], v130
	ds_read_b128 v[182:185], v130 offset:1024
	ds_read_b128 v[186:189], v130 offset:2048
	ds_read_b128 v[190:193], v130 offset:3072
	s_add_u32 s42, s42, 0x40000
	s_addc_u32 s43, s43, 0
	s_mov_b32 m0, s54
	v_lshl_add_u64 v[234:235], s[42:43], 0, v[136:137]
	ds_read_b128 v[194:197], v164 offset:32768
	ds_read_b128 v[198:201], v164 offset:33792
	ds_read_b128 v[202:205], v164 offset:34816
	ds_read_b128 v[206:209], v164 offset:35840
	ds_read_b128 v[210:213], v164 offset:36864
	ds_read_b128 v[214:217], v164 offset:37888
	ds_read_b128 v[218:221], v164 offset:38912
	ds_read_b128 v[222:225], v164 offset:39936
	global_load_lds_dwordx4 v[234:235], off
	v_lshl_add_u64 v[234:235], s[42:43], 0, v[140:141]
	s_mov_b32 m0, s55
	s_nop 0
	global_load_lds_dwordx4 v[234:235], off
	s_waitcnt vmcnt(8)
	s_waitcnt lgkmcnt(0)
	s_barrier
	s_setprio 1
	s_waitcnt lgkmcnt(0)
	v_mfma_f32_16x16x32_bf16 v[124:127], v[148:151], v[194:197], v[124:127]
	v_mfma_f32_16x16x32_bf16 v[120:123], v[170:173], v[194:197], v[120:123]
	v_mfma_f32_16x16x32_bf16 v[108:111], v[148:151], v[202:205], v[108:111]
	v_mfma_f32_16x16x32_bf16 v[104:107], v[170:173], v[202:205], v[104:107]
	v_mfma_f32_16x16x32_bf16 v[92:95], v[148:151], v[210:213], v[92:95]
	v_mfma_f32_16x16x32_bf16 v[88:91], v[170:173], v[210:213], v[88:91]
	v_mfma_f32_16x16x32_bf16 v[76:79], v[148:151], v[218:221], v[76:79]
	v_mfma_f32_16x16x32_bf16 v[72:75], v[170:173], v[218:221], v[72:75]
	v_mfma_f32_16x16x32_bf16 v[124:127], v[166:169], v[198:201], v[124:127]
	v_mfma_f32_16x16x32_bf16 v[120:123], v[174:177], v[198:201], v[120:123]
	v_mfma_f32_16x16x32_bf16 v[108:111], v[166:169], v[206:209], v[108:111]
	v_mfma_f32_16x16x32_bf16 v[104:107], v[174:177], v[206:209], v[104:107]
	v_mfma_f32_16x16x32_bf16 v[92:95], v[166:169], v[214:217], v[92:95]
	v_mfma_f32_16x16x32_bf16 v[88:91], v[174:177], v[214:217], v[88:91]
	v_mfma_f32_16x16x32_bf16 v[76:79], v[166:169], v[222:225], v[76:79]
	v_mfma_f32_16x16x32_bf16 v[72:75], v[174:177], v[222:225], v[72:75]
	s_setprio 0
	s_setprio 1
	v_mfma_f32_16x16x32_bf16 v[116:119], v[178:181], v[194:197], v[116:119]
	v_mfma_f32_16x16x32_bf16 v[112:115], v[186:189], v[194:197], v[112:115]
	v_mfma_f32_16x16x32_bf16 v[100:103], v[178:181], v[202:205], v[100:103]
	v_mfma_f32_16x16x32_bf16 v[96:99], v[186:189], v[202:205], v[96:99]
	v_mfma_f32_16x16x32_bf16 v[84:87], v[178:181], v[210:213], v[84:87]
	v_mfma_f32_16x16x32_bf16 v[80:83], v[186:189], v[210:213], v[80:83]
	v_mfma_f32_16x16x32_bf16 v[68:71], v[178:181], v[218:221], v[68:71]
	v_mfma_f32_16x16x32_bf16 v[64:67], v[186:189], v[218:221], v[64:67]
	v_mfma_f32_16x16x32_bf16 v[116:119], v[182:185], v[198:201], v[116:119]
	v_mfma_f32_16x16x32_bf16 v[112:115], v[190:193], v[198:201], v[112:115]
	v_mfma_f32_16x16x32_bf16 v[100:103], v[182:185], v[206:209], v[100:103]
	v_mfma_f32_16x16x32_bf16 v[96:99], v[190:193], v[206:209], v[96:99]
	v_mfma_f32_16x16x32_bf16 v[84:87], v[182:185], v[214:217], v[84:87]
	v_mfma_f32_16x16x32_bf16 v[80:83], v[190:193], v[214:217], v[80:83]
	v_mfma_f32_16x16x32_bf16 v[68:71], v[182:185], v[222:225], v[68:71]
	v_mfma_f32_16x16x32_bf16 v[64:67], v[190:193], v[222:225], v[64:67]
	s_setprio 0
	s_barrier
; #define PG8_STAGE(bufoff, gbase, voff) do { _Pragma("unroll") for (int _i = 0; _i < 2; ++_i) \
;         __builtin_amdgcn_global_load_lds((const unsigned*)((const char*)(gbase) + (voff)[_i]), (PG8_LAS unsigned*)(lds + (bufoff) + ldsw + _i * 8192), 16, 0, 0); } while (0)
; #define PG8_LDA(dst, b, h) do { _Pragma("unroll") for (int m = 0; m < 4; ++m) _Pragma("unroll") for (int k = 0; k < 2; ++k) dst[m][k] = *(const PG8_LAS bf16x8*)(lds + PG8_SA(b, h) + aoff + m * 2048 + k * 1024); } while (0)
; #define PG8_MMA(ai, bj, At, Bt) do { __builtin_amdgcn_s_setprio(1); _Pragma("unroll") for (int m = 0; m < 4; ++m) _Pragma("unroll") for (int n = 0; n < 2; ++n) _Pragma("unroll") for (int k = 0; k < 2; ++k) \
;         acc[ai][bj][m][n] = __builtin_amdgcn_mfma_f32_16x16x32_bf16(Bt[n][k], At[m][k], acc[ai][bj][m][n], 0, 0, 0); __builtin_amdgcn_s_setprio(0); } while (0)
; #define PG8_WAIT_V(n) asm volatile("s_waitcnt vmcnt(" #n ")" ::: "memory")
; #define PG8_WAIT_L(n) asm volatile("s_waitcnt lgkmcnt(" #n ")" ::: "memory")
; #define PG8_BAR __builtin_amdgcn_s_barrier()
; #define PG8_SCHED __builtin_amdgcn_sched_barrier(0)
; template <class Epi, class Sched, bool ALIGN_EPI = false, bool SP2 = false>
; __device__ __forceinline__ void gemm_phase(PG8_LAS unsigned char* lds, const Gemm g, const Sched& S, const Epi& E) {
;     ...
;         for (int t = 0; t < nt; t += 2) {
;     ...
;             PG8_LDA(At, 1, 1); PG8_STAGE(PG8_SB(1, 0), b3, voffB); PG8_STAGE(PG8_SB(1, 1), b3 + hstep, voffB); PG8_STAGE(PG8_SA(1, 0), a3, voffA);
;             PG8_WAIT_V(8); PG8_WAIT_L(0); PG8_BAR; PG8_MMA(1, 0, At, B0); PG8_MMA(1, 1, At, B1); PG8_BAR; PG8_SCHED;
	s_add_i32 s42, s71, s33
	v_lshl_add_u64 v[226:227], v[226:227], 0, s[24:25]
	s_mov_b32 m0, s42
	ds_read_b128 v[194:197], v164 offset:49152
	ds_read_b128 v[198:201], v164 offset:50176
	ds_read_b128 v[202:205], v164 offset:51200
	ds_read_b128 v[206:209], v164 offset:52224
	ds_read_b128 v[210:213], v164 offset:53248
	ds_read_b128 v[214:217], v164 offset:54272
	ds_read_b128 v[218:221], v164 offset:55296
	ds_read_b128 v[222:225], v164 offset:56320
	global_load_lds_dwordx4 v[226:227], off
	s_add_i32 m0, s42, 0x2000
	s_add_u32 s40, s40, 0x40080
	v_lshl_add_u64 v[226:227], v[228:229], 0, s[24:25]
	s_addc_u32 s41, s41, 0
	s_add_i32 s42, s72, s33
	global_load_lds_dwordx4 v[226:227], off
	v_lshl_add_u64 v[226:227], s[40:41], 0, v[138:139]
	s_mov_b32 m0, s42
	s_nop 0
	global_load_lds_dwordx4 v[226:227], off
	v_lshl_add_u64 v[226:227], s[40:41], 0, v[142:143]
	s_add_i32 m0, s42, 0x2000
	s_nop 0
	global_load_lds_dwordx4 v[226:227], off
	v_lshl_add_u64 v[226:227], v[230:231], 0, s[24:25]
	s_mov_b32 m0, s57
	s_nop 0
	global_load_lds_dwordx4 v[226:227], off
	v_lshl_add_u64 v[226:227], v[232:233], 0, s[24:25]
	s_mov_b32 m0, s58
	s_nop 0
	global_load_lds_dwordx4 v[226:227], off
	s_waitcnt vmcnt(8)
	s_waitcnt lgkmcnt(0)
	s_barrier
	s_setprio 1
	s_waitcnt lgkmcnt(0)
	v_mfma_f32_16x16x32_bf16 v[60:63], v[148:151], v[194:197], v[60:63]
	v_mfma_f32_16x16x32_bf16 v[56:59], v[170:173], v[194:197], v[56:59]
	v_mfma_f32_16x16x32_bf16 v[44:47], v[148:151], v[202:205], v[44:47]
	v_mfma_f32_16x16x32_bf16 v[40:43], v[170:173], v[202:205], v[40:43]
	v_mfma_f32_16x16x32_bf16 v[28:31], v[148:151], v[210:213], v[28:31]
	v_mfma_f32_16x16x32_bf16 v[24:27], v[170:173], v[210:213], v[24:27]
	v_mfma_f32_16x16x32_bf16 v[12:15], v[148:151], v[218:221], v[12:15]
	v_mfma_f32_16x16x32_bf16 v[8:11], v[170:173], v[218:221], v[8:11]
	v_mfma_f32_16x16x32_bf16 v[60:63], v[166:169], v[198:201], v[60:63]
	v_mfma_f32_16x16x32_bf16 v[56:59], v[174:177], v[198:201], v[56:59]
	v_mfma_f32_16x16x32_bf16 v[44:47], v[166:169], v[206:209], v[44:47]
	v_mfma_f32_16x16x32_bf16 v[40:43], v[174:177], v[206:209], v[40:43]
	v_mfma_f32_16x16x32_bf16 v[28:31], v[166:169], v[214:217], v[28:31]
	v_mfma_f32_16x16x32_bf16 v[24:27], v[174:177], v[214:217], v[24:27]
	v_mfma_f32_16x16x32_bf16 v[12:15], v[166:169], v[222:225], v[12:15]
	v_mfma_f32_16x16x32_bf16 v[8:11], v[174:177], v[222:225], v[8:11]
	s_setprio 0
	s_setprio 1
	v_mfma_f32_16x16x32_bf16 v[52:55], v[178:181], v[194:197], v[52:55]
	v_mfma_f32_16x16x32_bf16 v[48:51], v[186:189], v[194:197], v[48:51]
	v_mfma_f32_16x16x32_bf16 v[36:39], v[178:181], v[202:205], v[36:39]
	v_mfma_f32_16x16x32_bf16 v[32:35], v[186:189], v[202:205], v[32:35]
	v_mfma_f32_16x16x32_bf16 v[20:23], v[178:181], v[210:213], v[20:23]
	v_mfma_f32_16x16x32_bf16 v[16:19], v[186:189], v[210:213], v[16:19]
	v_mfma_f32_16x16x32_bf16 v[4:7], v[178:181], v[218:221], v[4:7]
	v_mfma_f32_16x16x32_bf16 v[0:3], v[186:189], v[218:221], v[0:3]
	v_mfma_f32_16x16x32_bf16 v[52:55], v[182:185], v[198:201], v[52:55]
	v_mfma_f32_16x16x32_bf16 v[48:51], v[190:193], v[198:201], v[48:51]
	v_mfma_f32_16x16x32_bf16 v[36:39], v[182:185], v[206:209], v[36:39]
	v_mfma_f32_16x16x32_bf16 v[32:35], v[190:193], v[206:209], v[32:35]
	v_mfma_f32_16x16x32_bf16 v[20:23], v[182:185], v[214:217], v[20:23]
	v_mfma_f32_16x16x32_bf16 v[16:19], v[190:193], v[214:217], v[16:19]
	v_mfma_f32_16x16x32_bf16 v[4:7], v[182:185], v[222:225], v[4:7]
	v_mfma_f32_16x16x32_bf16 v[0:3], v[190:193], v[222:225], v[0:3]
	s_setprio 0
	s_barrier
	s_add_i32 s70, s70, 2
	s_add_u32 s38, s38, 0x100
	s_addc_u32 s39, s39, 0
	s_add_u32 s44, s44, 0x100
	s_addc_u32 s45, s45, 0
	s_cmp_gt_u32 s70, 13

; #define PG8_STAGE(bufoff, gbase, voff) do { _Pragma("unroll") for (int _i = 0; _i < 2; ++_i) \
;         __builtin_amdgcn_global_load_lds((const unsigned*)((const char*)(gbase) + (voff)[_i]), (PG8_LAS unsigned*)(lds + (bufoff) + ldsw + _i * 8192), 16, 0, 0); } while (0)
; #define PG8_LDA(dst, b, h) do { _Pragma("unroll") for (int m = 0; m < 4; ++m) _Pragma("unroll") for (int k = 0; k < 2; ++k) dst[m][k] = *(const PG8_LAS bf16x8*)(lds + PG8_SA(b, h) + aoff + m * 2048 + k * 1024); } while (0)
; #define PG8_LDB(dst, b, h) do { _Pragma("unroll") for (int n = 0; n < 2; ++n) _Pragma("unroll") for (int k = 0; k < 2; ++k) dst[n][k] = *(const PG8_LAS bf16x8*)(lds + PG8_SB(b, h) + boff + n * 2048 + k * 1024); } while (0)
; #define PG8_WAIT_V(n) asm volatile("s_waitcnt vmcnt(" #n ")" ::: "memory")
; #define PG8_WAIT_L(n) asm volatile("s_waitcnt lgkmcnt(" #n ")" ::: "memory")
; #define PG8_BAR __builtin_amdgcn_s_barrier()
; #define PG8_SCHED __builtin_amdgcn_sched_barrier(0)
; template <class Epi, class Sched, bool ALIGN_EPI = false, bool SP2 = false>
; __device__ __forceinline__ void gemm_phase(PG8_LAS unsigned char* lds, const Gemm g, const Sched& S, const Epi& E) {
;     ...
;         const bool has_next = S.next(ui + 1, nxt);
;         const char* nA = has_next ? (const char*)g.A + (size_t)nxt.pm * tstep : cA; const char* nB = has_next ? (const char*)g.Bt + (size_t)nxt.pn * tstep : cB;
;         for (int t = 0; t < nt; t += 2) {
;             const bool last = (t == nt - 2);
;             const char* a1 = cA + (size_t)(t + 1) * kstep;
;             const char* a2 = last ? nA : cA + (size_t)(t + 2) * kstep; const char* b2 = last ? nB : cB + (size_t)(t + 2) * kstep;
;             const char* a3 = a2 + kstep; const char* b3 = b2 + kstep;
;             if (last && has_next) S.a_ready(nxt, ui + 1);
;             if constexpr (SP2) {
;             PG8_LDB(B0, 0, 0); PG8_LDB(B1, 0, 1); PG8_SCHED; PG8_LDA(At, 0, 0); PG8_STAGE(PG8_SA(1, 1), a1 + hstep, voffA);
;             PG8_WAIT_V(8); PG8_WAIT_L(0); PG8_BAR; PG8_MMA(0, 0, At, B0); PG8_MMA(0, 1, At, B1); PG8_BAR; PG8_SCHED;
;             PG8_LDA(At, 0, 1); PG8_STAGE(PG8_SB(0, 0), b2, voffB); PG8_STAGE(PG8_SB(0, 1), b2 + hstep, voffB); PG8_STAGE(PG8_SA(0, 0), a2, voffA);
;             PG8_WAIT_V(8); PG8_WAIT_L(0); PG8_BAR; PG8_MMA(1, 0, At, B0); PG8_MMA(1, 1, At, B1); PG8_BAR; PG8_SCHED;
.LBB0_606:
	s_ashr_i32 s21, s20, 31
	s_lshl_b64 s[22:23], s[20:21], 19
	s_add_u32 s22, s36, s22
	s_addc_u32 s23, s37, s23
	s_and_b64 s[24:25], s[4:5], exec
	s_cselect_b32 s21, s23, s29
	s_cselect_b32 s55, s22, s28
	s_ashr_i32 s19, s18, 31
	s_lshl_b64 s[24:25], s[18:19], 19
	s_add_u32 s24, s48, s24
	s_addc_u32 s25, s49, s25
	s_and_b64 s[34:35], s[4:5], exec
	s_cselect_b32 s19, s25, s31
	s_cselect_b32 s56, s24, s30
	s_add_u32 s28, s28, 0x40080
	s_addc_u32 s29, s29, 0
	s_add_u32 s57, s30, 0x100
	s_addc_u32 s58, s31, 0
	s_mov_b32 s59, -2
	ds_read_b128 v[128:131], v170
	ds_read_b128 v[132:135], v170 offset:1024
	ds_read_b128 v[174:177], v170 offset:2048
	ds_read_b128 v[178:181], v170 offset:3072
	ds_read_b128 v[182:185], v171
	ds_read_b128 v[186:189], v171 offset:1024
	ds_read_b128 v[190:193], v171 offset:2048
	ds_read_b128 v[194:197], v171 offset:3072
	s_add_u32 s30, s28, 0xfffc0080
	s_addc_u32 s31, s29, -1
	s_cmp_eq_u32 s59, 12
	s_cselect_b32 s35, s21, s31
	s_cselect_b32 s34, s55, s30
	s_cselect_b32 s31, s19, s58
	s_cselect_b32 s30, s56, s57
	v_lshl_add_u64 v[160:161], s[28:29], 0, v[152:153]
	s_add_i32 m0, s38, 0xc000
	ds_read_b128 v[198:201], v172
	ds_read_b128 v[202:205], v172 offset:1024
	ds_read_b128 v[206:209], v172 offset:2048
	ds_read_b128 v[210:213], v172 offset:3072
	ds_read_b128 v[214:217], v172 offset:4096
	ds_read_b128 v[218:221], v172 offset:5120
	ds_read_b128 v[222:225], v172 offset:6144
	ds_read_b128 v[226:229], v172 offset:7168
	global_load_lds_dwordx4 v[160:161], off
	v_lshl_add_u64 v[160:161], s[28:29], 0, v[154:155]
	s_add_i32 m0, s38, 0xe000
	s_nop 0
	global_load_lds_dwordx4 v[160:161], off
	s_waitcnt vmcnt(8)
	s_waitcnt lgkmcnt(0)
	s_barrier
	s_setprio 1
	s_waitcnt lgkmcnt(0)
	v_mfma_f32_16x16x32_bf16 v[124:127], v[128:131], v[198:201], 0
	v_mfma_f32_16x16x32_bf16 v[120:123], v[174:177], v[198:201], 0
	v_mfma_f32_16x16x32_bf16 v[116:119], v[128:131], v[206:209], 0
	v_mfma_f32_16x16x32_bf16 v[112:115], v[174:177], v[206:209], 0
	v_mfma_f32_16x16x32_bf16 v[108:111], v[128:131], v[214:217], 0
	v_mfma_f32_16x16x32_bf16 v[104:107], v[174:177], v[214:217], 0
	v_mfma_f32_16x16x32_bf16 v[100:103], v[128:131], v[222:225], 0
	v_mfma_f32_16x16x32_bf16 v[96:99], v[174:177], v[222:225], 0
	v_mfma_f32_16x16x32_bf16 v[124:127], v[132:135], v[202:205], v[124:127]
	v_mfma_f32_16x16x32_bf16 v[120:123], v[178:181], v[202:205], v[120:123]
	v_mfma_f32_16x16x32_bf16 v[116:119], v[132:135], v[210:213], v[116:119]
	v_mfma_f32_16x16x32_bf16 v[112:115], v[178:181], v[210:213], v[112:115]
	v_mfma_f32_16x16x32_bf16 v[108:111], v[132:135], v[218:221], v[108:111]
	v_mfma_f32_16x16x32_bf16 v[104:107], v[178:181], v[218:221], v[104:107]
	v_mfma_f32_16x16x32_bf16 v[100:103], v[132:135], v[226:229], v[100:103]
	v_mfma_f32_16x16x32_bf16 v[96:99], v[178:181], v[226:229], v[96:99]
	s_setprio 0
	s_setprio 1
	v_mfma_f32_16x16x32_bf16 v[60:63], v[182:185], v[198:201], 0
	v_mfma_f32_16x16x32_bf16 v[56:59], v[190:193], v[198:201], 0
	v_mfma_f32_16x16x32_bf16 v[52:55], v[182:185], v[206:209], 0
	v_mfma_f32_16x16x32_bf16 v[48:51], v[190:193], v[206:209], 0
	v_mfma_f32_16x16x32_bf16 v[44:47], v[182:185], v[214:217], 0
	v_mfma_f32_16x16x32_bf16 v[40:43], v[190:193], v[214:217], 0
	v_mfma_f32_16x16x32_bf16 v[36:39], v[182:185], v[222:225], 0
	v_mfma_f32_16x16x32_bf16 v[32:35], v[190:193], v[222:225], 0
	v_mfma_f32_16x16x32_bf16 v[60:63], v[186:189], v[202:205], v[60:63]
	v_mfma_f32_16x16x32_bf16 v[56:59], v[194:197], v[202:205], v[56:59]
	v_mfma_f32_16x16x32_bf16 v[52:55], v[186:189], v[210:213], v[52:55]
	v_mfma_f32_16x16x32_bf16 v[48:51], v[194:197], v[210:213], v[48:51]
	v_mfma_f32_16x16x32_bf16 v[44:47], v[186:189], v[218:221], v[44:47]
	v_mfma_f32_16x16x32_bf16 v[40:43], v[194:197], v[218:221], v[40:43]
	v_mfma_f32_16x16x32_bf16 v[36:39], v[186:189], v[226:229], v[36:39]
	v_mfma_f32_16x16x32_bf16 v[32:35], v[194:197], v[226:229], v[32:35]
	s_setprio 0
	s_barrier
	s_add_i32 s60, s45, s33
	v_lshl_add_u64 v[160:161], s[30:31], 0, v[138:139]
	s_mov_b32 m0, s60
	ds_read_b128 v[198:201], v172 offset:16384
	ds_read_b128 v[202:205], v172 offset:17408
	ds_read_b128 v[206:209], v172 offset:18432
	ds_read_b128 v[210:213], v172 offset:19456
	ds_read_b128 v[214:217], v172 offset:20480
	ds_read_b128 v[218:221], v172 offset:21504
	ds_read_b128 v[222:225], v172 offset:22528
	ds_read_b128 v[226:229], v172 offset:23552
	global_load_lds_dwordx4 v[160:161], off
	s_add_i32 m0, s60, 0x2000
	s_add_u32 s60, s30, 0x40000
	v_lshl_add_u64 v[230:231], s[30:31], 0, v[142:143]
	s_addc_u32 s61, s31, 0
	s_add_i32 s62, s50, s33
	global_load_lds_dwordx4 v[230:231], off
	v_lshl_add_u64 v[232:233], s[60:61], 0, v[138:139]
	s_mov_b32 m0, s62
	v_lshl_add_u64 v[234:235], s[34:35], 0, v[140:141]
	global_load_lds_dwordx4 v[232:233], off
	v_lshl_add_u64 v[232:233], s[60:61], 0, v[142:143]
	s_add_i32 m0, s62, 0x2000
	s_nop 0
	global_load_lds_dwordx4 v[232:233], off
	v_lshl_add_u64 v[232:233], s[34:35], 0, v[136:137]
	s_mov_b32 m0, s38
	s_nop 0
	global_load_lds_dwordx4 v[232:233], off
	s_mov_b32 m0, s39
	s_nop 0
	global_load_lds_dwordx4 v[234:235], off
	s_waitcnt vmcnt(8)
	s_waitcnt lgkmcnt(0)
	s_barrier
; #define PG8_STAGE(bufoff, gbase, voff) do { _Pragma("unroll") for (int _i = 0; _i < 2; ++_i) \
;         __builtin_amdgcn_global_load_lds((const unsigned*)((const char*)(gbase) + (voff)[_i]), (PG8_LAS unsigned*)(lds + (bufoff) + ldsw + _i * 8192), 16, 0, 0); } while (0)
; #define PG8_LDA(dst, b, h) do { _Pragma("unroll") for (int m = 0; m < 4; ++m) _Pragma("unroll") for (int k = 0; k < 2; ++k) dst[m][k] = *(const PG8_LAS bf16x8*)(lds + PG8_SA(b, h) + aoff + m * 2048 + k * 1024); } while (0)
; #define PG8_LDB(dst, b, h) do { _Pragma("unroll") for (int n = 0; n < 2; ++n) _Pragma("unroll") for (int k = 0; k < 2; ++k) dst[n][k] = *(const PG8_LAS bf16x8*)(lds + PG8_SB(b, h) + boff + n * 2048 + k * 1024); } while (0)
; #define PG8_MMA(ai, bj, At, Bt) do { __builtin_amdgcn_s_setprio(1); _Pragma("unroll") for (int m = 0; m < 4; ++m) _Pragma("unroll") for (int n = 0; n < 2; ++n) _Pragma("unroll") for (int k = 0; k < 2; ++k) \
;         acc[ai][bj][m][n] = __builtin_amdgcn_mfma_f32_16x16x32_bf16(Bt[n][k], At[m][k], acc[ai][bj][m][n], 0, 0, 0); __builtin_amdgcn_s_setprio(0); } while (0)
; #define PG8_WAIT_V(n) asm volatile("s_waitcnt vmcnt(" #n ")" ::: "memory")
; #define PG8_WAIT_L(n) asm volatile("s_waitcnt lgkmcnt(" #n ")" ::: "memory")
; #define PG8_BAR __builtin_amdgcn_s_barrier()
; #define PG8_SCHED __builtin_amdgcn_sched_barrier(0)
; template <class Epi, class Sched, bool ALIGN_EPI = false, bool SP2 = false>
; __device__ __forceinline__ void gemm_phase(PG8_LAS unsigned char* lds, const Gemm g, const Sched& S, const Epi& E) {
;     ...
;             PG8_WAIT_V(8); PG8_WAIT_L(0); PG8_BAR; PG8_MMA(1, 0, At, B0); PG8_MMA(1, 1, At, B1); PG8_BAR; PG8_SCHED;
;             PG8_LDB(B0, 1, 0); PG8_LDB(B1, 1, 1); PG8_SCHED; PG8_LDA(At, 1, 0); PG8_STAGE(PG8_SA(0, 1), a2 + hstep, voffA);
;             PG8_WAIT_V(8); PG8_WAIT_L(0); PG8_BAR; PG8_MMA(0, 0, At, B0); PG8_MMA(0, 1, At, B1); PG8_BAR; PG8_SCHED;
	s_setprio 1
	s_waitcnt lgkmcnt(0)
	v_mfma_f32_16x16x32_bf16 v[92:95], v[128:131], v[198:201], 0
	v_mfma_f32_16x16x32_bf16 v[88:91], v[174:177], v[198:201], 0
	v_mfma_f32_16x16x32_bf16 v[84:87], v[128:131], v[206:209], 0
	v_mfma_f32_16x16x32_bf16 v[80:83], v[174:177], v[206:209], 0
	v_mfma_f32_16x16x32_bf16 v[76:79], v[128:131], v[214:217], 0
	v_mfma_f32_16x16x32_bf16 v[72:75], v[174:177], v[214:217], 0
	v_mfma_f32_16x16x32_bf16 v[68:71], v[128:131], v[222:225], 0
	v_mfma_f32_16x16x32_bf16 v[64:67], v[174:177], v[222:225], 0
	v_mfma_f32_16x16x32_bf16 v[92:95], v[132:135], v[202:205], v[92:95]
	v_mfma_f32_16x16x32_bf16 v[88:91], v[178:181], v[202:205], v[88:91]
	v_mfma_f32_16x16x32_bf16 v[84:87], v[132:135], v[210:213], v[84:87]
	v_mfma_f32_16x16x32_bf16 v[80:83], v[178:181], v[210:213], v[80:83]
	v_mfma_f32_16x16x32_bf16 v[76:79], v[132:135], v[218:221], v[76:79]
	v_mfma_f32_16x16x32_bf16 v[72:75], v[178:181], v[218:221], v[72:75]
	v_mfma_f32_16x16x32_bf16 v[68:71], v[132:135], v[226:229], v[68:71]
	v_mfma_f32_16x16x32_bf16 v[64:67], v[178:181], v[226:229], v[64:67]
	s_setprio 0
	s_setprio 1
	v_mfma_f32_16x16x32_bf16 v[28:31], v[182:185], v[198:201], 0
	v_mfma_f32_16x16x32_bf16 v[24:27], v[190:193], v[198:201], 0
	v_mfma_f32_16x16x32_bf16 v[20:23], v[182:185], v[206:209], 0
	v_mfma_f32_16x16x32_bf16 v[16:19], v[190:193], v[206:209], 0
	v_mfma_f32_16x16x32_bf16 v[12:15], v[182:185], v[214:217], 0
	v_mfma_f32_16x16x32_bf16 v[8:11], v[190:193], v[214:217], 0
	v_mfma_f32_16x16x32_bf16 v[4:7], v[182:185], v[222:225], 0
	v_mfma_f32_16x16x32_bf16 v[0:3], v[190:193], v[222:225], 0
	v_mfma_f32_16x16x32_bf16 v[28:31], v[186:189], v[202:205], v[28:31]
	v_mfma_f32_16x16x32_bf16 v[24:27], v[194:197], v[202:205], v[24:27]
	v_mfma_f32_16x16x32_bf16 v[20:23], v[186:189], v[210:213], v[20:23]
	v_mfma_f32_16x16x32_bf16 v[16:19], v[194:197], v[210:213], v[16:19]
	v_mfma_f32_16x16x32_bf16 v[12:15], v[186:189], v[218:221], v[12:15]
	v_mfma_f32_16x16x32_bf16 v[8:11], v[194:197], v[218:221], v[8:11]
	v_mfma_f32_16x16x32_bf16 v[4:7], v[186:189], v[226:229], v[4:7]
	v_mfma_f32_16x16x32_bf16 v[0:3], v[194:197], v[226:229], v[0:3]
	s_setprio 0
	s_barrier
	s_add_i32 s60, 0, 0x18000
	s_add_i32 s61, 0, 0x1c000
	v_add_u32_e32 v178, s60, v163
	v_add_u32_e32 v194, s61, v163
	ds_read_b128 v[128:131], v178
	ds_read_b128 v[132:135], v178 offset:1024
	ds_read_b128 v[174:177], v178 offset:2048
	ds_read_b128 v[178:181], v178 offset:3072
	ds_read_b128 v[182:185], v194
	ds_read_b128 v[186:189], v194 offset:1024
	ds_read_b128 v[190:193], v194 offset:2048
	ds_read_b128 v[194:197], v194 offset:3072
	s_add_u32 s34, s34, 0x40000
	s_addc_u32 s35, s35, 0
	s_mov_b32 m0, s40
	v_lshl_add_u64 v[236:237], s[34:35], 0, v[136:137]
	ds_read_b128 v[198:201], v172 offset:32768
	ds_read_b128 v[202:205], v172 offset:33792
	ds_read_b128 v[206:209], v172 offset:34816
	ds_read_b128 v[210:213], v172 offset:35840
	ds_read_b128 v[214:217], v172 offset:36864
	ds_read_b128 v[218:221], v172 offset:37888
	ds_read_b128 v[222:225], v172 offset:38912
	ds_read_b128 v[226:229], v172 offset:39936
	global_load_lds_dwordx4 v[236:237], off
	v_lshl_add_u64 v[236:237], s[34:35], 0, v[140:141]
	s_mov_b32 m0, s41
	s_nop 0
	global_load_lds_dwordx4 v[236:237], off
	s_waitcnt vmcnt(8)
	s_waitcnt lgkmcnt(0)
	s_barrier
	s_setprio 1
	s_waitcnt lgkmcnt(0)
	v_mfma_f32_16x16x32_bf16 v[124:127], v[128:131], v[198:201], v[124:127]
	v_mfma_f32_16x16x32_bf16 v[120:123], v[174:177], v[198:201], v[120:123]
	v_mfma_f32_16x16x32_bf16 v[116:119], v[128:131], v[206:209], v[116:119]
	v_mfma_f32_16x16x32_bf16 v[112:115], v[174:177], v[206:209], v[112:115]
	v_mfma_f32_16x16x32_bf16 v[108:111], v[128:131], v[214:217], v[108:111]
	v_mfma_f32_16x16x32_bf16 v[104:107], v[174:177], v[214:217], v[104:107]
	v_mfma_f32_16x16x32_bf16 v[100:103], v[128:131], v[222:225], v[100:103]
	v_mfma_f32_16x16x32_bf16 v[96:99], v[174:177], v[222:225], v[96:99]
	v_mfma_f32_16x16x32_bf16 v[124:127], v[132:135], v[202:205], v[124:127]
	v_mfma_f32_16x16x32_bf16 v[120:123], v[178:181], v[202:205], v[120:123]
	v_mfma_f32_16x16x32_bf16 v[116:119], v[132:135], v[210:213], v[116:119]
	v_mfma_f32_16x16x32_bf16 v[112:115], v[178:181], v[210:213], v[112:115]
	v_mfma_f32_16x16x32_bf16 v[108:111], v[132:135], v[218:221], v[108:111]
	v_mfma_f32_16x16x32_bf16 v[104:107], v[178:181], v[218:221], v[104:107]
	v_mfma_f32_16x16x32_bf16 v[100:103], v[132:135], v[226:229], v[100:103]
	v_mfma_f32_16x16x32_bf16 v[96:99], v[178:181], v[226:229], v[96:99]
	s_setprio 0
	s_setprio 1
	v_mfma_f32_16x16x32_bf16 v[60:63], v[182:185], v[198:201], v[60:63]
	v_mfma_f32_16x16x32_bf16 v[56:59], v[190:193], v[198:201], v[56:59]
	v_mfma_f32_16x16x32_bf16 v[52:55], v[182:185], v[206:209], v[52:55]
	v_mfma_f32_16x16x32_bf16 v[48:51], v[190:193], v[206:209], v[48:51]
	v_mfma_f32_16x16x32_bf16 v[44:47], v[182:185], v[214:217], v[44:47]
	v_mfma_f32_16x16x32_bf16 v[40:43], v[190:193], v[214:217], v[40:43]
	v_mfma_f32_16x16x32_bf16 v[36:39], v[182:185], v[222:225], v[36:39]
	v_mfma_f32_16x16x32_bf16 v[32:35], v[190:193], v[222:225], v[32:35]
	v_mfma_f32_16x16x32_bf16 v[60:63], v[186:189], v[202:205], v[60:63]
	v_mfma_f32_16x16x32_bf16 v[56:59], v[194:197], v[202:205], v[56:59]
	v_mfma_f32_16x16x32_bf16 v[52:55], v[186:189], v[210:213], v[52:55]
	v_mfma_f32_16x16x32_bf16 v[48:51], v[194:197], v[210:213], v[48:51]
	v_mfma_f32_16x16x32_bf16 v[44:47], v[186:189], v[218:221], v[44:47]
	v_mfma_f32_16x16x32_bf16 v[40:43], v[194:197], v[218:221], v[40:43]
	v_mfma_f32_16x16x32_bf16 v[36:39], v[186:189], v[226:229], v[36:39]
	v_mfma_f32_16x16x32_bf16 v[32:35], v[194:197], v[226:229], v[32:35]
	s_setprio 0
	s_barrier
; #define PG8_STAGE(bufoff, gbase, voff) do { _Pragma("unroll") for (int _i = 0; _i < 2; ++_i) \
;         __builtin_amdgcn_global_load_lds((const unsigned*)((const char*)(gbase) + (voff)[_i]), (PG8_LAS unsigned*)(lds + (bufoff) + ldsw + _i * 8192), 16, 0, 0); } while (0)
; #define PG8_LDA(dst, b, h) do { _Pragma("unroll") for (int m = 0; m < 4; ++m) _Pragma("unroll") for (int k = 0; k < 2; ++k) dst[m][k] = *(const PG8_LAS bf16x8*)(lds + PG8_SA(b, h) + aoff + m * 2048 + k * 1024); } while (0)
; #define PG8_MMA(ai, bj, At, Bt) do { __builtin_amdgcn_s_setprio(1); _Pragma("unroll") for (int m = 0; m < 4; ++m) _Pragma("unroll") for (int n = 0; n < 2; ++n) _Pragma("unroll") for (int k = 0; k < 2; ++k) \
;         acc[ai][bj][m][n] = __builtin_amdgcn_mfma_f32_16x16x32_bf16(Bt[n][k], At[m][k], acc[ai][bj][m][n], 0, 0, 0); __builtin_amdgcn_s_setprio(0); } while (0)
; #define PG8_WAIT_V(n) asm volatile("s_waitcnt vmcnt(" #n ")" ::: "memory")
; #define PG8_WAIT_L(n) asm volatile("s_waitcnt lgkmcnt(" #n ")" ::: "memory")
; #define PG8_BAR __builtin_amdgcn_s_barrier()
; #define PG8_SCHED __builtin_amdgcn_sched_barrier(0)
; template <class Epi, class Sched, bool ALIGN_EPI = false, bool SP2 = false>
; __device__ __forceinline__ void gemm_phase(PG8_LAS unsigned char* lds, const Gemm g, const Sched& S, const Epi& E) {
;     ...
;         for (int t = 0; t < nt; t += 2) {
;     ...
;             PG8_LDA(At, 1, 1); PG8_STAGE(PG8_SB(1, 0), b3, voffB); PG8_STAGE(PG8_SB(1, 1), b3 + hstep, voffB); PG8_STAGE(PG8_SA(1, 0), a3, voffA);
;             PG8_WAIT_V(8); PG8_WAIT_L(0); PG8_BAR; PG8_MMA(1, 0, At, B0); PG8_MMA(1, 1, At, B1); PG8_BAR; PG8_SCHED;
	s_add_i32 s34, s60, s33
	v_lshl_add_u64 v[160:161], v[160:161], 0, s[16:17]
	s_mov_b32 m0, s34
	ds_read_b128 v[198:201], v172 offset:49152
	ds_read_b128 v[202:205], v172 offset:50176
	ds_read_b128 v[206:209], v172 offset:51200
	ds_read_b128 v[210:213], v172 offset:52224
	ds_read_b128 v[214:217], v172 offset:53248
	ds_read_b128 v[218:221], v172 offset:54272
	ds_read_b128 v[222:225], v172 offset:55296
	ds_read_b128 v[226:229], v172 offset:56320
	global_load_lds_dwordx4 v[160:161], off
	s_add_i32 m0, s34, 0x2000
	s_add_u32 s30, s30, 0x40080
	v_lshl_add_u64 v[160:161], v[230:231], 0, s[16:17]
	s_addc_u32 s31, s31, 0
	s_add_i32 s34, s61, s33
	global_load_lds_dwordx4 v[160:161], off
	v_lshl_add_u64 v[160:161], s[30:31], 0, v[138:139]
	s_mov_b32 m0, s34
	s_nop 0
	global_load_lds_dwordx4 v[160:161], off
	v_lshl_add_u64 v[160:161], s[30:31], 0, v[142:143]
	s_add_i32 m0, s34, 0x2000
	s_nop 0
	global_load_lds_dwordx4 v[160:161], off
	v_lshl_add_u64 v[160:161], v[232:233], 0, s[16:17]
	s_mov_b32 m0, s42
	s_nop 0
	global_load_lds_dwordx4 v[160:161], off
	v_lshl_add_u64 v[160:161], v[234:235], 0, s[16:17]
	s_mov_b32 m0, s43
	s_nop 0
	global_load_lds_dwordx4 v[160:161], off
	s_waitcnt vmcnt(8)
	s_waitcnt lgkmcnt(0)
	s_barrier
	s_setprio 1
	s_waitcnt lgkmcnt(0)
	v_mfma_f32_16x16x32_bf16 v[92:95], v[128:131], v[198:201], v[92:95]
	v_mfma_f32_16x16x32_bf16 v[88:91], v[174:177], v[198:201], v[88:91]
	v_mfma_f32_16x16x32_bf16 v[84:87], v[128:131], v[206:209], v[84:87]
	v_mfma_f32_16x16x32_bf16 v[80:83], v[174:177], v[206:209], v[80:83]
	v_mfma_f32_16x16x32_bf16 v[76:79], v[128:131], v[214:217], v[76:79]
	v_mfma_f32_16x16x32_bf16 v[72:75], v[174:177], v[214:217], v[72:75]
	v_mfma_f32_16x16x32_bf16 v[68:71], v[128:131], v[222:225], v[68:71]
	v_mfma_f32_16x16x32_bf16 v[64:67], v[174:177], v[222:225], v[64:67]
	v_mfma_f32_16x16x32_bf16 v[92:95], v[132:135], v[202:205], v[92:95]
	v_mfma_f32_16x16x32_bf16 v[88:91], v[178:181], v[202:205], v[88:91]
	v_mfma_f32_16x16x32_bf16 v[84:87], v[132:135], v[210:213], v[84:87]
	v_mfma_f32_16x16x32_bf16 v[80:83], v[178:181], v[210:213], v[80:83]
	v_mfma_f32_16x16x32_bf16 v[76:79], v[132:135], v[218:221], v[76:79]
	v_mfma_f32_16x16x32_bf16 v[72:75], v[178:181], v[218:221], v[72:75]
	v_mfma_f32_16x16x32_bf16 v[68:71], v[132:135], v[226:229], v[68:71]
	v_mfma_f32_16x16x32_bf16 v[64:67], v[178:181], v[226:229], v[64:67]
	s_setprio 0
	s_setprio 1
	v_mfma_f32_16x16x32_bf16 v[28:31], v[182:185], v[198:201], v[28:31]
	v_mfma_f32_16x16x32_bf16 v[24:27], v[190:193], v[198:201], v[24:27]
	v_mfma_f32_16x16x32_bf16 v[20:23], v[182:185], v[206:209], v[20:23]
	v_mfma_f32_16x16x32_bf16 v[16:19], v[190:193], v[206:209], v[16:19]
	v_mfma_f32_16x16x32_bf16 v[12:15], v[182:185], v[214:217], v[12:15]
	v_mfma_f32_16x16x32_bf16 v[8:11], v[190:193], v[214:217], v[8:11]
	v_mfma_f32_16x16x32_bf16 v[4:7], v[182:185], v[222:225], v[4:7]
	v_mfma_f32_16x16x32_bf16 v[0:3], v[190:193], v[222:225], v[0:3]
	v_mfma_f32_16x16x32_bf16 v[28:31], v[186:189], v[202:205], v[28:31]
	v_mfma_f32_16x16x32_bf16 v[24:27], v[194:197], v[202:205], v[24:27]
	v_mfma_f32_16x16x32_bf16 v[20:23], v[186:189], v[210:213], v[20:23]
	v_mfma_f32_16x16x32_bf16 v[16:19], v[194:197], v[210:213], v[16:19]
	v_mfma_f32_16x16x32_bf16 v[12:15], v[186:189], v[218:221], v[12:15]
	v_mfma_f32_16x16x32_bf16 v[8:11], v[194:197], v[218:221], v[8:11]
	v_mfma_f32_16x16x32_bf16 v[4:7], v[186:189], v[226:229], v[4:7]
	v_mfma_f32_16x16x32_bf16 v[0:3], v[194:197], v[226:229], v[0:3]
	s_setprio 0
	s_barrier
	s_add_i32 s59, s59, 2
	s_add_u32 s28, s28, 0x100
	s_addc_u32 s29, s29, 0
	s_add_u32 s57, s57, 0x100
	s_addc_u32 s58, s58, 0
	s_cmp_gt_u32 s59, 13

; #define PG8_STAGE(bufoff, gbase, voff) do { _Pragma("unroll") for (int _i = 0; _i < 2; ++_i) \
;         __builtin_amdgcn_global_load_lds((const unsigned*)((const char*)(gbase) + (voff)[_i]), (PG8_LAS unsigned*)(lds + (bufoff) + ldsw + _i * 8192), 16, 0, 0); } while (0)
; #define PG8_LDA(dst, b, h) do { _Pragma("unroll") for (int m = 0; m < 4; ++m) _Pragma("unroll") for (int k = 0; k < 2; ++k) dst[m][k] = *(const PG8_LAS bf16x8*)(lds + PG8_SA(b, h) + aoff + m * 2048 + k * 1024); } while (0)
; #define PG8_LDB(dst, b, h) do { _Pragma("unroll") for (int n = 0; n < 2; ++n) _Pragma("unroll") for (int k = 0; k < 2; ++k) dst[n][k] = *(const PG8_LAS bf16x8*)(lds + PG8_SB(b, h) + boff + n * 2048 + k * 1024); } while (0)
; #define PG8_WAIT_V(n) asm volatile("s_waitcnt vmcnt(" #n ")" ::: "memory")
; #define PG8_WAIT_L(n) asm volatile("s_waitcnt lgkmcnt(" #n ")" ::: "memory")
; #define PG8_BAR __builtin_amdgcn_s_barrier()
; #define PG8_SCHED __builtin_amdgcn_sched_barrier(0)
; template <class Epi, class Sched, bool ALIGN_EPI = false, bool SP2 = false>
; __device__ __forceinline__ void gemm_phase(PG8_LAS unsigned char* lds, const Gemm g, const Sched& S, const Epi& E) {
;     ...
;         const bool has_next = S.next(ui + 1, nxt);
;         const char* nA = has_next ? (const char*)g.A + (size_t)nxt.pm * tstep : cA; const char* nB = has_next ? (const char*)g.Bt + (size_t)nxt.pn * tstep : cB;
;         for (int t = 0; t < nt; t += 2) {
;             const bool last = (t == nt - 2);
;             const char* a1 = cA + (size_t)(t + 1) * kstep;
;             const char* a2 = last ? nA : cA + (size_t)(t + 2) * kstep; const char* b2 = last ? nB : cB + (size_t)(t + 2) * kstep;
;             const char* a3 = a2 + kstep; const char* b3 = b2 + kstep;
;             if (last && has_next) S.a_ready(nxt, ui + 1);
;             if constexpr (SP2) {
;             PG8_LDB(B0, 0, 0); PG8_LDB(B1, 0, 1); PG8_SCHED; PG8_LDA(At, 0, 0); PG8_STAGE(PG8_SA(1, 1), a1 + hstep, voffA);
;             PG8_WAIT_V(8); PG8_WAIT_L(0); PG8_BAR; PG8_MMA(0, 0, At, B0); PG8_MMA(0, 1, At, B1); PG8_BAR; PG8_SCHED;
;             PG8_LDA(At, 0, 1); PG8_STAGE(PG8_SB(0, 0), b2, voffB); PG8_STAGE(PG8_SB(0, 1), b2 + hstep, voffB); PG8_STAGE(PG8_SA(0, 0), a2, voffA);
;             PG8_WAIT_V(8); PG8_WAIT_L(0); PG8_BAR; PG8_MMA(1, 0, At, B0); PG8_MMA(1, 1, At, B1); PG8_BAR; PG8_SCHED;
.LBB0_959:
	s_ashr_i32 s23, s22, 31
	s_lshl_b64 s[24:25], s[22:23], 19
	s_add_u32 s24, s3, s24
	s_addc_u32 s25, s33, s25
	s_and_b64 s[26:27], s[4:5], exec
	s_cselect_b32 s23, s25, s31
	s_cselect_b32 s29, s24, s30
	s_ashr_i32 s21, s20, 31
	s_lshl_b64 s[26:27], s[20:21], 19
	s_add_u32 s26, s38, s26
	s_addc_u32 s27, s39, s27
	s_and_b64 s[36:37], s[4:5], exec
	s_cselect_b32 s21, s27, s35
	s_cselect_b32 s54, s26, s34
	s_add_u32 s30, s30, 0x40080
	s_addc_u32 s31, s31, 0
	s_add_u32 s55, s34, 0x100
	s_addc_u32 s56, s35, 0
	s_mov_b32 s57, -2
	ds_read_b128 v[120:123], v245
	ds_read_b128 v[128:131], v245 offset:1024
	ds_read_b128 v[136:139], v245 offset:2048
	ds_read_b128 v[140:143], v245 offset:3072
	ds_read_b128 v[144:147], v246
	ds_read_b128 v[148:151], v246 offset:1024
	ds_read_b128 v[152:155], v246 offset:2048
	ds_read_b128 v[156:159], v246 offset:3072
	s_add_u32 s34, s30, 0xfffc0080
	s_addc_u32 s35, s31, -1
	s_cmp_eq_u32 s57, 12
	s_cselect_b32 s37, s23, s35
	s_cselect_b32 s36, s29, s34
	s_cselect_b32 s35, s21, s56
	s_cselect_b32 s34, s54, s55
	v_lshl_add_u64 v[204:205], s[30:31], 0, v[200:201]
	s_add_i32 m0, s41, 0xc000
	ds_read_b128 v[160:163], v247
	ds_read_b128 v[164:167], v247 offset:1024
	ds_read_b128 v[168:171], v247 offset:2048
	ds_read_b128 v[172:175], v247 offset:3072
	ds_read_b128 v[176:179], v247 offset:4096
	ds_read_b128 v[180:183], v247 offset:5120
	ds_read_b128 v[184:187], v247 offset:6144
	ds_read_b128 v[188:191], v247 offset:7168
	global_load_lds_dwordx4 v[204:205], off
	v_lshl_add_u64 v[204:205], s[30:31], 0, v[202:203]
	s_add_i32 m0, s41, 0xe000
	s_nop 0
	global_load_lds_dwordx4 v[204:205], off
	s_waitcnt vmcnt(8)
	s_waitcnt lgkmcnt(0)
	s_barrier
	s_setprio 1
	s_waitcnt lgkmcnt(0)
	v_mfma_f32_16x16x32_bf16 v[132:135], v[120:123], v[160:163], 0
	v_mfma_f32_16x16x32_bf16 v[124:127], v[136:139], v[160:163], 0
	v_mfma_f32_16x16x32_bf16 v[108:111], v[120:123], v[168:171], 0
	v_mfma_f32_16x16x32_bf16 v[104:107], v[136:139], v[168:171], 0
	v_mfma_f32_16x16x32_bf16 v[92:95], v[120:123], v[176:179], 0
	v_mfma_f32_16x16x32_bf16 v[88:91], v[136:139], v[176:179], 0
	v_mfma_f32_16x16x32_bf16 v[76:79], v[120:123], v[184:187], 0
	v_mfma_f32_16x16x32_bf16 v[72:75], v[136:139], v[184:187], 0
	v_mfma_f32_16x16x32_bf16 v[132:135], v[128:131], v[164:167], v[132:135]
	v_mfma_f32_16x16x32_bf16 v[124:127], v[140:143], v[164:167], v[124:127]
	v_mfma_f32_16x16x32_bf16 v[108:111], v[128:131], v[172:175], v[108:111]
	v_mfma_f32_16x16x32_bf16 v[104:107], v[140:143], v[172:175], v[104:107]
	v_mfma_f32_16x16x32_bf16 v[92:95], v[128:131], v[180:183], v[92:95]
	v_mfma_f32_16x16x32_bf16 v[88:91], v[140:143], v[180:183], v[88:91]
	v_mfma_f32_16x16x32_bf16 v[76:79], v[128:131], v[188:191], v[76:79]
	v_mfma_f32_16x16x32_bf16 v[72:75], v[140:143], v[188:191], v[72:75]
	s_setprio 0
	s_setprio 1
	v_mfma_f32_16x16x32_bf16 v[116:119], v[144:147], v[160:163], 0
	v_mfma_f32_16x16x32_bf16 v[112:115], v[152:155], v[160:163], 0
	v_mfma_f32_16x16x32_bf16 v[100:103], v[144:147], v[168:171], 0
	v_mfma_f32_16x16x32_bf16 v[96:99], v[152:155], v[168:171], 0
	v_mfma_f32_16x16x32_bf16 v[84:87], v[144:147], v[176:179], 0
	v_mfma_f32_16x16x32_bf16 v[80:83], v[152:155], v[176:179], 0
	v_mfma_f32_16x16x32_bf16 v[68:71], v[144:147], v[184:187], 0
	v_mfma_f32_16x16x32_bf16 v[64:67], v[152:155], v[184:187], 0
	v_mfma_f32_16x16x32_bf16 v[116:119], v[148:151], v[164:167], v[116:119]
	v_mfma_f32_16x16x32_bf16 v[112:115], v[156:159], v[164:167], v[112:115]
	v_mfma_f32_16x16x32_bf16 v[100:103], v[148:151], v[172:175], v[100:103]
	v_mfma_f32_16x16x32_bf16 v[96:99], v[156:159], v[172:175], v[96:99]
	v_mfma_f32_16x16x32_bf16 v[84:87], v[148:151], v[180:183], v[84:87]
	v_mfma_f32_16x16x32_bf16 v[80:83], v[156:159], v[180:183], v[80:83]
	v_mfma_f32_16x16x32_bf16 v[68:71], v[148:151], v[188:191], v[68:71]
	v_mfma_f32_16x16x32_bf16 v[64:67], v[156:159], v[188:191], v[64:67]
	s_setprio 0
	s_barrier
	s_add_i32 s58, s51, s40
	v_lshl_add_u64 v[204:205], s[34:35], 0, v[194:195]
	s_mov_b32 m0, s58
	ds_read_b128 v[160:163], v247 offset:16384
	ds_read_b128 v[164:167], v247 offset:17408
	ds_read_b128 v[168:171], v247 offset:18432
	ds_read_b128 v[172:175], v247 offset:19456
	ds_read_b128 v[176:179], v247 offset:20480
	ds_read_b128 v[180:183], v247 offset:21504
	ds_read_b128 v[184:187], v247 offset:22528
	ds_read_b128 v[188:191], v247 offset:23552
	global_load_lds_dwordx4 v[204:205], off
	s_add_i32 m0, s58, 0x2000
	s_add_u32 s58, s34, 0x40000
	v_lshl_add_u64 v[206:207], s[34:35], 0, v[198:199]
	s_addc_u32 s59, s35, 0
	s_add_i32 s60, s52, s40
	global_load_lds_dwordx4 v[206:207], off
	v_lshl_add_u64 v[208:209], s[58:59], 0, v[194:195]
	s_mov_b32 m0, s60
	v_lshl_add_u64 v[210:211], s[36:37], 0, v[196:197]
	global_load_lds_dwordx4 v[208:209], off
	v_lshl_add_u64 v[208:209], s[58:59], 0, v[198:199]
	s_add_i32 m0, s60, 0x2000
	s_nop 0
	global_load_lds_dwordx4 v[208:209], off
	v_lshl_add_u64 v[208:209], s[36:37], 0, v[192:193]
	s_mov_b32 m0, s41
	s_nop 0
	global_load_lds_dwordx4 v[208:209], off
	s_mov_b32 m0, s42
	s_nop 0
	global_load_lds_dwordx4 v[210:211], off
	s_waitcnt vmcnt(8)
	s_waitcnt lgkmcnt(0)
	s_barrier
; #define PG8_STAGE(bufoff, gbase, voff) do { _Pragma("unroll") for (int _i = 0; _i < 2; ++_i) \
;         __builtin_amdgcn_global_load_lds((const unsigned*)((const char*)(gbase) + (voff)[_i]), (PG8_LAS unsigned*)(lds + (bufoff) + ldsw + _i * 8192), 16, 0, 0); } while (0)
; #define PG8_LDA(dst, b, h) do { _Pragma("unroll") for (int m = 0; m < 4; ++m) _Pragma("unroll") for (int k = 0; k < 2; ++k) dst[m][k] = *(const PG8_LAS bf16x8*)(lds + PG8_SA(b, h) + aoff + m * 2048 + k * 1024); } while (0)
; #define PG8_LDB(dst, b, h) do { _Pragma("unroll") for (int n = 0; n < 2; ++n) _Pragma("unroll") for (int k = 0; k < 2; ++k) dst[n][k] = *(const PG8_LAS bf16x8*)(lds + PG8_SB(b, h) + boff + n * 2048 + k * 1024); } while (0)
; #define PG8_MMA(ai, bj, At, Bt) do { __builtin_amdgcn_s_setprio(1); _Pragma("unroll") for (int m = 0; m < 4; ++m) _Pragma("unroll") for (int n = 0; n < 2; ++n) _Pragma("unroll") for (int k = 0; k < 2; ++k) \
;         acc[ai][bj][m][n] = __builtin_amdgcn_mfma_f32_16x16x32_bf16(Bt[n][k], At[m][k], acc[ai][bj][m][n], 0, 0, 0); __builtin_amdgcn_s_setprio(0); } while (0)
; #define PG8_WAIT_V(n) asm volatile("s_waitcnt vmcnt(" #n ")" ::: "memory")
; #define PG8_WAIT_L(n) asm volatile("s_waitcnt lgkmcnt(" #n ")" ::: "memory")
; #define PG8_BAR __builtin_amdgcn_s_barrier()
; #define PG8_SCHED __builtin_amdgcn_sched_barrier(0)
; template <class Epi, class Sched, bool ALIGN_EPI = false, bool SP2 = false>
; __device__ __forceinline__ void gemm_phase(PG8_LAS unsigned char* lds, const Gemm g, const Sched& S, const Epi& E) {
;     ...
;             PG8_WAIT_V(8); PG8_WAIT_L(0); PG8_BAR; PG8_MMA(1, 0, At, B0); PG8_MMA(1, 1, At, B1); PG8_BAR; PG8_SCHED;
;             PG8_LDB(B0, 1, 0); PG8_LDB(B1, 1, 1); PG8_SCHED; PG8_LDA(At, 1, 0); PG8_STAGE(PG8_SA(0, 1), a2 + hstep, voffA);
;             PG8_WAIT_V(8); PG8_WAIT_L(0); PG8_BAR; PG8_MMA(0, 0, At, B0); PG8_MMA(0, 1, At, B1); PG8_BAR; PG8_SCHED;
	s_setprio 1
	s_waitcnt lgkmcnt(0)
	v_mfma_f32_16x16x32_bf16 v[60:63], v[120:123], v[160:163], 0
	v_mfma_f32_16x16x32_bf16 v[56:59], v[136:139], v[160:163], 0
	v_mfma_f32_16x16x32_bf16 v[44:47], v[120:123], v[168:171], 0
	v_mfma_f32_16x16x32_bf16 v[40:43], v[136:139], v[168:171], 0
	v_mfma_f32_16x16x32_bf16 v[28:31], v[120:123], v[176:179], 0
	v_mfma_f32_16x16x32_bf16 v[24:27], v[136:139], v[176:179], 0
	v_mfma_f32_16x16x32_bf16 v[12:15], v[120:123], v[184:187], 0
	v_mfma_f32_16x16x32_bf16 v[8:11], v[136:139], v[184:187], 0
	v_mfma_f32_16x16x32_bf16 v[60:63], v[128:131], v[164:167], v[60:63]
	v_mfma_f32_16x16x32_bf16 v[56:59], v[140:143], v[164:167], v[56:59]
	v_mfma_f32_16x16x32_bf16 v[44:47], v[128:131], v[172:175], v[44:47]
	v_mfma_f32_16x16x32_bf16 v[40:43], v[140:143], v[172:175], v[40:43]
	v_mfma_f32_16x16x32_bf16 v[28:31], v[128:131], v[180:183], v[28:31]
	v_mfma_f32_16x16x32_bf16 v[24:27], v[140:143], v[180:183], v[24:27]
	v_mfma_f32_16x16x32_bf16 v[12:15], v[128:131], v[188:191], v[12:15]
	v_mfma_f32_16x16x32_bf16 v[8:11], v[140:143], v[188:191], v[8:11]
	s_setprio 0
	s_setprio 1
	v_mfma_f32_16x16x32_bf16 v[52:55], v[144:147], v[160:163], 0
	v_mfma_f32_16x16x32_bf16 v[48:51], v[152:155], v[160:163], 0
	v_mfma_f32_16x16x32_bf16 v[36:39], v[144:147], v[168:171], 0
	v_mfma_f32_16x16x32_bf16 v[32:35], v[152:155], v[168:171], 0
	v_mfma_f32_16x16x32_bf16 v[20:23], v[144:147], v[176:179], 0
	v_mfma_f32_16x16x32_bf16 v[16:19], v[152:155], v[176:179], 0
	v_mfma_f32_16x16x32_bf16 v[4:7], v[144:147], v[184:187], 0
	v_mfma_f32_16x16x32_bf16 v[0:3], v[152:155], v[184:187], 0
	v_mfma_f32_16x16x32_bf16 v[52:55], v[148:151], v[164:167], v[52:55]
	v_mfma_f32_16x16x32_bf16 v[48:51], v[156:159], v[164:167], v[48:51]
	v_mfma_f32_16x16x32_bf16 v[36:39], v[148:151], v[172:175], v[36:39]
	v_mfma_f32_16x16x32_bf16 v[32:35], v[156:159], v[172:175], v[32:35]
	v_mfma_f32_16x16x32_bf16 v[20:23], v[148:151], v[180:183], v[20:23]
	v_mfma_f32_16x16x32_bf16 v[16:19], v[156:159], v[180:183], v[16:19]
	v_mfma_f32_16x16x32_bf16 v[4:7], v[148:151], v[188:191], v[4:7]
	v_mfma_f32_16x16x32_bf16 v[0:3], v[156:159], v[188:191], v[0:3]
	s_setprio 0
	s_barrier
	s_add_i32 s58, 0, 0x18000
	s_add_i32 s59, 0, 0x1c000
	v_add_u32_e32 v140, s58, v243
	v_add_u32_e32 v156, s59, v243
	ds_read_b128 v[120:123], v140
	ds_read_b128 v[128:131], v140 offset:1024
	ds_read_b128 v[136:139], v140 offset:2048
	ds_read_b128 v[140:143], v140 offset:3072
	ds_read_b128 v[144:147], v156
	ds_read_b128 v[148:151], v156 offset:1024
	ds_read_b128 v[152:155], v156 offset:2048
	ds_read_b128 v[156:159], v156 offset:3072
	s_add_u32 s36, s36, 0x40000
	s_addc_u32 s37, s37, 0
	s_mov_b32 m0, s43
	v_lshl_add_u64 v[212:213], s[36:37], 0, v[192:193]
	ds_read_b128 v[160:163], v247 offset:32768
	ds_read_b128 v[164:167], v247 offset:33792
	ds_read_b128 v[168:171], v247 offset:34816
	ds_read_b128 v[172:175], v247 offset:35840
	ds_read_b128 v[176:179], v247 offset:36864
	ds_read_b128 v[180:183], v247 offset:37888
	ds_read_b128 v[184:187], v247 offset:38912
	ds_read_b128 v[188:191], v247 offset:39936
	global_load_lds_dwordx4 v[212:213], off
	v_lshl_add_u64 v[212:213], s[36:37], 0, v[196:197]
	s_mov_b32 m0, s44
	s_nop 0
	global_load_lds_dwordx4 v[212:213], off
	s_waitcnt vmcnt(8)
	s_waitcnt lgkmcnt(0)
	s_barrier
	s_setprio 1
	s_waitcnt lgkmcnt(0)
	v_mfma_f32_16x16x32_bf16 v[132:135], v[120:123], v[160:163], v[132:135]
	v_mfma_f32_16x16x32_bf16 v[124:127], v[136:139], v[160:163], v[124:127]
	v_mfma_f32_16x16x32_bf16 v[108:111], v[120:123], v[168:171], v[108:111]
	v_mfma_f32_16x16x32_bf16 v[104:107], v[136:139], v[168:171], v[104:107]
	v_mfma_f32_16x16x32_bf16 v[92:95], v[120:123], v[176:179], v[92:95]
	v_mfma_f32_16x16x32_bf16 v[88:91], v[136:139], v[176:179], v[88:91]
	v_mfma_f32_16x16x32_bf16 v[76:79], v[120:123], v[184:187], v[76:79]
	v_mfma_f32_16x16x32_bf16 v[72:75], v[136:139], v[184:187], v[72:75]
	v_mfma_f32_16x16x32_bf16 v[132:135], v[128:131], v[164:167], v[132:135]
	v_mfma_f32_16x16x32_bf16 v[124:127], v[140:143], v[164:167], v[124:127]
	v_mfma_f32_16x16x32_bf16 v[108:111], v[128:131], v[172:175], v[108:111]
	v_mfma_f32_16x16x32_bf16 v[104:107], v[140:143], v[172:175], v[104:107]
	v_mfma_f32_16x16x32_bf16 v[92:95], v[128:131], v[180:183], v[92:95]
	v_mfma_f32_16x16x32_bf16 v[88:91], v[140:143], v[180:183], v[88:91]
	v_mfma_f32_16x16x32_bf16 v[76:79], v[128:131], v[188:191], v[76:79]
	v_mfma_f32_16x16x32_bf16 v[72:75], v[140:143], v[188:191], v[72:75]
	s_setprio 0
	s_setprio 1
	v_mfma_f32_16x16x32_bf16 v[116:119], v[144:147], v[160:163], v[116:119]
	v_mfma_f32_16x16x32_bf16 v[112:115], v[152:155], v[160:163], v[112:115]
	v_mfma_f32_16x16x32_bf16 v[100:103], v[144:147], v[168:171], v[100:103]
	v_mfma_f32_16x16x32_bf16 v[96:99], v[152:155], v[168:171], v[96:99]
	v_mfma_f32_16x16x32_bf16 v[84:87], v[144:147], v[176:179], v[84:87]
	v_mfma_f32_16x16x32_bf16 v[80:83], v[152:155], v[176:179], v[80:83]
	v_mfma_f32_16x16x32_bf16 v[68:71], v[144:147], v[184:187], v[68:71]
	v_mfma_f32_16x16x32_bf16 v[64:67], v[152:155], v[184:187], v[64:67]
	v_mfma_f32_16x16x32_bf16 v[116:119], v[148:151], v[164:167], v[116:119]
	v_mfma_f32_16x16x32_bf16 v[112:115], v[156:159], v[164:167], v[112:115]
	v_mfma_f32_16x16x32_bf16 v[100:103], v[148:151], v[172:175], v[100:103]
	v_mfma_f32_16x16x32_bf16 v[96:99], v[156:159], v[172:175], v[96:99]
	v_mfma_f32_16x16x32_bf16 v[84:87], v[148:151], v[180:183], v[84:87]
	v_mfma_f32_16x16x32_bf16 v[80:83], v[156:159], v[180:183], v[80:83]
	v_mfma_f32_16x16x32_bf16 v[68:71], v[148:151], v[188:191], v[68:71]
	v_mfma_f32_16x16x32_bf16 v[64:67], v[156:159], v[188:191], v[64:67]
	s_setprio 0
	s_barrier
; #define PG8_STAGE(bufoff, gbase, voff) do { _Pragma("unroll") for (int _i = 0; _i < 2; ++_i) \
;         __builtin_amdgcn_global_load_lds((const unsigned*)((const char*)(gbase) + (voff)[_i]), (PG8_LAS unsigned*)(lds + (bufoff) + ldsw + _i * 8192), 16, 0, 0); } while (0)
; #define PG8_LDA(dst, b, h) do { _Pragma("unroll") for (int m = 0; m < 4; ++m) _Pragma("unroll") for (int k = 0; k < 2; ++k) dst[m][k] = *(const PG8_LAS bf16x8*)(lds + PG8_SA(b, h) + aoff + m * 2048 + k * 1024); } while (0)
; #define PG8_MMA(ai, bj, At, Bt) do { __builtin_amdgcn_s_setprio(1); _Pragma("unroll") for (int m = 0; m < 4; ++m) _Pragma("unroll") for (int n = 0; n < 2; ++n) _Pragma("unroll") for (int k = 0; k < 2; ++k) \
;         acc[ai][bj][m][n] = __builtin_amdgcn_mfma_f32_16x16x32_bf16(Bt[n][k], At[m][k], acc[ai][bj][m][n], 0, 0, 0); __builtin_amdgcn_s_setprio(0); } while (0)
; #define PG8_WAIT_V(n) asm volatile("s_waitcnt vmcnt(" #n ")" ::: "memory")
; #define PG8_WAIT_L(n) asm volatile("s_waitcnt lgkmcnt(" #n ")" ::: "memory")
; #define PG8_BAR __builtin_amdgcn_s_barrier()
; #define PG8_SCHED __builtin_amdgcn_sched_barrier(0)
; template <class Epi, class Sched, bool ALIGN_EPI = false, bool SP2 = false>
; __device__ __forceinline__ void gemm_phase(PG8_LAS unsigned char* lds, const Gemm g, const Sched& S, const Epi& E) {
;     ...
;         for (int t = 0; t < nt; t += 2) {
;     ...
;             PG8_LDA(At, 1, 1); PG8_STAGE(PG8_SB(1, 0), b3, voffB); PG8_STAGE(PG8_SB(1, 1), b3 + hstep, voffB); PG8_STAGE(PG8_SA(1, 0), a3, voffA);
;             PG8_WAIT_V(8); PG8_WAIT_L(0); PG8_BAR; PG8_MMA(1, 0, At, B0); PG8_MMA(1, 1, At, B1); PG8_BAR; PG8_SCHED;
	s_add_i32 s36, s58, s40
	v_lshl_add_u64 v[204:205], v[204:205], 0, s[16:17]
	s_mov_b32 m0, s36
	ds_read_b128 v[160:163], v247 offset:49152
	ds_read_b128 v[164:167], v247 offset:50176
	ds_read_b128 v[168:171], v247 offset:51200
	ds_read_b128 v[172:175], v247 offset:52224
	ds_read_b128 v[176:179], v247 offset:53248
	ds_read_b128 v[180:183], v247 offset:54272
	ds_read_b128 v[184:187], v247 offset:55296
	ds_read_b128 v[188:191], v247 offset:56320
	global_load_lds_dwordx4 v[204:205], off
	s_add_i32 m0, s36, 0x2000
	s_add_u32 s34, s34, 0x40080
	v_lshl_add_u64 v[204:205], v[206:207], 0, s[16:17]
	s_addc_u32 s35, s35, 0
	s_add_i32 s36, s59, s40
	global_load_lds_dwordx4 v[204:205], off
	v_lshl_add_u64 v[204:205], s[34:35], 0, v[194:195]
	s_mov_b32 m0, s36
	s_nop 0
	global_load_lds_dwordx4 v[204:205], off
	v_lshl_add_u64 v[204:205], s[34:35], 0, v[198:199]
	s_add_i32 m0, s36, 0x2000
	s_nop 0
	global_load_lds_dwordx4 v[204:205], off
	v_lshl_add_u64 v[204:205], v[208:209], 0, s[16:17]
	s_mov_b32 m0, s46
	s_nop 0
	global_load_lds_dwordx4 v[204:205], off
	v_lshl_add_u64 v[204:205], v[210:211], 0, s[16:17]
	s_mov_b32 m0, s47
	s_nop 0
	global_load_lds_dwordx4 v[204:205], off
	s_waitcnt vmcnt(8)
	s_waitcnt lgkmcnt(0)
	s_barrier
	s_setprio 1
	s_waitcnt lgkmcnt(0)
	v_mfma_f32_16x16x32_bf16 v[60:63], v[120:123], v[160:163], v[60:63]
	v_mfma_f32_16x16x32_bf16 v[56:59], v[136:139], v[160:163], v[56:59]
	v_mfma_f32_16x16x32_bf16 v[44:47], v[120:123], v[168:171], v[44:47]
	v_mfma_f32_16x16x32_bf16 v[40:43], v[136:139], v[168:171], v[40:43]
	v_mfma_f32_16x16x32_bf16 v[28:31], v[120:123], v[176:179], v[28:31]
	v_mfma_f32_16x16x32_bf16 v[24:27], v[136:139], v[176:179], v[24:27]
	v_mfma_f32_16x16x32_bf16 v[12:15], v[120:123], v[184:187], v[12:15]
	v_mfma_f32_16x16x32_bf16 v[8:11], v[136:139], v[184:187], v[8:11]
	v_mfma_f32_16x16x32_bf16 v[60:63], v[128:131], v[164:167], v[60:63]
	v_mfma_f32_16x16x32_bf16 v[56:59], v[140:143], v[164:167], v[56:59]
	v_mfma_f32_16x16x32_bf16 v[44:47], v[128:131], v[172:175], v[44:47]
	v_mfma_f32_16x16x32_bf16 v[40:43], v[140:143], v[172:175], v[40:43]
	v_mfma_f32_16x16x32_bf16 v[28:31], v[128:131], v[180:183], v[28:31]
	v_mfma_f32_16x16x32_bf16 v[24:27], v[140:143], v[180:183], v[24:27]
	v_mfma_f32_16x16x32_bf16 v[12:15], v[128:131], v[188:191], v[12:15]
	v_mfma_f32_16x16x32_bf16 v[8:11], v[140:143], v[188:191], v[8:11]
	s_setprio 0
	s_setprio 1
	v_mfma_f32_16x16x32_bf16 v[52:55], v[144:147], v[160:163], v[52:55]
	v_mfma_f32_16x16x32_bf16 v[48:51], v[152:155], v[160:163], v[48:51]
	v_mfma_f32_16x16x32_bf16 v[36:39], v[144:147], v[168:171], v[36:39]
	v_mfma_f32_16x16x32_bf16 v[32:35], v[152:155], v[168:171], v[32:35]
	v_mfma_f32_16x16x32_bf16 v[20:23], v[144:147], v[176:179], v[20:23]
	v_mfma_f32_16x16x32_bf16 v[16:19], v[152:155], v[176:179], v[16:19]
	v_mfma_f32_16x16x32_bf16 v[4:7], v[144:147], v[184:187], v[4:7]
	v_mfma_f32_16x16x32_bf16 v[0:3], v[152:155], v[184:187], v[0:3]
	v_mfma_f32_16x16x32_bf16 v[52:55], v[148:151], v[164:167], v[52:55]
	v_mfma_f32_16x16x32_bf16 v[48:51], v[156:159], v[164:167], v[48:51]
	v_mfma_f32_16x16x32_bf16 v[36:39], v[148:151], v[172:175], v[36:39]
	v_mfma_f32_16x16x32_bf16 v[32:35], v[156:159], v[172:175], v[32:35]
	v_mfma_f32_16x16x32_bf16 v[20:23], v[148:151], v[180:183], v[20:23]
	v_mfma_f32_16x16x32_bf16 v[16:19], v[156:159], v[180:183], v[16:19]
	v_mfma_f32_16x16x32_bf16 v[4:7], v[148:151], v[188:191], v[4:7]
	v_mfma_f32_16x16x32_bf16 v[0:3], v[156:159], v[188:191], v[0:3]
	s_setprio 0
	s_barrier
	s_add_i32 s57, s57, 2
	s_add_u32 s30, s30, 0x100
	s_addc_u32 s31, s31, 0
	s_add_u32 s55, s55, 0x100
	s_addc_u32 s56, s56, 0
	s_cmp_gt_u32 s57, 13

; #define PG8_STAGE(bufoff, gbase, voff) do { _Pragma("unroll") for (int _i = 0; _i < 2; ++_i) \
;         __builtin_amdgcn_global_load_lds((const unsigned*)((const char*)(gbase) + (voff)[_i]), (PG8_LAS unsigned*)(lds + (bufoff) + ldsw + _i * 8192), 16, 0, 0); } while (0)
; #define PG8_LDA(dst, b, h) do { _Pragma("unroll") for (int m = 0; m < 4; ++m) _Pragma("unroll") for (int k = 0; k < 2; ++k) dst[m][k] = *(const PG8_LAS bf16x8*)(lds + PG8_SA(b, h) + aoff + m * 2048 + k * 1024); } while (0)
; #define PG8_LDB(dst, b, h) do { _Pragma("unroll") for (int n = 0; n < 2; ++n) _Pragma("unroll") for (int k = 0; k < 2; ++k) dst[n][k] = *(const PG8_LAS bf16x8*)(lds + PG8_SB(b, h) + boff + n * 2048 + k * 1024); } while (0)
; #define PG8_WAIT_V(n) asm volatile("s_waitcnt vmcnt(" #n ")" ::: "memory")
; #define PG8_WAIT_L(n) asm volatile("s_waitcnt lgkmcnt(" #n ")" ::: "memory")
; #define PG8_BAR __builtin_amdgcn_s_barrier()
; #define PG8_SCHED __builtin_amdgcn_sched_barrier(0)
; template <class Epi, class Sched, bool ALIGN_EPI = false, bool SP2 = false>
; __device__ __forceinline__ void gemm_phase(PG8_LAS unsigned char* lds, const Gemm g, const Sched& S, const Epi& E) {
;     ...
;         const bool has_next = S.next(ui + 1, nxt);
;         const char* nA = has_next ? (const char*)g.A + (size_t)nxt.pm * tstep : cA; const char* nB = has_next ? (const char*)g.Bt + (size_t)nxt.pn * tstep : cB;
;         for (int t = 0; t < nt; t += 2) {
;             const bool last = (t == nt - 2);
;             const char* a1 = cA + (size_t)(t + 1) * kstep;
;             const char* a2 = last ? nA : cA + (size_t)(t + 2) * kstep; const char* b2 = last ? nB : cB + (size_t)(t + 2) * kstep;
;             const char* a3 = a2 + kstep; const char* b3 = b2 + kstep;
;             if (last && has_next) S.a_ready(nxt, ui + 1);
;             if constexpr (SP2) {
;             PG8_LDB(B0, 0, 0); PG8_LDB(B1, 0, 1); PG8_SCHED; PG8_LDA(At, 0, 0); PG8_STAGE(PG8_SA(1, 1), a1 + hstep, voffA);
;             PG8_WAIT_V(8); PG8_WAIT_L(0); PG8_BAR; PG8_MMA(0, 0, At, B0); PG8_MMA(0, 1, At, B1); PG8_BAR; PG8_SCHED;
;             PG8_LDA(At, 0, 1); PG8_STAGE(PG8_SB(0, 0), b2, voffB); PG8_STAGE(PG8_SB(0, 1), b2 + hstep, voffB); PG8_STAGE(PG8_SA(0, 0), a2, voffA);
;             PG8_WAIT_V(8); PG8_WAIT_L(0); PG8_BAR; PG8_MMA(1, 0, At, B0); PG8_MMA(1, 1, At, B1); PG8_BAR; PG8_SCHED;
.LBB0_1048:
	s_ashr_i32 s17, s16, 31
	s_lshl_b64 s[18:19], s[16:17], 19
	s_add_u32 s18, s34, s18
	s_addc_u32 s19, s35, s19
	s_and_b64 s[20:21], s[0:1], exec
	s_cselect_b32 s17, s19, s25
	s_cselect_b32 s50, s18, s24
	s_ashr_i32 s15, s14, 31
	s_lshl_b64 s[20:21], s[14:15], 19
	s_add_u32 s20, s36, s20
	s_addc_u32 s21, s37, s21
	s_and_b64 s[28:29], s[0:1], exec
	s_cselect_b32 s15, s21, s27
	s_cselect_b32 s51, s20, s26
	s_add_u32 s24, s24, 0x40080
	s_addc_u32 s25, s25, 0
	s_add_u32 s52, s26, 0x100
	s_addc_u32 s53, s27, 0
	s_mov_b32 s54, -2
	ds_read_b128 v[152:155], v148
	ds_read_b128 v[156:159], v148 offset:1024
	ds_read_b128 v[160:163], v148 offset:2048
	ds_read_b128 v[164:167], v148 offset:3072
	ds_read_b128 v[168:171], v149
	ds_read_b128 v[172:175], v149 offset:1024
	ds_read_b128 v[176:179], v149 offset:2048
	ds_read_b128 v[180:183], v149 offset:3072
	s_add_u32 s26, s24, 0xfffc0080
	s_addc_u32 s27, s25, -1
	s_cmp_eq_u32 s54, 12
	s_cselect_b32 s29, s17, s27
	s_cselect_b32 s28, s50, s26
	s_cselect_b32 s27, s15, s53
	s_cselect_b32 s26, s51, s52
	v_lshl_add_u64 v[216:217], s[24:25], 0, v[136:137]
	s_add_i32 m0, s23, 0xc000
	ds_read_b128 v[184:187], v150
	ds_read_b128 v[188:191], v150 offset:1024
	ds_read_b128 v[192:195], v150 offset:2048
	ds_read_b128 v[196:199], v150 offset:3072
	ds_read_b128 v[200:203], v150 offset:4096
	ds_read_b128 v[204:207], v150 offset:5120
	ds_read_b128 v[208:211], v150 offset:6144
	ds_read_b128 v[212:215], v150 offset:7168
	global_load_lds_dwordx4 v[216:217], off
	v_lshl_add_u64 v[216:217], s[24:25], 0, v[138:139]
	s_add_i32 m0, s23, 0xe000
	s_nop 0
	global_load_lds_dwordx4 v[216:217], off
	s_waitcnt vmcnt(8)
	s_waitcnt lgkmcnt(0)
	s_barrier
	s_setprio 1
	s_waitcnt lgkmcnt(0)
	v_mfma_f32_16x16x32_bf16 v[124:127], v[152:155], v[184:187], 0
	v_mfma_f32_16x16x32_bf16 v[120:123], v[160:163], v[184:187], 0
	v_mfma_f32_16x16x32_bf16 v[108:111], v[152:155], v[192:195], 0
	v_mfma_f32_16x16x32_bf16 v[104:107], v[160:163], v[192:195], 0
	v_mfma_f32_16x16x32_bf16 v[92:95], v[152:155], v[200:203], 0
	v_mfma_f32_16x16x32_bf16 v[88:91], v[160:163], v[200:203], 0
	v_mfma_f32_16x16x32_bf16 v[76:79], v[152:155], v[208:211], 0
	v_mfma_f32_16x16x32_bf16 v[72:75], v[160:163], v[208:211], 0
	v_mfma_f32_16x16x32_bf16 v[124:127], v[156:159], v[188:191], v[124:127]
	v_mfma_f32_16x16x32_bf16 v[120:123], v[164:167], v[188:191], v[120:123]
	v_mfma_f32_16x16x32_bf16 v[108:111], v[156:159], v[196:199], v[108:111]
	v_mfma_f32_16x16x32_bf16 v[104:107], v[164:167], v[196:199], v[104:107]
	v_mfma_f32_16x16x32_bf16 v[92:95], v[156:159], v[204:207], v[92:95]
	v_mfma_f32_16x16x32_bf16 v[88:91], v[164:167], v[204:207], v[88:91]
	v_mfma_f32_16x16x32_bf16 v[76:79], v[156:159], v[212:215], v[76:79]
	v_mfma_f32_16x16x32_bf16 v[72:75], v[164:167], v[212:215], v[72:75]
	s_setprio 0
	s_setprio 1
	v_mfma_f32_16x16x32_bf16 v[116:119], v[168:171], v[184:187], 0
	v_mfma_f32_16x16x32_bf16 v[112:115], v[176:179], v[184:187], 0
	v_mfma_f32_16x16x32_bf16 v[100:103], v[168:171], v[192:195], 0
	v_mfma_f32_16x16x32_bf16 v[96:99], v[176:179], v[192:195], 0
	v_mfma_f32_16x16x32_bf16 v[84:87], v[168:171], v[200:203], 0
	v_mfma_f32_16x16x32_bf16 v[80:83], v[176:179], v[200:203], 0
	v_mfma_f32_16x16x32_bf16 v[68:71], v[168:171], v[208:211], 0
	v_mfma_f32_16x16x32_bf16 v[64:67], v[176:179], v[208:211], 0
	v_mfma_f32_16x16x32_bf16 v[116:119], v[172:175], v[188:191], v[116:119]
	v_mfma_f32_16x16x32_bf16 v[112:115], v[180:183], v[188:191], v[112:115]
	v_mfma_f32_16x16x32_bf16 v[100:103], v[172:175], v[196:199], v[100:103]
	v_mfma_f32_16x16x32_bf16 v[96:99], v[180:183], v[196:199], v[96:99]
	v_mfma_f32_16x16x32_bf16 v[84:87], v[172:175], v[204:207], v[84:87]
	v_mfma_f32_16x16x32_bf16 v[80:83], v[180:183], v[204:207], v[80:83]
	v_mfma_f32_16x16x32_bf16 v[68:71], v[172:175], v[212:215], v[68:71]
	v_mfma_f32_16x16x32_bf16 v[64:67], v[180:183], v[212:215], v[64:67]
	s_setprio 0
	s_barrier
	s_add_i32 s55, s44, s33
	v_lshl_add_u64 v[216:217], s[26:27], 0, v[132:133]
	s_mov_b32 m0, s55
	ds_read_b128 v[184:187], v150 offset:16384
	ds_read_b128 v[188:191], v150 offset:17408
	ds_read_b128 v[192:195], v150 offset:18432
	ds_read_b128 v[196:199], v150 offset:19456
	ds_read_b128 v[200:203], v150 offset:20480
	ds_read_b128 v[204:207], v150 offset:21504
	ds_read_b128 v[208:211], v150 offset:22528
	ds_read_b128 v[212:215], v150 offset:23552
	global_load_lds_dwordx4 v[216:217], off
	s_add_i32 m0, s55, 0x2000
	s_add_u32 s56, s26, 0x40000
	v_lshl_add_u64 v[218:219], s[26:27], 0, v[128:129]
	s_addc_u32 s57, s27, 0
	s_add_i32 s55, s45, s33
	global_load_lds_dwordx4 v[218:219], off
	v_lshl_add_u64 v[220:221], s[56:57], 0, v[132:133]
	s_mov_b32 m0, s55
	v_lshl_add_u64 v[222:223], s[28:29], 0, v[130:131]
	global_load_lds_dwordx4 v[220:221], off
	v_lshl_add_u64 v[220:221], s[56:57], 0, v[128:129]
	s_add_i32 m0, s55, 0x2000
	s_nop 0
	global_load_lds_dwordx4 v[220:221], off
	v_lshl_add_u64 v[220:221], s[28:29], 0, v[134:135]
	s_mov_b32 m0, s23
	s_nop 0
	global_load_lds_dwordx4 v[220:221], off
	s_mov_b32 m0, s39
	s_nop 0
	global_load_lds_dwordx4 v[222:223], off
	s_waitcnt vmcnt(8)
	s_waitcnt lgkmcnt(0)
	s_barrier
; #define PG8_STAGE(bufoff, gbase, voff) do { _Pragma("unroll") for (int _i = 0; _i < 2; ++_i) \
;         __builtin_amdgcn_global_load_lds((const unsigned*)((const char*)(gbase) + (voff)[_i]), (PG8_LAS unsigned*)(lds + (bufoff) + ldsw + _i * 8192), 16, 0, 0); } while (0)
; #define PG8_LDA(dst, b, h) do { _Pragma("unroll") for (int m = 0; m < 4; ++m) _Pragma("unroll") for (int k = 0; k < 2; ++k) dst[m][k] = *(const PG8_LAS bf16x8*)(lds + PG8_SA(b, h) + aoff + m * 2048 + k * 1024); } while (0)
; #define PG8_LDB(dst, b, h) do { _Pragma("unroll") for (int n = 0; n < 2; ++n) _Pragma("unroll") for (int k = 0; k < 2; ++k) dst[n][k] = *(const PG8_LAS bf16x8*)(lds + PG8_SB(b, h) + boff + n * 2048 + k * 1024); } while (0)
; #define PG8_MMA(ai, bj, At, Bt) do { __builtin_amdgcn_s_setprio(1); _Pragma("unroll") for (int m = 0; m < 4; ++m) _Pragma("unroll") for (int n = 0; n < 2; ++n) _Pragma("unroll") for (int k = 0; k < 2; ++k) \
;         acc[ai][bj][m][n] = __builtin_amdgcn_mfma_f32_16x16x32_bf16(Bt[n][k], At[m][k], acc[ai][bj][m][n], 0, 0, 0); __builtin_amdgcn_s_setprio(0); } while (0)
; #define PG8_WAIT_V(n) asm volatile("s_waitcnt vmcnt(" #n ")" ::: "memory")
; #define PG8_WAIT_L(n) asm volatile("s_waitcnt lgkmcnt(" #n ")" ::: "memory")
; #define PG8_BAR __builtin_amdgcn_s_barrier()
; #define PG8_SCHED __builtin_amdgcn_sched_barrier(0)
; template <class Epi, class Sched, bool ALIGN_EPI = false, bool SP2 = false>
; __device__ __forceinline__ void gemm_phase(PG8_LAS unsigned char* lds, const Gemm g, const Sched& S, const Epi& E) {
;     ...
;             PG8_WAIT_V(8); PG8_WAIT_L(0); PG8_BAR; PG8_MMA(1, 0, At, B0); PG8_MMA(1, 1, At, B1); PG8_BAR; PG8_SCHED;
;             PG8_LDB(B0, 1, 0); PG8_LDB(B1, 1, 1); PG8_SCHED; PG8_LDA(At, 1, 0); PG8_STAGE(PG8_SA(0, 1), a2 + hstep, voffA);
;             PG8_WAIT_V(8); PG8_WAIT_L(0); PG8_BAR; PG8_MMA(0, 0, At, B0); PG8_MMA(0, 1, At, B1); PG8_BAR; PG8_SCHED;
	s_setprio 1
	s_waitcnt lgkmcnt(0)
	v_mfma_f32_16x16x32_bf16 v[60:63], v[152:155], v[184:187], 0
	v_mfma_f32_16x16x32_bf16 v[56:59], v[160:163], v[184:187], 0
	v_mfma_f32_16x16x32_bf16 v[44:47], v[152:155], v[192:195], 0
	v_mfma_f32_16x16x32_bf16 v[40:43], v[160:163], v[192:195], 0
	v_mfma_f32_16x16x32_bf16 v[28:31], v[152:155], v[200:203], 0
	v_mfma_f32_16x16x32_bf16 v[24:27], v[160:163], v[200:203], 0
	v_mfma_f32_16x16x32_bf16 v[12:15], v[152:155], v[208:211], 0
	v_mfma_f32_16x16x32_bf16 v[8:11], v[160:163], v[208:211], 0
	v_mfma_f32_16x16x32_bf16 v[60:63], v[156:159], v[188:191], v[60:63]
	v_mfma_f32_16x16x32_bf16 v[56:59], v[164:167], v[188:191], v[56:59]
	v_mfma_f32_16x16x32_bf16 v[44:47], v[156:159], v[196:199], v[44:47]
	v_mfma_f32_16x16x32_bf16 v[40:43], v[164:167], v[196:199], v[40:43]
	v_mfma_f32_16x16x32_bf16 v[28:31], v[156:159], v[204:207], v[28:31]
	v_mfma_f32_16x16x32_bf16 v[24:27], v[164:167], v[204:207], v[24:27]
	v_mfma_f32_16x16x32_bf16 v[12:15], v[156:159], v[212:215], v[12:15]
	v_mfma_f32_16x16x32_bf16 v[8:11], v[164:167], v[212:215], v[8:11]
	s_setprio 0
	s_setprio 1
	v_mfma_f32_16x16x32_bf16 v[52:55], v[168:171], v[184:187], 0
	v_mfma_f32_16x16x32_bf16 v[48:51], v[176:179], v[184:187], 0
	v_mfma_f32_16x16x32_bf16 v[36:39], v[168:171], v[192:195], 0
	v_mfma_f32_16x16x32_bf16 v[32:35], v[176:179], v[192:195], 0
	v_mfma_f32_16x16x32_bf16 v[20:23], v[168:171], v[200:203], 0
	v_mfma_f32_16x16x32_bf16 v[16:19], v[176:179], v[200:203], 0
	v_mfma_f32_16x16x32_bf16 v[4:7], v[168:171], v[208:211], 0
	v_mfma_f32_16x16x32_bf16 v[0:3], v[176:179], v[208:211], 0
	v_mfma_f32_16x16x32_bf16 v[52:55], v[172:175], v[188:191], v[52:55]
	v_mfma_f32_16x16x32_bf16 v[48:51], v[180:183], v[188:191], v[48:51]
	v_mfma_f32_16x16x32_bf16 v[36:39], v[172:175], v[196:199], v[36:39]
	v_mfma_f32_16x16x32_bf16 v[32:35], v[180:183], v[196:199], v[32:35]
	v_mfma_f32_16x16x32_bf16 v[20:23], v[172:175], v[204:207], v[20:23]
	v_mfma_f32_16x16x32_bf16 v[16:19], v[180:183], v[204:207], v[16:19]
	v_mfma_f32_16x16x32_bf16 v[4:7], v[172:175], v[212:215], v[4:7]
	v_mfma_f32_16x16x32_bf16 v[0:3], v[180:183], v[212:215], v[0:3]
	s_setprio 0
	s_barrier
	s_add_i32 s55, 0, 0x18000
	v_add_u32_e32 v151, s55, v145
	s_add_i32 s56, 0, 0x1c000
	ds_read_b128 v[152:155], v151
	ds_read_b128 v[156:159], v151 offset:1024
	ds_read_b128 v[160:163], v151 offset:2048
	ds_read_b128 v[164:167], v151 offset:3072
	v_add_u32_e32 v151, s56, v145
	ds_read_b128 v[168:171], v151
	ds_read_b128 v[172:175], v151 offset:1024
	ds_read_b128 v[176:179], v151 offset:2048
	ds_read_b128 v[180:183], v151 offset:3072
	s_add_u32 s28, s28, 0x40000
	s_addc_u32 s29, s29, 0
	s_mov_b32 m0, s40
	v_lshl_add_u64 v[224:225], s[28:29], 0, v[134:135]
	ds_read_b128 v[184:187], v150 offset:32768
	ds_read_b128 v[188:191], v150 offset:33792
	ds_read_b128 v[192:195], v150 offset:34816
	ds_read_b128 v[196:199], v150 offset:35840
	ds_read_b128 v[200:203], v150 offset:36864
	ds_read_b128 v[204:207], v150 offset:37888
	ds_read_b128 v[208:211], v150 offset:38912
	ds_read_b128 v[212:215], v150 offset:39936
	global_load_lds_dwordx4 v[224:225], off
	v_lshl_add_u64 v[224:225], s[28:29], 0, v[130:131]
	s_mov_b32 m0, s41
	s_nop 0
	global_load_lds_dwordx4 v[224:225], off
	s_waitcnt vmcnt(8)
	s_waitcnt lgkmcnt(0)
	s_barrier
	s_setprio 1
	s_waitcnt lgkmcnt(0)
	v_mfma_f32_16x16x32_bf16 v[124:127], v[152:155], v[184:187], v[124:127]
	v_mfma_f32_16x16x32_bf16 v[120:123], v[160:163], v[184:187], v[120:123]
	v_mfma_f32_16x16x32_bf16 v[108:111], v[152:155], v[192:195], v[108:111]
	v_mfma_f32_16x16x32_bf16 v[104:107], v[160:163], v[192:195], v[104:107]
	v_mfma_f32_16x16x32_bf16 v[92:95], v[152:155], v[200:203], v[92:95]
	v_mfma_f32_16x16x32_bf16 v[88:91], v[160:163], v[200:203], v[88:91]
	v_mfma_f32_16x16x32_bf16 v[76:79], v[152:155], v[208:211], v[76:79]
	v_mfma_f32_16x16x32_bf16 v[72:75], v[160:163], v[208:211], v[72:75]
	v_mfma_f32_16x16x32_bf16 v[124:127], v[156:159], v[188:191], v[124:127]
	v_mfma_f32_16x16x32_bf16 v[120:123], v[164:167], v[188:191], v[120:123]
	v_mfma_f32_16x16x32_bf16 v[108:111], v[156:159], v[196:199], v[108:111]
	v_mfma_f32_16x16x32_bf16 v[104:107], v[164:167], v[196:199], v[104:107]
	v_mfma_f32_16x16x32_bf16 v[92:95], v[156:159], v[204:207], v[92:95]
	v_mfma_f32_16x16x32_bf16 v[88:91], v[164:167], v[204:207], v[88:91]
	v_mfma_f32_16x16x32_bf16 v[76:79], v[156:159], v[212:215], v[76:79]
	v_mfma_f32_16x16x32_bf16 v[72:75], v[164:167], v[212:215], v[72:75]
	s_setprio 0
	s_setprio 1
	v_mfma_f32_16x16x32_bf16 v[116:119], v[168:171], v[184:187], v[116:119]
	v_mfma_f32_16x16x32_bf16 v[112:115], v[176:179], v[184:187], v[112:115]
	v_mfma_f32_16x16x32_bf16 v[100:103], v[168:171], v[192:195], v[100:103]
	v_mfma_f32_16x16x32_bf16 v[96:99], v[176:179], v[192:195], v[96:99]
	v_mfma_f32_16x16x32_bf16 v[84:87], v[168:171], v[200:203], v[84:87]
	v_mfma_f32_16x16x32_bf16 v[80:83], v[176:179], v[200:203], v[80:83]
	v_mfma_f32_16x16x32_bf16 v[68:71], v[168:171], v[208:211], v[68:71]
	v_mfma_f32_16x16x32_bf16 v[64:67], v[176:179], v[208:211], v[64:67]
	v_mfma_f32_16x16x32_bf16 v[116:119], v[172:175], v[188:191], v[116:119]
	v_mfma_f32_16x16x32_bf16 v[112:115], v[180:183], v[188:191], v[112:115]
	v_mfma_f32_16x16x32_bf16 v[100:103], v[172:175], v[196:199], v[100:103]
	v_mfma_f32_16x16x32_bf16 v[96:99], v[180:183], v[196:199], v[96:99]
	v_mfma_f32_16x16x32_bf16 v[84:87], v[172:175], v[204:207], v[84:87]
	v_mfma_f32_16x16x32_bf16 v[80:83], v[180:183], v[204:207], v[80:83]
	v_mfma_f32_16x16x32_bf16 v[68:71], v[172:175], v[212:215], v[68:71]
	v_mfma_f32_16x16x32_bf16 v[64:67], v[180:183], v[212:215], v[64:67]
	s_setprio 0
	s_barrier
; #define PG8_STAGE(bufoff, gbase, voff) do { _Pragma("unroll") for (int _i = 0; _i < 2; ++_i) \
;         __builtin_amdgcn_global_load_lds((const unsigned*)((const char*)(gbase) + (voff)[_i]), (PG8_LAS unsigned*)(lds + (bufoff) + ldsw + _i * 8192), 16, 0, 0); } while (0)
; #define PG8_LDA(dst, b, h) do { _Pragma("unroll") for (int m = 0; m < 4; ++m) _Pragma("unroll") for (int k = 0; k < 2; ++k) dst[m][k] = *(const PG8_LAS bf16x8*)(lds + PG8_SA(b, h) + aoff + m * 2048 + k * 1024); } while (0)
; #define PG8_MMA(ai, bj, At, Bt) do { __builtin_amdgcn_s_setprio(1); _Pragma("unroll") for (int m = 0; m < 4; ++m) _Pragma("unroll") for (int n = 0; n < 2; ++n) _Pragma("unroll") for (int k = 0; k < 2; ++k) \
;         acc[ai][bj][m][n] = __builtin_amdgcn_mfma_f32_16x16x32_bf16(Bt[n][k], At[m][k], acc[ai][bj][m][n], 0, 0, 0); __builtin_amdgcn_s_setprio(0); } while (0)
; #define PG8_WAIT_V(n) asm volatile("s_waitcnt vmcnt(" #n ")" ::: "memory")
; #define PG8_WAIT_L(n) asm volatile("s_waitcnt lgkmcnt(" #n ")" ::: "memory")
; #define PG8_BAR __builtin_amdgcn_s_barrier()
; #define PG8_SCHED __builtin_amdgcn_sched_barrier(0)
; template <class Epi, class Sched, bool ALIGN_EPI = false, bool SP2 = false>
; __device__ __forceinline__ void gemm_phase(PG8_LAS unsigned char* lds, const Gemm g, const Sched& S, const Epi& E) {
;     ...
;         for (int t = 0; t < nt; t += 2) {
;     ...
;             PG8_LDA(At, 1, 1); PG8_STAGE(PG8_SB(1, 0), b3, voffB); PG8_STAGE(PG8_SB(1, 1), b3 + hstep, voffB); PG8_STAGE(PG8_SA(1, 0), a3, voffA);
;             PG8_WAIT_V(8); PG8_WAIT_L(0); PG8_BAR; PG8_MMA(1, 0, At, B0); PG8_MMA(1, 1, At, B1); PG8_BAR; PG8_SCHED;
	s_add_i32 s28, s55, s33
	v_lshl_add_u64 v[216:217], v[216:217], 0, s[8:9]
	s_mov_b32 m0, s28
	ds_read_b128 v[184:187], v150 offset:49152
	ds_read_b128 v[188:191], v150 offset:50176
	ds_read_b128 v[192:195], v150 offset:51200
	ds_read_b128 v[196:199], v150 offset:52224
	ds_read_b128 v[200:203], v150 offset:53248
	ds_read_b128 v[204:207], v150 offset:54272
	ds_read_b128 v[208:211], v150 offset:55296
	ds_read_b128 v[212:215], v150 offset:56320
	global_load_lds_dwordx4 v[216:217], off
	s_add_i32 m0, s28, 0x2000
	s_add_u32 s26, s26, 0x40080
	v_lshl_add_u64 v[216:217], v[218:219], 0, s[8:9]
	s_addc_u32 s27, s27, 0
	s_add_i32 s28, s56, s33
	global_load_lds_dwordx4 v[216:217], off
	v_lshl_add_u64 v[216:217], s[26:27], 0, v[132:133]
	s_mov_b32 m0, s28
	s_nop 0
	global_load_lds_dwordx4 v[216:217], off
	v_lshl_add_u64 v[216:217], s[26:27], 0, v[128:129]
	s_add_i32 m0, s28, 0x2000
	s_nop 0
	global_load_lds_dwordx4 v[216:217], off
	v_lshl_add_u64 v[216:217], v[220:221], 0, s[8:9]
	s_mov_b32 m0, s42
	s_nop 0
	global_load_lds_dwordx4 v[216:217], off
	v_lshl_add_u64 v[216:217], v[222:223], 0, s[8:9]
	s_mov_b32 m0, s43
	s_nop 0
	global_load_lds_dwordx4 v[216:217], off
	s_waitcnt vmcnt(8)
	s_waitcnt lgkmcnt(0)
	s_barrier
	s_setprio 1
	s_waitcnt lgkmcnt(0)
	v_mfma_f32_16x16x32_bf16 v[60:63], v[152:155], v[184:187], v[60:63]
	v_mfma_f32_16x16x32_bf16 v[56:59], v[160:163], v[184:187], v[56:59]
	v_mfma_f32_16x16x32_bf16 v[44:47], v[152:155], v[192:195], v[44:47]
	v_mfma_f32_16x16x32_bf16 v[40:43], v[160:163], v[192:195], v[40:43]
	v_mfma_f32_16x16x32_bf16 v[28:31], v[152:155], v[200:203], v[28:31]
	v_mfma_f32_16x16x32_bf16 v[24:27], v[160:163], v[200:203], v[24:27]
	v_mfma_f32_16x16x32_bf16 v[12:15], v[152:155], v[208:211], v[12:15]
	v_mfma_f32_16x16x32_bf16 v[8:11], v[160:163], v[208:211], v[8:11]
	v_mfma_f32_16x16x32_bf16 v[60:63], v[156:159], v[188:191], v[60:63]
	v_mfma_f32_16x16x32_bf16 v[56:59], v[164:167], v[188:191], v[56:59]
	v_mfma_f32_16x16x32_bf16 v[44:47], v[156:159], v[196:199], v[44:47]
	v_mfma_f32_16x16x32_bf16 v[40:43], v[164:167], v[196:199], v[40:43]
	v_mfma_f32_16x16x32_bf16 v[28:31], v[156:159], v[204:207], v[28:31]
	v_mfma_f32_16x16x32_bf16 v[24:27], v[164:167], v[204:207], v[24:27]
	v_mfma_f32_16x16x32_bf16 v[12:15], v[156:159], v[212:215], v[12:15]
	v_mfma_f32_16x16x32_bf16 v[8:11], v[164:167], v[212:215], v[8:11]
	s_setprio 0
	s_setprio 1
	v_mfma_f32_16x16x32_bf16 v[52:55], v[168:171], v[184:187], v[52:55]
	v_mfma_f32_16x16x32_bf16 v[48:51], v[176:179], v[184:187], v[48:51]
	v_mfma_f32_16x16x32_bf16 v[36:39], v[168:171], v[192:195], v[36:39]
	v_mfma_f32_16x16x32_bf16 v[32:35], v[176:179], v[192:195], v[32:35]
	v_mfma_f32_16x16x32_bf16 v[20:23], v[168:171], v[200:203], v[20:23]
	v_mfma_f32_16x16x32_bf16 v[16:19], v[176:179], v[200:203], v[16:19]
	v_mfma_f32_16x16x32_bf16 v[4:7], v[168:171], v[208:211], v[4:7]
	v_mfma_f32_16x16x32_bf16 v[0:3], v[176:179], v[208:211], v[0:3]
	v_mfma_f32_16x16x32_bf16 v[52:55], v[172:175], v[188:191], v[52:55]
	v_mfma_f32_16x16x32_bf16 v[48:51], v[180:183], v[188:191], v[48:51]
	v_mfma_f32_16x16x32_bf16 v[36:39], v[172:175], v[196:199], v[36:39]
	v_mfma_f32_16x16x32_bf16 v[32:35], v[180:183], v[196:199], v[32:35]
	v_mfma_f32_16x16x32_bf16 v[20:23], v[172:175], v[204:207], v[20:23]
	v_mfma_f32_16x16x32_bf16 v[16:19], v[180:183], v[204:207], v[16:19]
	v_mfma_f32_16x16x32_bf16 v[4:7], v[172:175], v[212:215], v[4:7]
	v_mfma_f32_16x16x32_bf16 v[0:3], v[180:183], v[212:215], v[0:3]
	s_setprio 0
	s_barrier
	s_add_i32 s54, s54, 2
	s_add_u32 s24, s24, 0x100
	s_addc_u32 s25, s25, 0
	s_add_u32 s52, s52, 0x100
	s_addc_u32 s53, s53, 0
	s_cmp_gt_u32 s54, 13

.LBB0_1129:
	s_add_u32 s24, s24, 0xb0080
	s_addc_u32 s25, s25, 0
	s_add_u32 s51, s26, 0x100
	s_addc_u32 s52, s27, 0
	s_mov_b32 s53, -2
	ds_read_b128 v[120:123], v245
	ds_read_b128 v[128:131], v245 offset:1024
	ds_read_b128 v[136:139], v245 offset:2048
	ds_read_b128 v[140:143], v245 offset:3072
	ds_read_b128 v[144:147], v246
	ds_read_b128 v[148:151], v246 offset:1024
	ds_read_b128 v[152:155], v246 offset:2048
	ds_read_b128 v[156:159], v246 offset:3072
	s_add_u32 s26, s24, 0xfff50080
	s_addc_u32 s27, s25, -1
	s_cmp_eq_u32 s53, 40
	s_cselect_b32 s29, s7, s27
	s_cselect_b32 s28, s6, s26
	s_cselect_b32 s27, s23, s52
	s_cselect_b32 s26, s22, s51
	v_lshl_add_u64 v[204:205], s[24:25], 0, v[200:201]
	s_add_i32 m0, s35, 0xc000
	ds_read_b128 v[160:163], v247
	ds_read_b128 v[164:167], v247 offset:1024
	ds_read_b128 v[168:171], v247 offset:2048
	ds_read_b128 v[172:175], v247 offset:3072
	ds_read_b128 v[176:179], v247 offset:4096
	ds_read_b128 v[180:183], v247 offset:5120
	ds_read_b128 v[184:187], v247 offset:6144
	ds_read_b128 v[188:191], v247 offset:7168
	global_load_lds_dwordx4 v[204:205], off
	v_lshl_add_u64 v[204:205], s[24:25], 0, v[202:203]
	s_add_i32 m0, s35, 0xe000
	s_nop 0
	global_load_lds_dwordx4 v[204:205], off
	s_waitcnt vmcnt(8)
	s_waitcnt lgkmcnt(0)
	s_barrier
	s_setprio 1
	s_waitcnt lgkmcnt(0)
	v_mfma_f32_16x16x32_bf16 v[132:135], v[120:123], v[160:163], 0
	v_mfma_f32_16x16x32_bf16 v[124:127], v[136:139], v[160:163], 0
	v_mfma_f32_16x16x32_bf16 v[108:111], v[120:123], v[168:171], 0
	v_mfma_f32_16x16x32_bf16 v[104:107], v[136:139], v[168:171], 0
	v_mfma_f32_16x16x32_bf16 v[92:95], v[120:123], v[176:179], 0
	v_mfma_f32_16x16x32_bf16 v[88:91], v[136:139], v[176:179], 0
	v_mfma_f32_16x16x32_bf16 v[76:79], v[120:123], v[184:187], 0
	v_mfma_f32_16x16x32_bf16 v[72:75], v[136:139], v[184:187], 0
	v_mfma_f32_16x16x32_bf16 v[132:135], v[128:131], v[164:167], v[132:135]
	v_mfma_f32_16x16x32_bf16 v[124:127], v[140:143], v[164:167], v[124:127]
	v_mfma_f32_16x16x32_bf16 v[108:111], v[128:131], v[172:175], v[108:111]
	v_mfma_f32_16x16x32_bf16 v[104:107], v[140:143], v[172:175], v[104:107]
	v_mfma_f32_16x16x32_bf16 v[92:95], v[128:131], v[180:183], v[92:95]
	v_mfma_f32_16x16x32_bf16 v[88:91], v[140:143], v[180:183], v[88:91]
	v_mfma_f32_16x16x32_bf16 v[76:79], v[128:131], v[188:191], v[76:79]
	v_mfma_f32_16x16x32_bf16 v[72:75], v[140:143], v[188:191], v[72:75]
	s_setprio 0
	s_setprio 1
	v_mfma_f32_16x16x32_bf16 v[116:119], v[144:147], v[160:163], 0
	v_mfma_f32_16x16x32_bf16 v[112:115], v[152:155], v[160:163], 0
	v_mfma_f32_16x16x32_bf16 v[100:103], v[144:147], v[168:171], 0
	v_mfma_f32_16x16x32_bf16 v[96:99], v[152:155], v[168:171], 0
	v_mfma_f32_16x16x32_bf16 v[84:87], v[144:147], v[176:179], 0
	v_mfma_f32_16x16x32_bf16 v[80:83], v[152:155], v[176:179], 0
	v_mfma_f32_16x16x32_bf16 v[68:71], v[144:147], v[184:187], 0
	v_mfma_f32_16x16x32_bf16 v[64:67], v[152:155], v[184:187], 0
	v_mfma_f32_16x16x32_bf16 v[116:119], v[148:151], v[164:167], v[116:119]
	v_mfma_f32_16x16x32_bf16 v[112:115], v[156:159], v[164:167], v[112:115]
	v_mfma_f32_16x16x32_bf16 v[100:103], v[148:151], v[172:175], v[100:103]
	v_mfma_f32_16x16x32_bf16 v[96:99], v[156:159], v[172:175], v[96:99]
	v_mfma_f32_16x16x32_bf16 v[84:87], v[148:151], v[180:183], v[84:87]
	v_mfma_f32_16x16x32_bf16 v[80:83], v[156:159], v[180:183], v[80:83]
	v_mfma_f32_16x16x32_bf16 v[68:71], v[148:151], v[188:191], v[68:71]
	v_mfma_f32_16x16x32_bf16 v[64:67], v[156:159], v[188:191], v[64:67]
	s_setprio 0
	s_barrier
	s_add_i32 s54, s45, s34
	v_lshl_add_u64 v[204:205], s[26:27], 0, v[194:195]
	s_mov_b32 m0, s54
	ds_read_b128 v[160:163], v247 offset:16384
	ds_read_b128 v[164:167], v247 offset:17408
	ds_read_b128 v[168:171], v247 offset:18432
	ds_read_b128 v[172:175], v247 offset:19456
	ds_read_b128 v[176:179], v247 offset:20480
	ds_read_b128 v[180:183], v247 offset:21504
	ds_read_b128 v[184:187], v247 offset:22528
	ds_read_b128 v[188:191], v247 offset:23552
	global_load_lds_dwordx4 v[204:205], off
	s_add_i32 m0, s54, 0x2000
	s_add_u32 s54, s26, 0xb0000
	v_lshl_add_u64 v[206:207], s[26:27], 0, v[198:199]
	s_addc_u32 s55, s27, 0
	s_add_i32 s56, s46, s34
	global_load_lds_dwordx4 v[206:207], off
	v_lshl_add_u64 v[208:209], s[54:55], 0, v[194:195]
	s_mov_b32 m0, s56
	v_lshl_add_u64 v[210:211], s[28:29], 0, v[196:197]
	global_load_lds_dwordx4 v[208:209], off
	v_lshl_add_u64 v[208:209], s[54:55], 0, v[198:199]
	s_add_i32 m0, s56, 0x2000
	s_nop 0
	global_load_lds_dwordx4 v[208:209], off
	v_lshl_add_u64 v[208:209], s[28:29], 0, v[192:193]
	s_mov_b32 m0, s35
	s_nop 0
	global_load_lds_dwordx4 v[208:209], off
	s_mov_b32 m0, s36
	s_nop 0
	global_load_lds_dwordx4 v[210:211], off
	s_waitcnt vmcnt(8)
	s_waitcnt lgkmcnt(0)
	s_barrier
	s_setprio 1
	s_waitcnt lgkmcnt(0)
	v_mfma_f32_16x16x32_bf16 v[60:63], v[120:123], v[160:163], 0
	v_mfma_f32_16x16x32_bf16 v[56:59], v[136:139], v[160:163], 0
	v_mfma_f32_16x16x32_bf16 v[44:47], v[120:123], v[168:171], 0
	v_mfma_f32_16x16x32_bf16 v[40:43], v[136:139], v[168:171], 0
	v_mfma_f32_16x16x32_bf16 v[28:31], v[120:123], v[176:179], 0
	v_mfma_f32_16x16x32_bf16 v[24:27], v[136:139], v[176:179], 0
	v_mfma_f32_16x16x32_bf16 v[12:15], v[120:123], v[184:187], 0
	v_mfma_f32_16x16x32_bf16 v[8:11], v[136:139], v[184:187], 0
	v_mfma_f32_16x16x32_bf16 v[60:63], v[128:131], v[164:167], v[60:63]
	v_mfma_f32_16x16x32_bf16 v[56:59], v[140:143], v[164:167], v[56:59]
	v_mfma_f32_16x16x32_bf16 v[44:47], v[128:131], v[172:175], v[44:47]
	v_mfma_f32_16x16x32_bf16 v[40:43], v[140:143], v[172:175], v[40:43]
	v_mfma_f32_16x16x32_bf16 v[28:31], v[128:131], v[180:183], v[28:31]
	v_mfma_f32_16x16x32_bf16 v[24:27], v[140:143], v[180:183], v[24:27]
	v_mfma_f32_16x16x32_bf16 v[12:15], v[128:131], v[188:191], v[12:15]
	v_mfma_f32_16x16x32_bf16 v[8:11], v[140:143], v[188:191], v[8:11]
	s_setprio 0
	s_setprio 1
	v_mfma_f32_16x16x32_bf16 v[52:55], v[144:147], v[160:163], 0
	v_mfma_f32_16x16x32_bf16 v[48:51], v[152:155], v[160:163], 0
	v_mfma_f32_16x16x32_bf16 v[36:39], v[144:147], v[168:171], 0
	v_mfma_f32_16x16x32_bf16 v[32:35], v[152:155], v[168:171], 0
	v_mfma_f32_16x16x32_bf16 v[20:23], v[144:147], v[176:179], 0
	v_mfma_f32_16x16x32_bf16 v[16:19], v[152:155], v[176:179], 0
	v_mfma_f32_16x16x32_bf16 v[4:7], v[144:147], v[184:187], 0
	v_mfma_f32_16x16x32_bf16 v[0:3], v[152:155], v[184:187], 0
	v_mfma_f32_16x16x32_bf16 v[52:55], v[148:151], v[164:167], v[52:55]
	v_mfma_f32_16x16x32_bf16 v[48:51], v[156:159], v[164:167], v[48:51]
	v_mfma_f32_16x16x32_bf16 v[36:39], v[148:151], v[172:175], v[36:39]
	v_mfma_f32_16x16x32_bf16 v[32:35], v[156:159], v[172:175], v[32:35]
	v_mfma_f32_16x16x32_bf16 v[20:23], v[148:151], v[180:183], v[20:23]
	v_mfma_f32_16x16x32_bf16 v[16:19], v[156:159], v[180:183], v[16:19]
	v_mfma_f32_16x16x32_bf16 v[4:7], v[148:151], v[188:191], v[4:7]
	v_mfma_f32_16x16x32_bf16 v[0:3], v[156:159], v[188:191], v[0:3]
	s_setprio 0
	s_barrier
	s_add_i32 s54, 0, 0x18000
	s_add_i32 s55, 0, 0x1c000
	v_add_u32_e32 v140, s54, v243
	v_add_u32_e32 v156, s55, v243
	ds_read_b128 v[120:123], v140
	ds_read_b128 v[128:131], v140 offset:1024
	ds_read_b128 v[136:139], v140 offset:2048
	ds_read_b128 v[140:143], v140 offset:3072
	ds_read_b128 v[144:147], v156
	ds_read_b128 v[148:151], v156 offset:1024
	ds_read_b128 v[152:155], v156 offset:2048
	ds_read_b128 v[156:159], v156 offset:3072
	s_add_u32 s28, s28, 0xb0000
	s_addc_u32 s29, s29, 0
	s_mov_b32 m0, s37
	v_lshl_add_u64 v[212:213], s[28:29], 0, v[192:193]
	ds_read_b128 v[160:163], v247 offset:32768
	ds_read_b128 v[164:167], v247 offset:33792
	ds_read_b128 v[168:171], v247 offset:34816
	ds_read_b128 v[172:175], v247 offset:35840
	ds_read_b128 v[176:179], v247 offset:36864
	ds_read_b128 v[180:183], v247 offset:37888
	ds_read_b128 v[184:187], v247 offset:38912
	ds_read_b128 v[188:191], v247 offset:39936
	global_load_lds_dwordx4 v[212:213], off
	v_lshl_add_u64 v[212:213], s[28:29], 0, v[196:197]
	s_mov_b32 m0, s38
	s_nop 0
	global_load_lds_dwordx4 v[212:213], off
	s_waitcnt vmcnt(8)
	s_waitcnt lgkmcnt(0)
	s_barrier
	s_setprio 1
	s_waitcnt lgkmcnt(0)
	v_mfma_f32_16x16x32_bf16 v[132:135], v[120:123], v[160:163], v[132:135]
	v_mfma_f32_16x16x32_bf16 v[124:127], v[136:139], v[160:163], v[124:127]
	v_mfma_f32_16x16x32_bf16 v[108:111], v[120:123], v[168:171], v[108:111]
	v_mfma_f32_16x16x32_bf16 v[104:107], v[136:139], v[168:171], v[104:107]
	v_mfma_f32_16x16x32_bf16 v[92:95], v[120:123], v[176:179], v[92:95]
	v_mfma_f32_16x16x32_bf16 v[88:91], v[136:139], v[176:179], v[88:91]
	v_mfma_f32_16x16x32_bf16 v[76:79], v[120:123], v[184:187], v[76:79]
	v_mfma_f32_16x16x32_bf16 v[72:75], v[136:139], v[184:187], v[72:75]
	v_mfma_f32_16x16x32_bf16 v[132:135], v[128:131], v[164:167], v[132:135]
	v_mfma_f32_16x16x32_bf16 v[124:127], v[140:143], v[164:167], v[124:127]
	v_mfma_f32_16x16x32_bf16 v[108:111], v[128:131], v[172:175], v[108:111]
	v_mfma_f32_16x16x32_bf16 v[104:107], v[140:143], v[172:175], v[104:107]
	v_mfma_f32_16x16x32_bf16 v[92:95], v[128:131], v[180:183], v[92:95]
	v_mfma_f32_16x16x32_bf16 v[88:91], v[140:143], v[180:183], v[88:91]
	v_mfma_f32_16x16x32_bf16 v[76:79], v[128:131], v[188:191], v[76:79]
	v_mfma_f32_16x16x32_bf16 v[72:75], v[140:143], v[188:191], v[72:75]
	s_setprio 0
	s_setprio 1
	v_mfma_f32_16x16x32_bf16 v[116:119], v[144:147], v[160:163], v[116:119]
	v_mfma_f32_16x16x32_bf16 v[112:115], v[152:155], v[160:163], v[112:115]
	v_mfma_f32_16x16x32_bf16 v[100:103], v[144:147], v[168:171], v[100:103]
	v_mfma_f32_16x16x32_bf16 v[96:99], v[152:155], v[168:171], v[96:99]
	v_mfma_f32_16x16x32_bf16 v[84:87], v[144:147], v[176:179], v[84:87]
	v_mfma_f32_16x16x32_bf16 v[80:83], v[152:155], v[176:179], v[80:83]
	v_mfma_f32_16x16x32_bf16 v[68:71], v[144:147], v[184:187], v[68:71]
	v_mfma_f32_16x16x32_bf16 v[64:67], v[152:155], v[184:187], v[64:67]
	v_mfma_f32_16x16x32_bf16 v[116:119], v[148:151], v[164:167], v[116:119]
	v_mfma_f32_16x16x32_bf16 v[112:115], v[156:159], v[164:167], v[112:115]
	v_mfma_f32_16x16x32_bf16 v[100:103], v[148:151], v[172:175], v[100:103]
	v_mfma_f32_16x16x32_bf16 v[96:99], v[156:159], v[172:175], v[96:99]
	v_mfma_f32_16x16x32_bf16 v[84:87], v[148:151], v[180:183], v[84:87]
	v_mfma_f32_16x16x32_bf16 v[80:83], v[156:159], v[180:183], v[80:83]
	v_mfma_f32_16x16x32_bf16 v[68:71], v[148:151], v[188:191], v[68:71]
	v_mfma_f32_16x16x32_bf16 v[64:67], v[156:159], v[188:191], v[64:67]
	s_setprio 0
	s_barrier
	s_add_i32 s28, s54, s34
	v_lshl_add_u64 v[204:205], v[204:205], 0, s[18:19]
	s_mov_b32 m0, s28
	ds_read_b128 v[160:163], v247 offset:49152
	ds_read_b128 v[164:167], v247 offset:50176
	ds_read_b128 v[168:171], v247 offset:51200
	ds_read_b128 v[172:175], v247 offset:52224
	ds_read_b128 v[176:179], v247 offset:53248
	ds_read_b128 v[180:183], v247 offset:54272
	ds_read_b128 v[184:187], v247 offset:55296
	ds_read_b128 v[188:191], v247 offset:56320
	global_load_lds_dwordx4 v[204:205], off
	s_add_i32 m0, s28, 0x2000
	s_add_u32 s26, s26, 0xb0080
	v_lshl_add_u64 v[204:205], v[206:207], 0, s[18:19]
	s_addc_u32 s27, s27, 0
	s_add_i32 s28, s55, s34
	global_load_lds_dwordx4 v[204:205], off
	v_lshl_add_u64 v[204:205], s[26:27], 0, v[194:195]
	s_mov_b32 m0, s28
	s_nop 0
	global_load_lds_dwordx4 v[204:205], off
	v_lshl_add_u64 v[204:205], s[26:27], 0, v[198:199]
	s_add_i32 m0, s28, 0x2000
	s_nop 0
	global_load_lds_dwordx4 v[204:205], off
	v_lshl_add_u64 v[204:205], v[208:209], 0, s[18:19]
	s_mov_b32 m0, s40
	s_nop 0
	global_load_lds_dwordx4 v[204:205], off
	v_lshl_add_u64 v[204:205], v[210:211], 0, s[18:19]
	s_mov_b32 m0, s41
	s_nop 0
	global_load_lds_dwordx4 v[204:205], off
	s_waitcnt vmcnt(8)
	s_waitcnt lgkmcnt(0)
	s_barrier
	s_setprio 1
	s_waitcnt lgkmcnt(0)
	v_mfma_f32_16x16x32_bf16 v[60:63], v[120:123], v[160:163], v[60:63]
	v_mfma_f32_16x16x32_bf16 v[56:59], v[136:139], v[160:163], v[56:59]
	v_mfma_f32_16x16x32_bf16 v[44:47], v[120:123], v[168:171], v[44:47]
	v_mfma_f32_16x16x32_bf16 v[40:43], v[136:139], v[168:171], v[40:43]
	v_mfma_f32_16x16x32_bf16 v[28:31], v[120:123], v[176:179], v[28:31]
	v_mfma_f32_16x16x32_bf16 v[24:27], v[136:139], v[176:179], v[24:27]
	v_mfma_f32_16x16x32_bf16 v[12:15], v[120:123], v[184:187], v[12:15]
	v_mfma_f32_16x16x32_bf16 v[8:11], v[136:139], v[184:187], v[8:11]
	v_mfma_f32_16x16x32_bf16 v[60:63], v[128:131], v[164:167], v[60:63]
	v_mfma_f32_16x16x32_bf16 v[56:59], v[140:143], v[164:167], v[56:59]
	v_mfma_f32_16x16x32_bf16 v[44:47], v[128:131], v[172:175], v[44:47]
	v_mfma_f32_16x16x32_bf16 v[40:43], v[140:143], v[172:175], v[40:43]
	v_mfma_f32_16x16x32_bf16 v[28:31], v[128:131], v[180:183], v[28:31]
	v_mfma_f32_16x16x32_bf16 v[24:27], v[140:143], v[180:183], v[24:27]
	v_mfma_f32_16x16x32_bf16 v[12:15], v[128:131], v[188:191], v[12:15]
	v_mfma_f32_16x16x32_bf16 v[8:11], v[140:143], v[188:191], v[8:11]
	s_setprio 0
	s_setprio 1
	v_mfma_f32_16x16x32_bf16 v[52:55], v[144:147], v[160:163], v[52:55]
	v_mfma_f32_16x16x32_bf16 v[48:51], v[152:155], v[160:163], v[48:51]
	v_mfma_f32_16x16x32_bf16 v[36:39], v[144:147], v[168:171], v[36:39]
	v_mfma_f32_16x16x32_bf16 v[32:35], v[152:155], v[168:171], v[32:35]
	v_mfma_f32_16x16x32_bf16 v[20:23], v[144:147], v[176:179], v[20:23]
	v_mfma_f32_16x16x32_bf16 v[16:19], v[152:155], v[176:179], v[16:19]
	v_mfma_f32_16x16x32_bf16 v[4:7], v[144:147], v[184:187], v[4:7]
	v_mfma_f32_16x16x32_bf16 v[0:3], v[152:155], v[184:187], v[0:3]
	v_mfma_f32_16x16x32_bf16 v[52:55], v[148:151], v[164:167], v[52:55]
	v_mfma_f32_16x16x32_bf16 v[48:51], v[156:159], v[164:167], v[48:51]
	v_mfma_f32_16x16x32_bf16 v[36:39], v[148:151], v[172:175], v[36:39]
	v_mfma_f32_16x16x32_bf16 v[32:35], v[156:159], v[172:175], v[32:35]
	v_mfma_f32_16x16x32_bf16 v[20:23], v[148:151], v[180:183], v[20:23]
	v_mfma_f32_16x16x32_bf16 v[16:19], v[156:159], v[180:183], v[16:19]
	v_mfma_f32_16x16x32_bf16 v[4:7], v[148:151], v[188:191], v[4:7]
	v_mfma_f32_16x16x32_bf16 v[0:3], v[156:159], v[188:191], v[0:3]
	s_setprio 0
	s_barrier
	s_add_i32 s53, s53, 2
	s_add_u32 s24, s24, 0x100
	s_addc_u32 s25, s25, 0
	s_add_u32 s51, s51, 0x100
	s_addc_u32 s52, s52, 0
	s_cmp_gt_u32 s53, 41

.LBB0_1218:
	s_ashr_i32 s17, s16, 31
	s_lshl_b64 s[18:19], s[16:17], 19
	s_add_u32 s18, s36, s18
	s_addc_u32 s19, s37, s19
	s_and_b64 s[20:21], s[0:1], exec
	s_cselect_b32 s17, s19, s25
	s_cselect_b32 s50, s18, s24
	s_ashr_i32 s15, s14, 31
	s_lshl_b64 s[20:21], s[14:15], 19
	s_add_u32 s20, s34, s20
	s_addc_u32 s21, s35, s21
	s_and_b64 s[28:29], s[0:1], exec
	s_cselect_b32 s15, s21, s27
	s_cselect_b32 s51, s20, s26
	s_add_u32 s24, s24, 0x40080
	s_addc_u32 s25, s25, 0
	s_add_u32 s52, s26, 0x100
	s_addc_u32 s53, s27, 0
	s_mov_b32 s54, -2
	ds_read_b128 v[152:155], v148
	ds_read_b128 v[156:159], v148 offset:1024
	ds_read_b128 v[160:163], v148 offset:2048
	ds_read_b128 v[164:167], v148 offset:3072
	ds_read_b128 v[168:171], v149
	ds_read_b128 v[172:175], v149 offset:1024
	ds_read_b128 v[176:179], v149 offset:2048
	ds_read_b128 v[180:183], v149 offset:3072
	s_add_u32 s26, s24, 0xfffc0080
	s_addc_u32 s27, s25, -1
	s_cmp_eq_u32 s54, 12
	s_cselect_b32 s29, s17, s27
	s_cselect_b32 s28, s50, s26
	s_cselect_b32 s27, s15, s53
	s_cselect_b32 s26, s51, s52
	v_lshl_add_u64 v[216:217], s[24:25], 0, v[136:137]
	s_add_i32 m0, s23, 0xc000
	ds_read_b128 v[184:187], v150
	ds_read_b128 v[188:191], v150 offset:1024
	ds_read_b128 v[192:195], v150 offset:2048
	ds_read_b128 v[196:199], v150 offset:3072
	ds_read_b128 v[200:203], v150 offset:4096
	ds_read_b128 v[204:207], v150 offset:5120
	ds_read_b128 v[208:211], v150 offset:6144
	ds_read_b128 v[212:215], v150 offset:7168
	global_load_lds_dwordx4 v[216:217], off
	v_lshl_add_u64 v[216:217], s[24:25], 0, v[138:139]
	s_add_i32 m0, s23, 0xe000
	s_nop 0
	global_load_lds_dwordx4 v[216:217], off
	s_waitcnt vmcnt(8)
	s_waitcnt lgkmcnt(0)
	s_barrier
	s_setprio 1
	s_waitcnt lgkmcnt(0)
	v_mfma_f32_16x16x32_bf16 v[124:127], v[152:155], v[184:187], 0
	v_mfma_f32_16x16x32_bf16 v[120:123], v[160:163], v[184:187], 0
	v_mfma_f32_16x16x32_bf16 v[108:111], v[152:155], v[192:195], 0
	v_mfma_f32_16x16x32_bf16 v[104:107], v[160:163], v[192:195], 0
	v_mfma_f32_16x16x32_bf16 v[92:95], v[152:155], v[200:203], 0
	v_mfma_f32_16x16x32_bf16 v[88:91], v[160:163], v[200:203], 0
	v_mfma_f32_16x16x32_bf16 v[76:79], v[152:155], v[208:211], 0
	v_mfma_f32_16x16x32_bf16 v[72:75], v[160:163], v[208:211], 0
	v_mfma_f32_16x16x32_bf16 v[124:127], v[156:159], v[188:191], v[124:127]
	v_mfma_f32_16x16x32_bf16 v[120:123], v[164:167], v[188:191], v[120:123]
	v_mfma_f32_16x16x32_bf16 v[108:111], v[156:159], v[196:199], v[108:111]
	v_mfma_f32_16x16x32_bf16 v[104:107], v[164:167], v[196:199], v[104:107]
	v_mfma_f32_16x16x32_bf16 v[92:95], v[156:159], v[204:207], v[92:95]
	v_mfma_f32_16x16x32_bf16 v[88:91], v[164:167], v[204:207], v[88:91]
	v_mfma_f32_16x16x32_bf16 v[76:79], v[156:159], v[212:215], v[76:79]
	v_mfma_f32_16x16x32_bf16 v[72:75], v[164:167], v[212:215], v[72:75]
	s_setprio 0
	s_setprio 1
	v_mfma_f32_16x16x32_bf16 v[116:119], v[168:171], v[184:187], 0
	v_mfma_f32_16x16x32_bf16 v[112:115], v[176:179], v[184:187], 0
	v_mfma_f32_16x16x32_bf16 v[100:103], v[168:171], v[192:195], 0
	v_mfma_f32_16x16x32_bf16 v[96:99], v[176:179], v[192:195], 0
	v_mfma_f32_16x16x32_bf16 v[84:87], v[168:171], v[200:203], 0
	v_mfma_f32_16x16x32_bf16 v[80:83], v[176:179], v[200:203], 0
	v_mfma_f32_16x16x32_bf16 v[68:71], v[168:171], v[208:211], 0
	v_mfma_f32_16x16x32_bf16 v[64:67], v[176:179], v[208:211], 0
	v_mfma_f32_16x16x32_bf16 v[116:119], v[172:175], v[188:191], v[116:119]
	v_mfma_f32_16x16x32_bf16 v[112:115], v[180:183], v[188:191], v[112:115]
	v_mfma_f32_16x16x32_bf16 v[100:103], v[172:175], v[196:199], v[100:103]
	v_mfma_f32_16x16x32_bf16 v[96:99], v[180:183], v[196:199], v[96:99]
	v_mfma_f32_16x16x32_bf16 v[84:87], v[172:175], v[204:207], v[84:87]
	v_mfma_f32_16x16x32_bf16 v[80:83], v[180:183], v[204:207], v[80:83]
	v_mfma_f32_16x16x32_bf16 v[68:71], v[172:175], v[212:215], v[68:71]
	v_mfma_f32_16x16x32_bf16 v[64:67], v[180:183], v[212:215], v[64:67]
	s_setprio 0
	s_barrier
	s_add_i32 s55, s44, s33
	v_lshl_add_u64 v[216:217], s[26:27], 0, v[132:133]
	s_mov_b32 m0, s55
	ds_read_b128 v[184:187], v150 offset:16384
	ds_read_b128 v[188:191], v150 offset:17408
	ds_read_b128 v[192:195], v150 offset:18432
	ds_read_b128 v[196:199], v150 offset:19456
	ds_read_b128 v[200:203], v150 offset:20480
	ds_read_b128 v[204:207], v150 offset:21504
	ds_read_b128 v[208:211], v150 offset:22528
	ds_read_b128 v[212:215], v150 offset:23552
	global_load_lds_dwordx4 v[216:217], off
	s_add_i32 m0, s55, 0x2000
	s_add_u32 s56, s26, 0x40000
	v_lshl_add_u64 v[218:219], s[26:27], 0, v[128:129]
	s_addc_u32 s57, s27, 0
	s_add_i32 s55, s45, s33
	global_load_lds_dwordx4 v[218:219], off
	v_lshl_add_u64 v[220:221], s[56:57], 0, v[132:133]
	s_mov_b32 m0, s55
	v_lshl_add_u64 v[222:223], s[28:29], 0, v[130:131]
	global_load_lds_dwordx4 v[220:221], off
	v_lshl_add_u64 v[220:221], s[56:57], 0, v[128:129]
	s_add_i32 m0, s55, 0x2000
	s_nop 0
	global_load_lds_dwordx4 v[220:221], off
	v_lshl_add_u64 v[220:221], s[28:29], 0, v[134:135]
	s_mov_b32 m0, s23
	s_nop 0
	global_load_lds_dwordx4 v[220:221], off
	s_mov_b32 m0, s39
	s_nop 0
	global_load_lds_dwordx4 v[222:223], off
	s_waitcnt vmcnt(8)
	s_waitcnt lgkmcnt(0)
	s_barrier
	s_setprio 1
	s_waitcnt lgkmcnt(0)
	v_mfma_f32_16x16x32_bf16 v[60:63], v[152:155], v[184:187], 0
	v_mfma_f32_16x16x32_bf16 v[56:59], v[160:163], v[184:187], 0
	v_mfma_f32_16x16x32_bf16 v[44:47], v[152:155], v[192:195], 0
	v_mfma_f32_16x16x32_bf16 v[40:43], v[160:163], v[192:195], 0
	v_mfma_f32_16x16x32_bf16 v[28:31], v[152:155], v[200:203], 0
	v_mfma_f32_16x16x32_bf16 v[24:27], v[160:163], v[200:203], 0
	v_mfma_f32_16x16x32_bf16 v[12:15], v[152:155], v[208:211], 0
	v_mfma_f32_16x16x32_bf16 v[8:11], v[160:163], v[208:211], 0
	v_mfma_f32_16x16x32_bf16 v[60:63], v[156:159], v[188:191], v[60:63]
	v_mfma_f32_16x16x32_bf16 v[56:59], v[164:167], v[188:191], v[56:59]
	v_mfma_f32_16x16x32_bf16 v[44:47], v[156:159], v[196:199], v[44:47]
	v_mfma_f32_16x16x32_bf16 v[40:43], v[164:167], v[196:199], v[40:43]
	v_mfma_f32_16x16x32_bf16 v[28:31], v[156:159], v[204:207], v[28:31]
	v_mfma_f32_16x16x32_bf16 v[24:27], v[164:167], v[204:207], v[24:27]
	v_mfma_f32_16x16x32_bf16 v[12:15], v[156:159], v[212:215], v[12:15]
	v_mfma_f32_16x16x32_bf16 v[8:11], v[164:167], v[212:215], v[8:11]
	s_setprio 0
	s_setprio 1
	v_mfma_f32_16x16x32_bf16 v[52:55], v[168:171], v[184:187], 0
	v_mfma_f32_16x16x32_bf16 v[48:51], v[176:179], v[184:187], 0
	v_mfma_f32_16x16x32_bf16 v[36:39], v[168:171], v[192:195], 0
	v_mfma_f32_16x16x32_bf16 v[32:35], v[176:179], v[192:195], 0
	v_mfma_f32_16x16x32_bf16 v[20:23], v[168:171], v[200:203], 0
	v_mfma_f32_16x16x32_bf16 v[16:19], v[176:179], v[200:203], 0
	v_mfma_f32_16x16x32_bf16 v[4:7], v[168:171], v[208:211], 0
	v_mfma_f32_16x16x32_bf16 v[0:3], v[176:179], v[208:211], 0
	v_mfma_f32_16x16x32_bf16 v[52:55], v[172:175], v[188:191], v[52:55]
	v_mfma_f32_16x16x32_bf16 v[48:51], v[180:183], v[188:191], v[48:51]
	v_mfma_f32_16x16x32_bf16 v[36:39], v[172:175], v[196:199], v[36:39]
	v_mfma_f32_16x16x32_bf16 v[32:35], v[180:183], v[196:199], v[32:35]
	v_mfma_f32_16x16x32_bf16 v[20:23], v[172:175], v[204:207], v[20:23]
	v_mfma_f32_16x16x32_bf16 v[16:19], v[180:183], v[204:207], v[16:19]
	v_mfma_f32_16x16x32_bf16 v[4:7], v[172:175], v[212:215], v[4:7]
	v_mfma_f32_16x16x32_bf16 v[0:3], v[180:183], v[212:215], v[0:3]
	s_setprio 0
	s_barrier
	s_add_i32 s55, 0, 0x18000
	v_add_u32_e32 v151, s55, v145
	s_add_i32 s56, 0, 0x1c000
	ds_read_b128 v[152:155], v151
	ds_read_b128 v[156:159], v151 offset:1024
	ds_read_b128 v[160:163], v151 offset:2048
	ds_read_b128 v[164:167], v151 offset:3072
	v_add_u32_e32 v151, s56, v145
	ds_read_b128 v[168:171], v151
	ds_read_b128 v[172:175], v151 offset:1024
	ds_read_b128 v[176:179], v151 offset:2048
	ds_read_b128 v[180:183], v151 offset:3072
	s_add_u32 s28, s28, 0x40000
	s_addc_u32 s29, s29, 0
	s_mov_b32 m0, s40
	v_lshl_add_u64 v[224:225], s[28:29], 0, v[134:135]
	ds_read_b128 v[184:187], v150 offset:32768
	ds_read_b128 v[188:191], v150 offset:33792
	ds_read_b128 v[192:195], v150 offset:34816
	ds_read_b128 v[196:199], v150 offset:35840
	ds_read_b128 v[200:203], v150 offset:36864
	ds_read_b128 v[204:207], v150 offset:37888
	ds_read_b128 v[208:211], v150 offset:38912
	ds_read_b128 v[212:215], v150 offset:39936
	global_load_lds_dwordx4 v[224:225], off
	v_lshl_add_u64 v[224:225], s[28:29], 0, v[130:131]
	s_mov_b32 m0, s41
	s_nop 0
	global_load_lds_dwordx4 v[224:225], off
	s_waitcnt vmcnt(8)
	s_waitcnt lgkmcnt(0)
	s_barrier
	s_setprio 1
	s_waitcnt lgkmcnt(0)
	v_mfma_f32_16x16x32_bf16 v[124:127], v[152:155], v[184:187], v[124:127]
	v_mfma_f32_16x16x32_bf16 v[120:123], v[160:163], v[184:187], v[120:123]
	v_mfma_f32_16x16x32_bf16 v[108:111], v[152:155], v[192:195], v[108:111]
	v_mfma_f32_16x16x32_bf16 v[104:107], v[160:163], v[192:195], v[104:107]
	v_mfma_f32_16x16x32_bf16 v[92:95], v[152:155], v[200:203], v[92:95]
	v_mfma_f32_16x16x32_bf16 v[88:91], v[160:163], v[200:203], v[88:91]
	v_mfma_f32_16x16x32_bf16 v[76:79], v[152:155], v[208:211], v[76:79]
	v_mfma_f32_16x16x32_bf16 v[72:75], v[160:163], v[208:211], v[72:75]
	v_mfma_f32_16x16x32_bf16 v[124:127], v[156:159], v[188:191], v[124:127]
	v_mfma_f32_16x16x32_bf16 v[120:123], v[164:167], v[188:191], v[120:123]
	v_mfma_f32_16x16x32_bf16 v[108:111], v[156:159], v[196:199], v[108:111]
	v_mfma_f32_16x16x32_bf16 v[104:107], v[164:167], v[196:199], v[104:107]
	v_mfma_f32_16x16x32_bf16 v[92:95], v[156:159], v[204:207], v[92:95]
	v_mfma_f32_16x16x32_bf16 v[88:91], v[164:167], v[204:207], v[88:91]
	v_mfma_f32_16x16x32_bf16 v[76:79], v[156:159], v[212:215], v[76:79]
	v_mfma_f32_16x16x32_bf16 v[72:75], v[164:167], v[212:215], v[72:75]
	s_setprio 0
	s_setprio 1
	v_mfma_f32_16x16x32_bf16 v[116:119], v[168:171], v[184:187], v[116:119]
	v_mfma_f32_16x16x32_bf16 v[112:115], v[176:179], v[184:187], v[112:115]
	v_mfma_f32_16x16x32_bf16 v[100:103], v[168:171], v[192:195], v[100:103]
	v_mfma_f32_16x16x32_bf16 v[96:99], v[176:179], v[192:195], v[96:99]
	v_mfma_f32_16x16x32_bf16 v[84:87], v[168:171], v[200:203], v[84:87]
	v_mfma_f32_16x16x32_bf16 v[80:83], v[176:179], v[200:203], v[80:83]
	v_mfma_f32_16x16x32_bf16 v[68:71], v[168:171], v[208:211], v[68:71]
	v_mfma_f32_16x16x32_bf16 v[64:67], v[176:179], v[208:211], v[64:67]
	v_mfma_f32_16x16x32_bf16 v[116:119], v[172:175], v[188:191], v[116:119]
	v_mfma_f32_16x16x32_bf16 v[112:115], v[180:183], v[188:191], v[112:115]
	v_mfma_f32_16x16x32_bf16 v[100:103], v[172:175], v[196:199], v[100:103]
	v_mfma_f32_16x16x32_bf16 v[96:99], v[180:183], v[196:199], v[96:99]
	v_mfma_f32_16x16x32_bf16 v[84:87], v[172:175], v[204:207], v[84:87]
	v_mfma_f32_16x16x32_bf16 v[80:83], v[180:183], v[204:207], v[80:83]
	v_mfma_f32_16x16x32_bf16 v[68:71], v[172:175], v[212:215], v[68:71]
	v_mfma_f32_16x16x32_bf16 v[64:67], v[180:183], v[212:215], v[64:67]
	s_setprio 0
	s_barrier
	s_add_i32 s28, s55, s33
	v_lshl_add_u64 v[216:217], v[216:217], 0, s[10:11]
	s_mov_b32 m0, s28
	ds_read_b128 v[184:187], v150 offset:49152
	ds_read_b128 v[188:191], v150 offset:50176
	ds_read_b128 v[192:195], v150 offset:51200
	ds_read_b128 v[196:199], v150 offset:52224
	ds_read_b128 v[200:203], v150 offset:53248
	ds_read_b128 v[204:207], v150 offset:54272
	ds_read_b128 v[208:211], v150 offset:55296
	ds_read_b128 v[212:215], v150 offset:56320
	global_load_lds_dwordx4 v[216:217], off
	s_add_i32 m0, s28, 0x2000
	s_add_u32 s26, s26, 0x40080
	v_lshl_add_u64 v[216:217], v[218:219], 0, s[10:11]
	s_addc_u32 s27, s27, 0
	s_add_i32 s28, s56, s33
	global_load_lds_dwordx4 v[216:217], off
	v_lshl_add_u64 v[216:217], s[26:27], 0, v[132:133]
	s_mov_b32 m0, s28
	s_nop 0
	global_load_lds_dwordx4 v[216:217], off
	v_lshl_add_u64 v[216:217], s[26:27], 0, v[128:129]
	s_add_i32 m0, s28, 0x2000
	s_nop 0
	global_load_lds_dwordx4 v[216:217], off
	v_lshl_add_u64 v[216:217], v[220:221], 0, s[10:11]
	s_mov_b32 m0, s42
	s_nop 0
	global_load_lds_dwordx4 v[216:217], off
	v_lshl_add_u64 v[216:217], v[222:223], 0, s[10:11]
	s_mov_b32 m0, s43
	s_nop 0
	global_load_lds_dwordx4 v[216:217], off
	s_waitcnt vmcnt(8)
	s_waitcnt lgkmcnt(0)
	s_barrier
	s_setprio 1
	s_waitcnt lgkmcnt(0)
	v_mfma_f32_16x16x32_bf16 v[60:63], v[152:155], v[184:187], v[60:63]
	v_mfma_f32_16x16x32_bf16 v[56:59], v[160:163], v[184:187], v[56:59]
	v_mfma_f32_16x16x32_bf16 v[44:47], v[152:155], v[192:195], v[44:47]
	v_mfma_f32_16x16x32_bf16 v[40:43], v[160:163], v[192:195], v[40:43]
	v_mfma_f32_16x16x32_bf16 v[28:31], v[152:155], v[200:203], v[28:31]
	v_mfma_f32_16x16x32_bf16 v[24:27], v[160:163], v[200:203], v[24:27]
	v_mfma_f32_16x16x32_bf16 v[12:15], v[152:155], v[208:211], v[12:15]
	v_mfma_f32_16x16x32_bf16 v[8:11], v[160:163], v[208:211], v[8:11]
	v_mfma_f32_16x16x32_bf16 v[60:63], v[156:159], v[188:191], v[60:63]
	v_mfma_f32_16x16x32_bf16 v[56:59], v[164:167], v[188:191], v[56:59]
	v_mfma_f32_16x16x32_bf16 v[44:47], v[156:159], v[196:199], v[44:47]
	v_mfma_f32_16x16x32_bf16 v[40:43], v[164:167], v[196:199], v[40:43]
	v_mfma_f32_16x16x32_bf16 v[28:31], v[156:159], v[204:207], v[28:31]
	v_mfma_f32_16x16x32_bf16 v[24:27], v[164:167], v[204:207], v[24:27]
	v_mfma_f32_16x16x32_bf16 v[12:15], v[156:159], v[212:215], v[12:15]
	v_mfma_f32_16x16x32_bf16 v[8:11], v[164:167], v[212:215], v[8:11]
	s_setprio 0
	s_setprio 1
	v_mfma_f32_16x16x32_bf16 v[52:55], v[168:171], v[184:187], v[52:55]
	v_mfma_f32_16x16x32_bf16 v[48:51], v[176:179], v[184:187], v[48:51]
	v_mfma_f32_16x16x32_bf16 v[36:39], v[168:171], v[192:195], v[36:39]
	v_mfma_f32_16x16x32_bf16 v[32:35], v[176:179], v[192:195], v[32:35]
	v_mfma_f32_16x16x32_bf16 v[20:23], v[168:171], v[200:203], v[20:23]
	v_mfma_f32_16x16x32_bf16 v[16:19], v[176:179], v[200:203], v[16:19]
	v_mfma_f32_16x16x32_bf16 v[4:7], v[168:171], v[208:211], v[4:7]
	v_mfma_f32_16x16x32_bf16 v[0:3], v[176:179], v[208:211], v[0:3]
	v_mfma_f32_16x16x32_bf16 v[52:55], v[172:175], v[188:191], v[52:55]
	v_mfma_f32_16x16x32_bf16 v[48:51], v[180:183], v[188:191], v[48:51]
	v_mfma_f32_16x16x32_bf16 v[36:39], v[172:175], v[196:199], v[36:39]
	v_mfma_f32_16x16x32_bf16 v[32:35], v[180:183], v[196:199], v[32:35]
	v_mfma_f32_16x16x32_bf16 v[20:23], v[172:175], v[204:207], v[20:23]
	v_mfma_f32_16x16x32_bf16 v[16:19], v[180:183], v[204:207], v[16:19]
	v_mfma_f32_16x16x32_bf16 v[4:7], v[172:175], v[212:215], v[4:7]
	v_mfma_f32_16x16x32_bf16 v[0:3], v[180:183], v[212:215], v[0:3]
	s_setprio 0
	s_barrier
	s_add_i32 s54, s54, 2
	s_add_u32 s24, s24, 0x100
	s_addc_u32 s25, s25, 0
	s_add_u32 s52, s52, 0x100
	s_addc_u32 s53, s53, 0
	s_cmp_gt_u32 s54, 13
